# v7 + attention sample K/V stream: rows 2,3 of each slice via LDS-DMA two steps ahead (double LDS slot per wave), rows 0,1 via registers one step ahead
# baseline (speedup 1.0000x reference)
; #define LAS __attribute__((address_space(3)))
; __device__ __forceinline__ void attn_fused(Frame& F0, int layer) {
;     ...
;     const int tid = F.tid, lane = F.lane, w = F.wave, fr = lane & 15, fq = lane >> 4;
;     const bf16_t* Kl = ((bf16_t*)(F.ws + WS_KB)) + (size_t)layer * MMEM * D; const bf16_t* Vl = ((bf16_t*)(F.ws + WS_VB)) + (size_t)layer * MMEM * D;
;     LAS float* sc = (LAS float*)(lds + FA_SC); LAS float* red = (LAS float*)(lds + FA_RED);
;     const int sb = 16 * F.xq + (F.rk >> 1), hp = F.rk & 1;
;     const float* qp = ((float*)(F.ws + WS_SQ)) + (size_t)sb * D + hp * 512;
;     const f32x4 q0 = *(const f32x4*)(qp + 4 * lane), q1 = *(const f32x4*)(qp + 256 + 4 * lane);
;     const float* kp = FIN(5) + ((size_t)(layer * 128 + sb) * 256 + 4 * w) * 1024 + hp * 512;
;     const float* vp = FIN(6) + ((size_t)(layer * 128 + sb) * 256 + 4 * w) * 1024 + hp * 512;
;     const unsigned lo16 = (unsigned)lane * 16u;
;     f32x4 sv[8]; f32x4 a0 = (f32x4){0.f, 0.f, 0.f, 0.f}, a1 = a0; float mx0 = 0.f, mx1 = 0.f, iv0 = 0.f, iv1 = 0.f;
;     ...
;     FA_SLOAD(kp, 0);
; #pragma unroll 1
;     for (int ui = 0; ui < 2; ++ui) {
;         const int kk = 2 * F.rk + ui;
;         const int b = F.xq, h = kk >> 4, qb = kk & 15;
;         const size_t rowq = (size_t)b * SEQ + qb * 128 + 16 * w + fr;
;         bf16x8 Qf[8];
; #pragma unroll
;         for (int ks = 0; ks < 8; ++ks) Qf[ks] = *(const bf16x8*)(((bf16_t*)(F.ws + WS_Q)) + rowq * D + h * 256 + 32 * ks + 8 * fq);
;         const bf16_t* kbase = Kl + (size_t)(b * 256) * D + h * 256; const bf16_t* vbase = Vl + (size_t)(b * 256) * D + h * 256;
;         u32x4 st[2][4];
;         const unsigned goff = (unsigned)(tid >> 5) * (D * 2) + (unsigned)(tid & 31) * 16u, loff = (unsigned)(tid >> 5) * 544u + (unsigned)(tid & 31) * 16u;
;     ...
;         f32x4 S[16], Oa[16]; bf16x8 Pf[8]; float inv = 0.f;
;         const f32x4 zero4 = (f32x4){0.f, 0.f, 0.f, 0.f};
.LBB0_2028:
	v_readlane_b32 s14, v254, 12
	s_and_b64 vcc, exec, s[2:3]
	v_readlane_b32 s15, v254, 13
	s_cbranch_vccz .LBB0_2130
	s_waitcnt vmcnt(0)
	s_lshl_b32 s100, s67, 13
	s_add_u32 s100, s100, 0x12000
	s_cmp_eq_u32 s67, 7
	s_cselect_b32 s101, 0x400, 0
	s_add_u32 s100, s100, s101
	s_mov_b32 m0, s100
	v_mbcnt_lo_u32_b32 v9, -1, 0
	v_mbcnt_hi_u32_b32 v9, -1, v9
	s_movk_i32 s2, 0x100
	s_and_b32 s17, s20, 7
	s_lshl_b32 s2, s17, 4
	s_ashr_i32 s3, s20, 4
	s_add_i32 s4, s2, s3
	v_readlane_b32 s22, v254, 32
	s_ashr_i32 s5, s4, 31
	s_lshl_b32 s16, s22, 7
	s_ashr_i32 s18, s20, 3
	s_lshl_b64 s[2:3], s[4:5], 10
	s_lshl_b64 s[12:13], s[4:5], 12
	s_add_u32 s5, s10, s12
	s_addc_u32 s13, s11, s13
	s_lshl_b32 s12, s18, 9
	s_and_b32 s68, s12, 0x200
	s_lshl_b32 s19, s68, 2
	s_add_u32 s12, s5, s19
	v_lshlrev_b32_e32 v168, 2, v9
	s_addc_u32 s13, s13, 0
	v_ashrrev_i32_e32 v169, 31, v168
	v_lshl_add_u64 v[0:1], v[168:169], 2, s[12:13]
	s_mov_b64 s[12:13], 0x1b600000
	s_mov_b32 s5, 0x1b600000
	v_lshl_add_u64 v[4:5], v[0:1], 0, s[12:13]
	v_add_co_u32_e32 v0, vcc, s5, v0
	s_add_i32 s4, s4, s16
	s_nop 0
	v_addc_co_u32_e32 v1, vcc, 0, v1, vcc
	global_load_dwordx4 v[0:3], v[0:1], off
	s_nop 0
	global_load_dwordx4 v[4:7], v[4:5], off offset:1024
	s_load_dwordx4 s[12:15], s[6:7], 0x28
	s_lshl_b32 s6, s67, 2
	s_ashr_i32 s5, s4, 31
	s_ashr_i32 s7, s6, 31
	s_lshl_b64 s[4:5], s[4:5], 18
	s_lshl_b64 s[6:7], s[6:7], 10
	s_add_u32 s4, s4, s6
	s_addc_u32 s5, s5, s7
	s_lshl_b64 s[4:5], s[4:5], 2
	s_waitcnt lgkmcnt(0)
	s_add_u32 s6, s12, s4
	s_addc_u32 s7, s13, s5
	s_add_u32 s6, s6, s19
	s_addc_u32 s7, s7, 0
	s_add_u32 s4, s14, s4
	s_addc_u32 s5, s15, s5
	s_add_u32 s12, s4, s19
	s_addc_u32 s13, s5, 0
	v_lshlrev_b32_e32 v200, 4, v9
	s_mov_b64 s[4:5], s[6:7]
	v_ashrrev_i32_e32 v8, 4, v9
	v_lshl_add_u64 v[10:11], s[4:5], 0, v[200:201]
	v_add_co_u32_e32 v12, vcc, s33, v10
	v_lshl_or_b32 v170, s67, 6, v9
	s_nop 0
	v_addc_co_u32_e32 v13, vcc, 0, v11, vcc
	v_add_co_u32_e32 v14, vcc, s70, v10
	s_movk_i32 s52, 0x220
	s_nop 0
	v_addc_co_u32_e32 v15, vcc, 0, v11, vcc
	v_add_co_u32_e32 v10, vcc, s95, v10
	global_load_dwordx4 v[64:67], v200, s[4:5] offset:1024 nt
	global_load_dwordx4 v[60:63], v[14:15], off offset:-4096 nt
	global_load_dwordx4 v[52:55], v[14:15], off nt
	global_load_dwordx4 v[48:51], v[14:15], off offset:1024 nt
	v_addc_co_u32_e32 v11, vcc, 0, v11, vcc
	global_load_dwordx4 v[56:59], v[12:13], off offset:1024 nt
	global_load_dwordx4 v[44:47], v[10:11], off nt
	global_load_dwordx4 v[68:71], v200, s[4:5] nt
	global_load_dwordx4 v[40:43], v[10:11], off offset:1024 nt
	s_lshl_b32 s4, s22, 22
	s_add_u32 s16, s10, s4
	s_addc_u32 s19, s11, 0
	s_lshl_b32 s4, s18, 8
	s_lshl_b32 s21, s67, 4
	s_and_b32 s60, s4, 0x700
	s_ashr_i32 s4, s21, 31
	v_mov_b32_e32 v173, s4
	s_lshl_b32 s4, s20, 2
	s_and_b32 s4, s4, 0xffffff00
	s_ashr_i32 s5, s4, 31
	s_lshl_b32 s61, s17, 11
	s_lshl_b64 s[4:5], s[4:5], 1
	s_add_u32 s14, s10, s4
	v_lshlrev_b32_e32 v10, 3, v8
	s_addc_u32 s15, s11, s5
	v_ashrrev_i32_e32 v11, 31, v10
	v_lshl_add_u64 v[10:11], v[10:11], 1, s[14:15]
	s_mov_b64 s[14:15], 0x14c00000
	v_lshl_add_u64 v[174:175], v[10:11], 0, s[14:15]
	s_lshl_b32 s14, s17, 19
	s_add_u32 s14, s16, s14
	s_addc_u32 s15, s19, 0
	s_add_u32 s50, s14, s4
	s_addc_u32 s51, s15, s5
	s_add_u32 s14, s50, 0x19000000
	s_addc_u32 s15, s51, 0
	s_add_u32 s16, s50, 0x1a000000
	s_addc_u32 s17, s51, 0
	v_readlane_b32 s4, v254, 26
	s_add_u32 s18, s50, 0x19020000
	s_addc_u32 s19, s51, 0
	s_add_i32 s69, s4, s21
	v_and_b32_e32 v12, 15, v9
	s_add_u32 s20, s50, 0x19040000
	v_or_b32_e32 v172, s21, v12
	s_addc_u32 s21, s51, 0
	s_add_u32 s22, s12, 0x20000
	s_addc_u32 s23, s13, 0
	s_add_u32 s24, s6, 0x20000
	s_addc_u32 s25, s7, 0
	s_add_u32 s26, s50, 0x19060000
	s_addc_u32 s27, s51, 0
	s_add_u32 s28, s12, 0x40000
	s_addc_u32 s29, s13, 0
	s_add_u32 s30, s6, 0x40000
	s_addc_u32 s31, s7, 0
	s_add_u32 s34, s12, 0x60000
	s_addc_u32 s35, s13, 0
	s_add_u32 s36, s6, 0x60000
	s_addc_u32 s37, s7, 0
	s_add_u32 s38, s50, 0x1a020000
	s_addc_u32 s39, s51, 0
	s_add_u32 s40, s12, 0x80000
	s_addc_u32 s41, s13, 0
	s_add_u32 s42, s6, 0x80000
	s_addc_u32 s43, s7, 0
	s_add_u32 s44, s50, 0x1a040000
	s_addc_u32 s45, s51, 0
	s_add_u32 s46, s12, 0xa0000
	v_add_u32_e32 v171, s4, v168
	v_cmp_eq_u32_e64 s[4:5], 63, v9
	v_bfe_u32 v13, v9, 2, 2
	v_lshlrev_b32_e32 v14, 3, v9
	v_and_b32_e32 v15, -16, v9
	v_ashrrev_i32_e32 v9, 31, v8
	s_addc_u32 s47, s13, 0
	v_lshl_or_b32 v13, v8, 2, v13
	v_lshlrev_b64 v[8:9], 3, v[8:9]
	s_add_u32 s48, s6, 0xa0000
	v_sub_co_u32_e32 v8, vcc, 0, v8
	s_addc_u32 s49, s7, 0
	s_nop 0
	v_subb_co_u32_e32 v9, vcc, 0, v9, vcc
	s_add_u32 s50, s50, 0x1a060000
	v_ashrrev_i32_e32 v10, 5, v170
	v_and_b32_e32 v11, 0x1f0, v200
	v_lshl_add_u64 v[178:179], v[174:175], 0, v[8:9]
	v_mul_u32_u24_e32 v8, 0x220, v12
	s_addc_u32 s51, s51, 0
	v_lshl_or_b32 v176, v10, 11, v11
	v_mul_lo_u32 v10, v10, s52
	v_add3_u32 v189, 0, v15, v8
	v_mul_lo_u32 v8, v13, s52
	s_add_u32 s52, s12, 0xc0000
	s_addc_u32 s53, s13, 0
	s_add_u32 s54, s6, 0xc0000
	s_addc_u32 s55, s7, 0
	s_add_u32 s56, s12, 0xe0000
	s_addc_u32 s57, s13, 0
	v_mov_b32_e32 v74, v201
	v_mov_b32_e32 v75, v201
	v_add_u32_e32 v10, 0, v10
	v_and_b32_e32 v14, 24, v14
	s_add_u32 s58, s6, 0xe0000
	v_mov_b32_e32 v72, v201
	v_mov_b32_e32 v73, v201
	v_mov_b64_e32 v[78:79], v[74:75]
	s_mov_b32 s62, 0
	v_xor_b32_e32 v183, 4, v168
	v_xor_b32_e32 v184, 8, v168
	v_xor_b32_e32 v185, 16, v168
	v_xor_b32_e32 v186, 32, v168
	v_xor_b32_e32 v187, 64, v168
	v_xor_b32_e32 v188, 0x80, v168
	v_mov_b32_e32 v177, v201
	v_add3_u32 v190, 0, v14, v8
	s_addc_u32 s59, s7, 0
	s_or_b32 s72, s60, s61
	v_mov_b32_e32 v182, v201
	v_mov_b32_e32 v169, v201
	s_mov_b64 s[60:61], -1
	s_mov_b64 s[6:7], 0
	v_mov_b32_e32 v192, 0
	v_add_u32_e32 v191, v10, v11
	v_mov_b64_e32 v[76:77], v[72:73]
	v_mov_b32_e32 v193, 0
	s_bitset1_b32 m0, 12
	v_add_u32_e32 v8, 0x2000, v200
	v_add_u32_e32 v9, 0x2800, v200
	global_load_lds_dwordx4 v8, s[24:25] nt
	global_load_lds_dwordx4 v8, s[24:25] offset:1024 nt
	global_load_lds_dwordx4 v9, s[24:25] offset:2048 nt
	global_load_lds_dwordx4 v9, s[24:25] offset:3072 nt
	s_branch .LBB0_2032
; __device__ __forceinline__ void attn_fused(Frame& F0, int layer) {
;     ...
;                 if (c < 7) FA_SLOAD(kp, c + 1); else FA_SLOAD(vp, 0);
;             } else {
; #pragma unroll
;                 for (int r = 0; r < 4; ++r) {
;                     const int m = 32 * c + 4 * w + r;
;                     const float p0 = __builtin_amdgcn_exp2f(sc[m] - mx0) * iv0, p1 = __builtin_amdgcn_exp2f(sc[256 + m] - mx1) * iv1;
;                     a0 += sv[2 * r] * p0; a1 += sv[2 * r + 1] * p1;
;                 }
;                 if (c < 7) FA_SLOAD(vp, c + 1);
.LBB0_2030:
	s_or_b64 exec, exec, s[60:61]
	s_mov_b64 s[60:61], s[12:13]
	v_mov_b64_e32 v[74:75], v[14:15]
	v_lshl_add_u64 v[24:25], s[60:61], 0, v[200:201]
	v_add_co_u32_e32 v26, vcc, 0x3000, v24
	v_mov_b64_e32 v[78:79], v[10:11]
	s_nop 0
	v_addc_co_u32_e32 v27, vcc, 0, v25, vcc
	global_load_dwordx4 v[40:43], v[26:27], off offset:1024
	global_load_dwordx4 v[44:47], v[26:27], off
	v_add_co_u32_e32 v26, vcc, s70, v24
	v_mov_b64_e32 v[72:73], v[12:13]
	s_nop 0
	v_addc_co_u32_e32 v27, vcc, 0, v25, vcc
	global_load_dwordx4 v[48:51], v[26:27], off offset:1024
	global_load_dwordx4 v[52:55], v[26:27], off
	v_add_co_u32_e32 v26, vcc, s33, v24
	v_mov_b64_e32 v[76:77], v[8:9]
	s_nop 0
	v_addc_co_u32_e32 v27, vcc, 0, v25, vcc
	global_load_dwordx4 v[56:59], v[26:27], off offset:1024
	global_load_dwordx4 v[60:63], v[26:27], off
	global_load_dwordx4 v[64:67], v[24:25], off offset:1024
	global_load_dwordx4 v[68:71], v[24:25], off
	s_bitset1_b32 m0, 12
	v_add_u32_e32 v26, 0x2000, v200
	v_add_u32_e32 v27, 0x2800, v200
	global_load_lds_dwordx4 v26, s[22:23] nt
	global_load_lds_dwordx4 v26, s[22:23] offset:1024 nt
	global_load_lds_dwordx4 v27, s[22:23] offset:2048 nt
	global_load_lds_dwordx4 v27, s[22:23] offset:3072 nt

; #define LAS __attribute__((address_space(3)))
; #define LDS_BARRIER() asm volatile("s_waitcnt lgkmcnt(0)\n\ts_barrier" ::: "memory")
; #define MFMA16(a, b, c) __builtin_amdgcn_mfma_f32_16x16x32_bf16((a), (b), (c), 0, 0, 0)
; __device__ __forceinline__ void attn_fused(Frame& F0, int layer) {
;     ...
;             if (c < 6) ATT_GLOAD(c + 2);
;             if (ui == 0) {
; #pragma unroll
;                 for (int r = 0; r < 4; ++r) {
;                     const int m = 32 * c + 4 * w + r;
;                     const float d0 = wave_sum_dpp(dot4(sv[2 * r], q0)), d1 = wave_sum_dpp(dot4(sv[2 * r + 1], q1));
;                     if (lane == 63) { sc[m] = d0; sc[256 + m] = d1; }
;                 }
;                 if (c < 7) FA_SLOAD(kp, c + 1); else FA_SLOAD(vp, 0);
;             } else {
; #pragma unroll
;                 for (int r = 0; r < 4; ++r) {
;                     const int m = 32 * c + 4 * w + r;
;                     const float p0 = __builtin_amdgcn_exp2f(sc[m] - mx0) * iv0, p1 = __builtin_amdgcn_exp2f(sc[256 + m] - mx1) * iv1;
;                     a0 += sv[2 * r] * p0; a1 += sv[2 * r + 1] * p1;
;                 }
;                 if (c < 7) FA_SLOAD(vp, c + 1);
;             }
;             LAS unsigned char* slot = lds + (c & 1) * ATT_SLOT;
;             if (c < 4) {
;                 {
;                     bf16x8 Kf[2][4];
;                     __builtin_amdgcn_s_setprio(1);
; #pragma unroll
;                     for (int ml = 0; ml < 4; ++ml) Kf[0][ml] = *(LAS bf16x8*)(slot + (16 * ml + fr) * 544 + (8 * fq) * 2);
;                     __builtin_amdgcn_sched_group_barrier(0x100, 4, 0);
; #pragma unroll
;                     for (int ks = 0; ks < 8; ++ks) {
;                         if (ks < 7) {
; #pragma unroll
;                             for (int ml = 0; ml < 4; ++ml) Kf[(ks + 1) & 1][ml] = *(LAS bf16x8*)(slot + (16 * ml + fr) * 544 + (32 * (ks + 1) + 8 * fq) * 2);
;                         }
; #pragma unroll
;                         for (int ml = 0; ml < 4; ++ml) S[4 * c + ml] = MFMA16(Kf[ks & 1][ml], Qf[ks], ks == 0 ? zero4 : S[4 * c + ml]);
;                         __builtin_amdgcn_sched_group_barrier(0x100, 4, 0); __builtin_amdgcn_sched_group_barrier(0x008, 4, 0);
;                     }
;                     __builtin_amdgcn_s_setprio(0);
;                 }
;     ...
;             if (c < 7) ATT_LSTORE(c + 1);
;             LDS_BARRIER();
.LBB0_2046:
	s_nop 0
	s_add_u32 s100, s62, 0x20000
	s_addc_u32 s101, s63, 0
	v_lshl_add_u64 v[40:41], s[62:63], 0, v[200:201]
	v_add_co_u32_e32 v42, vcc, 0x1000, v40
	global_load_dwordx4 v[140:143], v[40:41], off nt
	s_nop 0
	v_addc_co_u32_e32 v43, vcc, 0, v41, vcc
	global_load_dwordx4 v[132:135], v[42:43], off nt
	global_load_dwordx4 v[128:131], v[42:43], off offset:1024 nt
	v_add_co_u32_e32 v42, vcc, 0x2000, v40
	global_load_dwordx4 v[136:139], v[40:41], off offset:1024 nt
	s_nop 0
	v_addc_co_u32_e32 v43, vcc, 0, v41, vcc
	v_add_co_u32_e32 v40, vcc, 0x3000, v40
	s_nop 0
	v_addc_co_u32_e32 v41, vcc, 0, v41, vcc
	s_bitset0_b32 m0, 12
	v_add_u32_e32 v74, 0x2000, v200
	v_add_u32_e32 v75, 0x2800, v200
	global_load_lds_dwordx4 v74, s[100:101] nt
	global_load_lds_dwordx4 v74, s[100:101] offset:1024 nt
	global_load_lds_dwordx4 v75, s[100:101] offset:2048 nt
	global_load_lds_dwordx4 v75, s[100:101] offset:3072 nt
	s_setprio 1
	ds_read_b128 v[40:43], v189
	ds_read_b128 v[44:47], v189 offset:8704
	ds_read_b128 v[48:51], v189 offset:17408
	ds_read_b128 v[52:55], v189 offset:26112
	ds_read_b128 v[56:59], v189 offset:64
	ds_read_b128 v[60:63], v189 offset:8768
	ds_read_b128 v[64:67], v189 offset:17472
	ds_read_b128 v[68:71], v189 offset:26176
	s_waitcnt lgkmcnt(7)
	v_mfma_f32_16x16x32_bf16 v[40:43], v[40:43], v[36:39], 0
	s_waitcnt lgkmcnt(6)
	v_mfma_f32_16x16x32_bf16 v[44:47], v[44:47], v[36:39], 0
	s_waitcnt lgkmcnt(5)
	v_mfma_f32_16x16x32_bf16 v[48:51], v[48:51], v[36:39], 0
	s_waitcnt lgkmcnt(4)
	v_mfma_f32_16x16x32_bf16 v[52:55], v[52:55], v[36:39], 0
	ds_read_b128 v[144:147], v189 offset:128
	ds_read_b128 v[148:151], v189 offset:8832
	ds_read_b128 v[152:155], v189 offset:17536
	ds_read_b128 v[156:159], v189 offset:26240
	s_waitcnt lgkmcnt(7)
	v_mfma_f32_16x16x32_bf16 v[40:43], v[56:59], v[32:35], v[40:43]
	s_waitcnt lgkmcnt(6)
	v_mfma_f32_16x16x32_bf16 v[44:47], v[60:63], v[32:35], v[44:47]
	s_waitcnt lgkmcnt(5)
	v_mfma_f32_16x16x32_bf16 v[48:51], v[64:67], v[32:35], v[48:51]
	s_waitcnt lgkmcnt(4)
	v_mfma_f32_16x16x32_bf16 v[52:55], v[68:71], v[32:35], v[52:55]
	ds_read_b128 v[56:59], v189 offset:192
	ds_read_b128 v[60:63], v189 offset:8896
	ds_read_b128 v[64:67], v189 offset:17600
	ds_read_b128 v[68:71], v189 offset:26304
	s_waitcnt lgkmcnt(7)
	v_mfma_f32_16x16x32_bf16 v[40:43], v[144:147], v[28:31], v[40:43]
	s_waitcnt lgkmcnt(6)
	v_mfma_f32_16x16x32_bf16 v[44:47], v[148:151], v[28:31], v[44:47]
	s_waitcnt lgkmcnt(5)
	v_mfma_f32_16x16x32_bf16 v[48:51], v[152:155], v[28:31], v[48:51]
	s_waitcnt lgkmcnt(4)
	v_mfma_f32_16x16x32_bf16 v[52:55], v[156:159], v[28:31], v[52:55]
	ds_read_b128 v[144:147], v189 offset:256
	ds_read_b128 v[148:151], v189 offset:8960
	ds_read_b128 v[152:155], v189 offset:17664
	ds_read_b128 v[156:159], v189 offset:26368
	s_waitcnt lgkmcnt(7)
	v_mfma_f32_16x16x32_bf16 v[40:43], v[56:59], v[24:27], v[40:43]
	s_waitcnt lgkmcnt(6)
	v_mfma_f32_16x16x32_bf16 v[44:47], v[60:63], v[24:27], v[44:47]
	s_waitcnt lgkmcnt(5)
	v_mfma_f32_16x16x32_bf16 v[48:51], v[64:67], v[24:27], v[48:51]
	s_waitcnt lgkmcnt(4)
	v_mfma_f32_16x16x32_bf16 v[52:55], v[68:71], v[24:27], v[52:55]
	ds_read_b128 v[56:59], v189 offset:320
	ds_read_b128 v[60:63], v189 offset:9024
	ds_read_b128 v[64:67], v189 offset:17728
	ds_read_b128 v[68:71], v189 offset:26432
	s_waitcnt lgkmcnt(7)
	v_mfma_f32_16x16x32_bf16 v[40:43], v[144:147], v[20:23], v[40:43]
	s_waitcnt lgkmcnt(6)
	v_mfma_f32_16x16x32_bf16 v[44:47], v[148:151], v[20:23], v[44:47]
	s_waitcnt lgkmcnt(5)
	v_mfma_f32_16x16x32_bf16 v[48:51], v[152:155], v[20:23], v[48:51]
	s_waitcnt lgkmcnt(4)
	v_mfma_f32_16x16x32_bf16 v[52:55], v[156:159], v[20:23], v[52:55]
	ds_read_b128 v[144:147], v189 offset:384
	ds_read_b128 v[148:151], v189 offset:9088
	ds_read_b128 v[152:155], v189 offset:17792
	ds_read_b128 v[156:159], v189 offset:26496
	s_waitcnt lgkmcnt(7)
	v_mfma_f32_16x16x32_bf16 v[40:43], v[56:59], v[16:19], v[40:43]
	s_waitcnt lgkmcnt(6)
	v_mfma_f32_16x16x32_bf16 v[44:47], v[60:63], v[16:19], v[44:47]
	s_waitcnt lgkmcnt(5)
	v_mfma_f32_16x16x32_bf16 v[48:51], v[64:67], v[16:19], v[48:51]
	s_waitcnt lgkmcnt(4)
	v_mfma_f32_16x16x32_bf16 v[52:55], v[68:71], v[16:19], v[52:55]
	ds_read_b128 v[56:59], v189 offset:448
	ds_read_b128 v[60:63], v189 offset:9152
	ds_read_b128 v[64:67], v189 offset:17856
	ds_read_b128 v[68:71], v189 offset:26560
	s_waitcnt lgkmcnt(7)
	v_mfma_f32_16x16x32_bf16 v[40:43], v[144:147], v[12:15], v[40:43]
	s_waitcnt lgkmcnt(6)
	v_mfma_f32_16x16x32_bf16 v[44:47], v[148:151], v[12:15], v[44:47]
	s_waitcnt lgkmcnt(5)
	v_mfma_f32_16x16x32_bf16 v[144:147], v[152:155], v[12:15], v[48:51]
	s_waitcnt lgkmcnt(4)
	v_mfma_f32_16x16x32_bf16 v[148:151], v[156:159], v[12:15], v[52:55]
	s_waitcnt lgkmcnt(3)
	v_mfma_f32_16x16x32_bf16 v[52:55], v[56:59], v[8:11], v[40:43]
	s_waitcnt lgkmcnt(2)
	v_mfma_f32_16x16x32_bf16 v[48:51], v[60:63], v[8:11], v[44:47]
	s_waitcnt lgkmcnt(1)
	v_mfma_f32_16x16x32_bf16 v[40:43], v[64:67], v[8:11], v[144:147]
	s_waitcnt lgkmcnt(0)
	v_mfma_f32_16x16x32_bf16 v[44:47], v[68:71], v[8:11], v[148:151]
	s_setprio 0
	s_waitcnt vmcnt(15)
	ds_write_b128 v191, v[92:95] offset:34816
	s_waitcnt vmcnt(14)
	ds_write_b128 v191, v[96:99] offset:43520
	s_waitcnt vmcnt(13)
	ds_write_b128 v191, v[112:115] offset:52224
	s_waitcnt vmcnt(12)
	ds_write_b128 v191, v[116:119] offset:60928
	s_mov_b64 s[62:63], s[26:27]
	s_waitcnt lgkmcnt(0)
	s_barrier
; __device__ __forceinline__ float dot4(f32x4 a, f32x4 b) { return (a[0] * b[0] + a[1] * b[1]) + (a[2] * b[2] + a[3] * b[3]); }
; #define ATT_GLOAD(c) do { const bf16_t* src_ = ((c) < 4 ? kbase : vbase) + (size_t)(64 * ((c) & 3)) * D; _Pragma("unroll") for (int i_ = 0; i_ < 4; ++i_) { const int idx_ = tid + 512 * i_; st[i_] = *(const u32x4*)(src_ + (size_t)(idx_ >> 5) * D + (idx_ & 31) * 8); } } while (0)
; #define ATT_GLOAD(c) do { unsigned long long pu_ = uni64((unsigned long long)(((c) < 4 ? kbase : vbase) + (size_t)(64 * ((c) & 3)) * D)); asm volatile("" : "+s"(pu_)); const char* pc_ = (const char*)(const GAS char*)pu_; \
;         _Pragma("unroll") for (int i_ = 0; i_ < 4; ++i_) st[(c) & 1][i_] = *(const u32x4*)(pc_ + (size_t)(16 * i_) * D * 2 + goff); } while (0)
; __device__ __forceinline__ void attn_fused(Frame& F0, int layer) {
;     ...
;             if (c < 6) ATT_GLOAD(c + 2);
;             if (ui == 0) {
; #pragma unroll
;                 for (int r = 0; r < 4; ++r) {
;                     const int m = 32 * c + 4 * w + r;
;                     const float d0 = wave_sum_dpp(dot4(sv[2 * r], q0)), d1 = wave_sum_dpp(dot4(sv[2 * r + 1], q1));
;                     if (lane == 63) { sc[m] = d0; sc[256 + m] = d1; }
;                 }
;                 if (c < 7) FA_SLOAD(kp, c + 1); else FA_SLOAD(vp, 0);
;             } else {
; #pragma unroll
;                 for (int r = 0; r < 4; ++r) {
;                     const int m = 32 * c + 4 * w + r;
;                     const float p0 = __builtin_amdgcn_exp2f(sc[m] - mx0) * iv0, p1 = __builtin_amdgcn_exp2f(sc[256 + m] - mx1) * iv1;
;                     a0 += sv[2 * r] * p0; a1 += sv[2 * r + 1] * p1;
;                 }
;                 if (c < 7) FA_SLOAD(vp, c + 1);
	s_mov_b64 s[64:65], -1
	v_lshl_add_u64 v[64:65], s[62:63], 0, v[176:177]
	v_add_co_u32_e32 v60, vcc, 0x8000, v64
	global_load_dwordx4 v[56:59], v[64:65], off
	s_nop 0
	v_addc_co_u32_e32 v61, vcc, 0, v65, vcc
	v_add_co_u32_e32 v66, vcc, 0x10000, v64
	global_load_dwordx4 v[60:63], v[60:61], off
	s_nop 0
	v_addc_co_u32_e32 v67, vcc, 0, v65, vcc
	v_add_co_u32_e32 v68, vcc, 0x18000, v64
	s_nop 1
	v_addc_co_u32_e32 v69, vcc, 0, v65, vcc
	global_load_dwordx4 v[64:67], v[66:67], off
	s_and_b64 vcc, exec, s[6:7]
	global_load_dwordx4 v[68:71], v[68:69], off
	s_cbranch_vccnz .LBB0_2048
	s_waitcnt vmcnt(8)
	v_add_u32_e32 v72, m0, v200
	v_and_b32_e32 v72, 0xffffefff, v72
	ds_read_b128 v[124:127], v72 offset:4096
	ds_read_b128 v[120:123], v72 offset:5120
	ds_read_b128 v[76:79], v72 offset:6144
	ds_read_b128 v[72:75], v72 offset:7168
	s_waitcnt lgkmcnt(0)
	v_mov_b32_e32 v96, s69
	ds_read_b128 v[92:95], v96 offset:1152
	ds_read_b128 v[96:99], v96 offset:128
	s_mov_b64 s[62:63], s[28:29]
	s_mov_b64 s[64:65], 0
	s_waitcnt lgkmcnt(1)
	v_sub_f32_e32 v92, v92, v193
	v_sub_f32_e32 v93, v93, v193
	v_exp_f32_e32 v92, v92
	v_exp_f32_e32 v93, v93
	v_sub_f32_e32 v94, v94, v193
	v_exp_f32_e32 v114, v94
	v_mul_f32_e32 v92, v182, v92
	v_mul_f32_e32 v94, v182, v93
	s_waitcnt vmcnt(8)
	v_pk_fma_f32 v[112:113], v[138:139], v[92:93], v[90:91] op_sel_hi:[1,0,1]
	v_pk_fma_f32 v[92:93], v[136:137], v[92:93], v[88:89] op_sel_hi:[1,0,1]
	v_pk_fma_f32 v[112:113], v[130:131], v[94:95], v[112:113] op_sel_hi:[1,0,1]
	v_pk_fma_f32 v[92:93], v[128:129], v[94:95], v[92:93] op_sel_hi:[1,0,1]
	v_sub_f32_e32 v94, v95, v193
	v_exp_f32_e32 v95, v94
	v_mul_f32_e32 v94, v182, v114
	s_waitcnt vmcnt(8)
	v_pk_fma_f32 v[112:113], v[122:123], v[94:95], v[112:113] op_sel_hi:[1,0,1]
	v_pk_fma_f32 v[92:93], v[120:121], v[94:95], v[92:93] op_sel_hi:[1,0,1]
	v_mul_f32_e32 v94, v182, v95
	s_waitcnt vmcnt(8)
	v_pk_fma_f32 v[114:115], v[74:75], v[94:95], v[112:113] op_sel_hi:[1,0,1]
	s_waitcnt lgkmcnt(0)
	v_sub_f32_e32 v95, v96, v192
	v_exp_f32_e32 v95, v95
	s_nop 0
	v_pk_fma_f32 v[112:113], v[72:73], v[94:95], v[92:93] op_sel_hi:[1,0,1]
	v_sub_f32_e32 v92, v97, v192
	v_exp_f32_e32 v96, v92
	v_mul_f32_e32 v92, v169, v95
	v_pk_fma_f32 v[94:95], v[142:143], v[92:93], v[102:103] op_sel_hi:[1,0,1]
	v_pk_fma_f32 v[92:93], v[140:141], v[92:93], v[100:101] op_sel_hi:[1,0,1]
	v_mul_f32_e32 v96, v169, v96
	v_pk_fma_f32 v[94:95], v[134:135], v[96:97], v[94:95] op_sel_hi:[1,0,1]
	v_sub_f32_e32 v97, v98, v192
	v_exp_f32_e32 v97, v97
	s_nop 0
	v_pk_fma_f32 v[92:93], v[132:133], v[96:97], v[92:93] op_sel_hi:[1,0,1]
	v_sub_f32_e32 v96, v99, v192
	v_exp_f32_e32 v98, v96
	v_mul_f32_e32 v96, v169, v97
	v_pk_fma_f32 v[94:95], v[126:127], v[96:97], v[94:95] op_sel_hi:[1,0,1]
	v_pk_fma_f32 v[92:93], v[124:125], v[96:97], v[92:93] op_sel_hi:[1,0,1]
	v_mul_f32_e32 v96, v169, v98
	v_pk_fma_f32 v[118:119], v[78:79], v[96:97], v[94:95] op_sel_hi:[1,0,1]
	v_pk_fma_f32 v[116:117], v[76:77], v[96:97], v[92:93] op_sel_hi:[1,0,1]
.LBB0_2048:
	s_andn2_b64 vcc, exec, s[64:65]
	s_cbranch_vccnz .LBB0_2058
	s_waitcnt vmcnt(8)
	v_add_u32_e32 v72, m0, v200
	v_and_b32_e32 v72, 0xffffefff, v72
	ds_read_b128 v[124:127], v72 offset:4096
	ds_read_b128 v[120:123], v72 offset:5120
	ds_read_b128 v[76:79], v72 offset:6144
	ds_read_b128 v[72:75], v72 offset:7168
	s_waitcnt lgkmcnt(0)
	s_waitcnt vmcnt(11)
	v_mul_f32_e32 v92, v1, v141
	v_mul_f32_e32 v93, v3, v143
	s_waitcnt vmcnt(8)
	v_mul_f32_e32 v94, v5, v137
	v_mul_f32_e32 v95, v7, v139
	v_fmac_f32_e32 v92, v0, v140
	v_fmac_f32_e32 v93, v2, v142
	v_fmac_f32_e32 v94, v4, v136
	v_fmac_f32_e32 v95, v6, v138
	v_add_f32_e32 v92, v92, v93
	v_add_f32_e32 v94, v94, v95
	v_mov_b32_e32 v93, v201
	v_add_f32_dpp v92, v92, v92 quad_perm:[1,0,3,2] row_mask:0xf bank_mask:0xf bound_ctrl:1
	v_add_f32_dpp v94, v94, v94 quad_perm:[1,0,3,2] row_mask:0xf bank_mask:0xf bound_ctrl:1
	v_mov_b32_e32 v95, v201
	v_add_f32_dpp v92, v92, v92 quad_perm:[2,3,0,1] row_mask:0xf bank_mask:0xf bound_ctrl:1
	v_add_f32_dpp v94, v94, v94 quad_perm:[2,3,0,1] row_mask:0xf bank_mask:0xf bound_ctrl:1
	s_nop 0
	v_add_f32_dpp v92, v92, v92 row_half_mirror row_mask:0xf bank_mask:0xf bound_ctrl:1
	v_add_f32_dpp v94, v94, v94 row_half_mirror row_mask:0xf bank_mask:0xf bound_ctrl:1
	s_nop 0
	v_add_f32_dpp v92, v92, v92 row_mirror row_mask:0xf bank_mask:0xf bound_ctrl:1
	v_add_f32_dpp v94, v94, v94 row_mirror row_mask:0xf bank_mask:0xf bound_ctrl:1
	s_nop 0
	v_mov_b32_dpp v93, v92 row_bcast:15 row_mask:0xa bank_mask:0xf
	v_mov_b32_dpp v95, v94 row_bcast:15 row_mask:0xa bank_mask:0xf
	v_add_f32_e32 v92, v92, v93
	v_mov_b32_e32 v93, v201
	v_add_f32_e32 v94, v94, v95
	v_mov_b32_e32 v95, v201
	v_mov_b32_dpp v93, v92 row_bcast:31 row_mask:0xc bank_mask:0xf
	s_nop 0
	v_mov_b32_dpp v95, v94 row_bcast:31 row_mask:0xc bank_mask:0xf
	s_and_saveexec_b64 s[62:63], s[4:5]
	v_add_f32_e32 v92, v92, v93
	v_add_f32_e32 v93, v94, v95
	v_mov_b32_e32 v94, s69
	v_add_u32_e32 v94, 0x80, v94
	ds_write2st64_b32 v94, v92, v93 offset1:4
	s_or_b64 exec, exec, s[62:63]
	v_mul_f32_e32 v92, v1, v133
	v_mul_f32_e32 v93, v3, v135
	v_mul_f32_e32 v94, v5, v129
	v_mul_f32_e32 v95, v7, v131
	v_fmac_f32_e32 v92, v0, v132
	v_fmac_f32_e32 v93, v2, v134
	v_fmac_f32_e32 v94, v4, v128
	v_fmac_f32_e32 v95, v6, v130
	v_add_f32_e32 v92, v92, v93
	v_add_f32_e32 v94, v94, v95
	v_mov_b32_e32 v93, v201
	v_add_f32_dpp v92, v92, v92 quad_perm:[1,0,3,2] row_mask:0xf bank_mask:0xf bound_ctrl:1
	v_add_f32_dpp v94, v94, v94 quad_perm:[1,0,3,2] row_mask:0xf bank_mask:0xf bound_ctrl:1
	v_mov_b32_e32 v95, v201
	v_add_f32_dpp v92, v92, v92 quad_perm:[2,3,0,1] row_mask:0xf bank_mask:0xf bound_ctrl:1
	v_add_f32_dpp v94, v94, v94 quad_perm:[2,3,0,1] row_mask:0xf bank_mask:0xf bound_ctrl:1
	s_nop 0
	v_add_f32_dpp v92, v92, v92 row_half_mirror row_mask:0xf bank_mask:0xf bound_ctrl:1
	v_add_f32_dpp v94, v94, v94 row_half_mirror row_mask:0xf bank_mask:0xf bound_ctrl:1
	s_nop 0
	v_add_f32_dpp v92, v92, v92 row_mirror row_mask:0xf bank_mask:0xf bound_ctrl:1
	v_add_f32_dpp v94, v94, v94 row_mirror row_mask:0xf bank_mask:0xf bound_ctrl:1
	s_nop 0
	v_mov_b32_dpp v93, v92 row_bcast:15 row_mask:0xa bank_mask:0xf
	v_mov_b32_dpp v95, v94 row_bcast:15 row_mask:0xa bank_mask:0xf
	v_add_f32_e32 v92, v92, v93
	v_mov_b32_e32 v93, v201
	v_add_f32_e32 v94, v94, v95
	v_mov_b32_e32 v95, v201
	v_mov_b32_dpp v93, v92 row_bcast:31 row_mask:0xc bank_mask:0xf
	s_nop 0
	v_mov_b32_dpp v95, v94 row_bcast:31 row_mask:0xc bank_mask:0xf
	s_and_saveexec_b64 s[62:63], s[4:5]
	v_add_f32_e32 v92, v92, v93
	v_add_f32_e32 v93, v94, v95
	v_mov_b32_e32 v94, s69
	v_add_u32_e32 v94, 0x84, v94
	ds_write2st64_b32 v94, v92, v93 offset1:4
	s_or_b64 exec, exec, s[62:63]
	s_waitcnt vmcnt(8)
; #define LAS __attribute__((address_space(3)))
; __device__ __forceinline__ float dot4(f32x4 a, f32x4 b) { return (a[0] * b[0] + a[1] * b[1]) + (a[2] * b[2] + a[3] * b[3]); }
; #define MFMA16(a, b, c) __builtin_amdgcn_mfma_f32_16x16x32_bf16((a), (b), (c), 0, 0, 0)
; __device__ __forceinline__ void attn_fused(Frame& F0, int layer) {
;     ...
;             if (ui == 0) {
; #pragma unroll
;                 for (int r = 0; r < 4; ++r) {
;                     const int m = 32 * c + 4 * w + r;
;                     const float d0 = wave_sum_dpp(dot4(sv[2 * r], q0)), d1 = wave_sum_dpp(dot4(sv[2 * r + 1], q1));
;                     if (lane == 63) { sc[m] = d0; sc[256 + m] = d1; }
;                 }
;                 if (c < 7) FA_SLOAD(kp, c + 1); else FA_SLOAD(vp, 0);
;             } else {
; #pragma unroll
;                 for (int r = 0; r < 4; ++r) {
;                     const int m = 32 * c + 4 * w + r;
;                     const float p0 = __builtin_amdgcn_exp2f(sc[m] - mx0) * iv0, p1 = __builtin_amdgcn_exp2f(sc[256 + m] - mx1) * iv1;
;                     a0 += sv[2 * r] * p0; a1 += sv[2 * r + 1] * p1;
;                 }
;                 if (c < 7) FA_SLOAD(vp, c + 1);
;             }
;             LAS unsigned char* slot = lds + (c & 1) * ATT_SLOT;
;             if (c < 4) {
;                 {
;                     bf16x8 Kf[2][4];
;                     __builtin_amdgcn_s_setprio(1);
; #pragma unroll
;                     for (int ml = 0; ml < 4; ++ml) Kf[0][ml] = *(LAS bf16x8*)(slot + (16 * ml + fr) * 544 + (8 * fq) * 2);
;                     __builtin_amdgcn_sched_group_barrier(0x100, 4, 0);
; #pragma unroll
;                     for (int ks = 0; ks < 8; ++ks) {
;                         if (ks < 7) {
; #pragma unroll
;                             for (int ml = 0; ml < 4; ++ml) Kf[(ks + 1) & 1][ml] = *(LAS bf16x8*)(slot + (16 * ml + fr) * 544 + (32 * (ks + 1) + 8 * fq) * 2);
;                         }
; #pragma unroll
;                         for (int ml = 0; ml < 4; ++ml) S[4 * c + ml] = MFMA16(Kf[ks & 1][ml], Qf[ks], ks == 0 ? zero4 : S[4 * c + ml]);
;                         __builtin_amdgcn_sched_group_barrier(0x100, 4, 0); __builtin_amdgcn_sched_group_barrier(0x008, 4, 0);
	v_mul_f32_e32 v92, v1, v125
	v_mul_f32_e32 v93, v3, v127
	s_waitcnt vmcnt(8)
	v_mul_f32_e32 v94, v5, v121
	v_mul_f32_e32 v95, v7, v123
	v_fmac_f32_e32 v92, v0, v124
	v_fmac_f32_e32 v93, v2, v126
	v_fmac_f32_e32 v94, v4, v120
	v_fmac_f32_e32 v95, v6, v122
	v_add_f32_e32 v92, v92, v93
	v_add_f32_e32 v94, v94, v95
	v_mov_b32_e32 v93, v201
	v_add_f32_dpp v92, v92, v92 quad_perm:[1,0,3,2] row_mask:0xf bank_mask:0xf bound_ctrl:1
	v_add_f32_dpp v94, v94, v94 quad_perm:[1,0,3,2] row_mask:0xf bank_mask:0xf bound_ctrl:1
	v_mov_b32_e32 v95, v201
	v_add_f32_dpp v92, v92, v92 quad_perm:[2,3,0,1] row_mask:0xf bank_mask:0xf bound_ctrl:1
	v_add_f32_dpp v94, v94, v94 quad_perm:[2,3,0,1] row_mask:0xf bank_mask:0xf bound_ctrl:1
	s_nop 0
	v_add_f32_dpp v92, v92, v92 row_half_mirror row_mask:0xf bank_mask:0xf bound_ctrl:1
	v_add_f32_dpp v94, v94, v94 row_half_mirror row_mask:0xf bank_mask:0xf bound_ctrl:1
	s_nop 0
	v_add_f32_dpp v92, v92, v92 row_mirror row_mask:0xf bank_mask:0xf bound_ctrl:1
	v_add_f32_dpp v94, v94, v94 row_mirror row_mask:0xf bank_mask:0xf bound_ctrl:1
	s_nop 0
	v_mov_b32_dpp v93, v92 row_bcast:15 row_mask:0xa bank_mask:0xf
	v_mov_b32_dpp v95, v94 row_bcast:15 row_mask:0xa bank_mask:0xf
	v_add_f32_e32 v92, v92, v93
	v_mov_b32_e32 v93, v201
	v_add_f32_e32 v94, v94, v95
	v_mov_b32_e32 v95, v201
	v_mov_b32_dpp v93, v92 row_bcast:31 row_mask:0xc bank_mask:0xf
	s_nop 0
	v_mov_b32_dpp v95, v94 row_bcast:31 row_mask:0xc bank_mask:0xf
	s_and_saveexec_b64 s[62:63], s[4:5]
	v_add_f32_e32 v92, v92, v93
	v_add_f32_e32 v93, v94, v95
	v_mov_b32_e32 v94, s69
	v_add_u32_e32 v94, 0x88, v94
	ds_write2st64_b32 v94, v92, v93 offset1:4
	s_or_b64 exec, exec, s[62:63]
	s_waitcnt vmcnt(8)
	v_mul_f32_e32 v77, v1, v77
	s_waitcnt vmcnt(8)
	v_mul_f32_e32 v73, v5, v73
	v_fmac_f32_e32 v77, v0, v76
	v_mul_f32_e32 v76, v3, v79
	v_fmac_f32_e32 v73, v4, v72
	v_mul_f32_e32 v72, v7, v75
	v_fmac_f32_e32 v76, v2, v78
	v_fmac_f32_e32 v72, v6, v74
	v_add_f32_e32 v76, v77, v76
	v_add_f32_e32 v72, v73, v72
	v_mov_b32_e32 v77, v201
	v_add_f32_dpp v76, v76, v76 quad_perm:[1,0,3,2] row_mask:0xf bank_mask:0xf bound_ctrl:1
	v_add_f32_dpp v72, v72, v72 quad_perm:[1,0,3,2] row_mask:0xf bank_mask:0xf bound_ctrl:1
	v_mov_b32_e32 v73, v201
	v_add_f32_dpp v76, v76, v76 quad_perm:[2,3,0,1] row_mask:0xf bank_mask:0xf bound_ctrl:1
	v_add_f32_dpp v72, v72, v72 quad_perm:[2,3,0,1] row_mask:0xf bank_mask:0xf bound_ctrl:1
	s_nop 0
	v_add_f32_dpp v76, v76, v76 row_half_mirror row_mask:0xf bank_mask:0xf bound_ctrl:1
	v_add_f32_dpp v72, v72, v72 row_half_mirror row_mask:0xf bank_mask:0xf bound_ctrl:1
	s_nop 0
	v_add_f32_dpp v76, v76, v76 row_mirror row_mask:0xf bank_mask:0xf bound_ctrl:1
	v_add_f32_dpp v72, v72, v72 row_mirror row_mask:0xf bank_mask:0xf bound_ctrl:1
	s_nop 0
	v_mov_b32_dpp v77, v76 row_bcast:15 row_mask:0xa bank_mask:0xf
	v_mov_b32_dpp v73, v72 row_bcast:15 row_mask:0xa bank_mask:0xf
	v_add_f32_e32 v76, v76, v77
	v_mov_b32_e32 v77, v201
	v_add_f32_e32 v72, v72, v73
	v_mov_b32_e32 v73, v201
	v_mov_b32_dpp v77, v76 row_bcast:31 row_mask:0xc bank_mask:0xf
	s_nop 0
	v_mov_b32_dpp v73, v72 row_bcast:31 row_mask:0xc bank_mask:0xf
	s_and_saveexec_b64 s[62:63], s[4:5]
	v_add_f32_e32 v72, v72, v73
	v_mov_b32_e32 v73, s69
	v_add_f32_e32 v74, v76, v77
	v_add_u32_e32 v73, 0x8c, v73
	ds_write2st64_b32 v73, v74, v72 offset1:4
	s_or_b64 exec, exec, s[62:63]
	v_mov_b64_e32 v[118:119], v[102:103]
	v_mov_b64_e32 v[114:115], v[90:91]
	s_mov_b64 s[62:63], s[30:31]
	v_mov_b64_e32 v[116:117], v[100:101]
	v_mov_b64_e32 v[112:113], v[88:89]
.LBB0_2058:
	s_waitcnt vmcnt(8)
	s_add_u32 s100, s62, 0x20000
	s_addc_u32 s101, s63, 0
	v_lshl_add_u64 v[72:73], s[62:63], 0, v[200:201]
	v_add_co_u32_e32 v74, vcc, 0x1000, v72
	global_load_dwordx4 v[156:159], v[72:73], off nt
	s_nop 0
	v_addc_co_u32_e32 v75, vcc, 0, v73, vcc
	global_load_dwordx4 v[148:151], v[74:75], off nt
	global_load_dwordx4 v[144:147], v[74:75], off offset:1024 nt
	v_add_co_u32_e32 v74, vcc, 0x2000, v72
	global_load_dwordx4 v[152:155], v[72:73], off offset:1024 nt
	s_nop 0
	v_addc_co_u32_e32 v75, vcc, 0, v73, vcc
	v_add_co_u32_e32 v72, vcc, 0x3000, v72
	s_nop 0
	v_addc_co_u32_e32 v73, vcc, 0, v73, vcc
	s_bitset1_b32 m0, 12
	v_add_u32_e32 v130, 0x2000, v200
	v_add_u32_e32 v131, 0x2800, v200
	global_load_lds_dwordx4 v130, s[100:101] nt
	global_load_lds_dwordx4 v130, s[100:101] offset:1024 nt
	global_load_lds_dwordx4 v131, s[100:101] offset:2048 nt
	global_load_lds_dwordx4 v131, s[100:101] offset:3072 nt
	s_setprio 1
	ds_read_b128 v[72:75], v189 offset:34816
	ds_read_b128 v[76:79], v189 offset:43520
	ds_read_b128 v[88:91], v189 offset:52224
	ds_read_b128 v[92:95], v189 offset:60928
	ds_read_b128 v[96:99], v189 offset:34880
	ds_read_b128 v[100:103], v189 offset:43584
	ds_read_b128 v[120:123], v189 offset:52288
	ds_read_b128 v[124:127], v189 offset:60992
	s_waitcnt lgkmcnt(7)
	v_mfma_f32_16x16x32_bf16 v[72:75], v[72:75], v[36:39], 0
	s_waitcnt lgkmcnt(6)
	v_mfma_f32_16x16x32_bf16 v[76:79], v[76:79], v[36:39], 0
	s_waitcnt lgkmcnt(5)
	v_mfma_f32_16x16x32_bf16 v[88:91], v[88:91], v[36:39], 0
	s_waitcnt lgkmcnt(4)
	v_mfma_f32_16x16x32_bf16 v[92:95], v[92:95], v[36:39], 0
	ds_read_b128 v[160:163], v189 offset:34944
	ds_read_b128 v[164:167], v189 offset:43648
	ds_read_b128 v[194:197], v189 offset:52352
	ds_read_b128 v[202:205], v189 offset:61056
	s_waitcnt lgkmcnt(7)
	v_mfma_f32_16x16x32_bf16 v[72:75], v[96:99], v[32:35], v[72:75]
	s_waitcnt lgkmcnt(6)
	v_mfma_f32_16x16x32_bf16 v[76:79], v[100:103], v[32:35], v[76:79]
	s_waitcnt lgkmcnt(5)
	v_mfma_f32_16x16x32_bf16 v[88:91], v[120:123], v[32:35], v[88:91]
	s_waitcnt lgkmcnt(4)
; #define LAS __attribute__((address_space(3)))
; __device__ __forceinline__ float dot4(f32x4 a, f32x4 b) { return (a[0] * b[0] + a[1] * b[1]) + (a[2] * b[2] + a[3] * b[3]); }
; #define MFMA16(a, b, c) __builtin_amdgcn_mfma_f32_16x16x32_bf16((a), (b), (c), 0, 0, 0)
; __device__ __forceinline__ void attn_fused(Frame& F0, int layer) {
;     ...
;             if (c < 6) ATT_GLOAD(c + 2);
;             if (ui == 0) {
; #pragma unroll
;                 for (int r = 0; r < 4; ++r) {
;                     const int m = 32 * c + 4 * w + r;
;                     const float d0 = wave_sum_dpp(dot4(sv[2 * r], q0)), d1 = wave_sum_dpp(dot4(sv[2 * r + 1], q1));
;                     if (lane == 63) { sc[m] = d0; sc[256 + m] = d1; }
;                 }
;                 if (c < 7) FA_SLOAD(kp, c + 1); else FA_SLOAD(vp, 0);
;             } else {
; #pragma unroll
;                 for (int r = 0; r < 4; ++r) {
;                     const int m = 32 * c + 4 * w + r;
;                     const float p0 = __builtin_amdgcn_exp2f(sc[m] - mx0) * iv0, p1 = __builtin_amdgcn_exp2f(sc[256 + m] - mx1) * iv1;
;                     a0 += sv[2 * r] * p0; a1 += sv[2 * r + 1] * p1;
;                 }
;                 if (c < 7) FA_SLOAD(vp, c + 1);
;             }
;             LAS unsigned char* slot = lds + (c & 1) * ATT_SLOT;
;             if (c < 4) {
;                 {
;                     bf16x8 Kf[2][4];
;                     __builtin_amdgcn_s_setprio(1);
; #pragma unroll
;                     for (int ml = 0; ml < 4; ++ml) Kf[0][ml] = *(LAS bf16x8*)(slot + (16 * ml + fr) * 544 + (8 * fq) * 2);
;                     __builtin_amdgcn_sched_group_barrier(0x100, 4, 0);
; #pragma unroll
;                     for (int ks = 0; ks < 8; ++ks) {
;                         if (ks < 7) {
; #pragma unroll
;                             for (int ml = 0; ml < 4; ++ml) Kf[(ks + 1) & 1][ml] = *(LAS bf16x8*)(slot + (16 * ml + fr) * 544 + (32 * (ks + 1) + 8 * fq) * 2);
;                         }
; #pragma unroll
;                         for (int ml = 0; ml < 4; ++ml) S[4 * c + ml] = MFMA16(Kf[ks & 1][ml], Qf[ks], ks == 0 ? zero4 : S[4 * c + ml]);
;                         __builtin_amdgcn_sched_group_barrier(0x100, 4, 0); __builtin_amdgcn_sched_group_barrier(0x008, 4, 0);
	v_mfma_f32_16x16x32_bf16 v[92:95], v[124:127], v[32:35], v[92:95]
	ds_read_b128 v[96:99], v189 offset:35008
	ds_read_b128 v[100:103], v189 offset:43712
	ds_read_b128 v[120:123], v189 offset:52416
	ds_read_b128 v[124:127], v189 offset:61120
	s_waitcnt lgkmcnt(7)
	v_mfma_f32_16x16x32_bf16 v[72:75], v[160:163], v[28:31], v[72:75]
	s_waitcnt lgkmcnt(6)
	v_mfma_f32_16x16x32_bf16 v[76:79], v[164:167], v[28:31], v[76:79]
	s_waitcnt lgkmcnt(5)
	v_mfma_f32_16x16x32_bf16 v[88:91], v[194:197], v[28:31], v[88:91]
	s_waitcnt lgkmcnt(4)
	v_mfma_f32_16x16x32_bf16 v[92:95], v[202:205], v[28:31], v[92:95]
	ds_read_b128 v[160:163], v189 offset:35072
	ds_read_b128 v[164:167], v189 offset:43776
	ds_read_b128 v[194:197], v189 offset:52480
	ds_read_b128 v[202:205], v189 offset:61184
	s_waitcnt lgkmcnt(7)
	v_mfma_f32_16x16x32_bf16 v[72:75], v[96:99], v[24:27], v[72:75]
	s_waitcnt lgkmcnt(6)
	v_mfma_f32_16x16x32_bf16 v[76:79], v[100:103], v[24:27], v[76:79]
	s_waitcnt lgkmcnt(5)
	v_mfma_f32_16x16x32_bf16 v[88:91], v[120:123], v[24:27], v[88:91]
	s_waitcnt lgkmcnt(4)
	v_mfma_f32_16x16x32_bf16 v[92:95], v[124:127], v[24:27], v[92:95]
	ds_read_b128 v[96:99], v189 offset:35136
	ds_read_b128 v[100:103], v189 offset:43840
	ds_read_b128 v[120:123], v189 offset:52544
	ds_read_b128 v[124:127], v189 offset:61248
	s_waitcnt lgkmcnt(7)
	v_mfma_f32_16x16x32_bf16 v[72:75], v[160:163], v[20:23], v[72:75]
	s_waitcnt lgkmcnt(6)
	v_mfma_f32_16x16x32_bf16 v[76:79], v[164:167], v[20:23], v[76:79]
	s_waitcnt lgkmcnt(5)
	v_mfma_f32_16x16x32_bf16 v[88:91], v[194:197], v[20:23], v[88:91]
	s_waitcnt lgkmcnt(4)
	v_mfma_f32_16x16x32_bf16 v[92:95], v[202:205], v[20:23], v[92:95]
	ds_read_b128 v[160:163], v189 offset:35200
	ds_read_b128 v[164:167], v189 offset:43904
	ds_read_b128 v[194:197], v189 offset:52608
	ds_read_b128 v[202:205], v189 offset:61312
	s_waitcnt lgkmcnt(7)
	v_mfma_f32_16x16x32_bf16 v[72:75], v[96:99], v[16:19], v[72:75]
	s_waitcnt lgkmcnt(6)
	v_mfma_f32_16x16x32_bf16 v[76:79], v[100:103], v[16:19], v[76:79]
	s_waitcnt lgkmcnt(5)
	v_mfma_f32_16x16x32_bf16 v[88:91], v[120:123], v[16:19], v[88:91]
	s_waitcnt lgkmcnt(4)
	v_mfma_f32_16x16x32_bf16 v[92:95], v[124:127], v[16:19], v[92:95]
	ds_read_b128 v[96:99], v189 offset:35264
	ds_read_b128 v[120:123], v189 offset:43968
	ds_read_b128 v[124:127], v189 offset:52672
	ds_read_b128 v[206:209], v189 offset:61376
	s_waitcnt lgkmcnt(7)
	v_mfma_f32_16x16x32_bf16 v[72:75], v[160:163], v[12:15], v[72:75]
	s_waitcnt lgkmcnt(6)
	v_mfma_f32_16x16x32_bf16 v[76:79], v[164:167], v[12:15], v[76:79]
	s_waitcnt lgkmcnt(5)
	v_mfma_f32_16x16x32_bf16 v[88:91], v[194:197], v[12:15], v[88:91]
	s_waitcnt lgkmcnt(4)
	v_mfma_f32_16x16x32_bf16 v[92:95], v[202:205], v[12:15], v[92:95]
	s_waitcnt lgkmcnt(3)
	v_mfma_f32_16x16x32_bf16 v[100:103], v[96:99], v[8:11], v[72:75]
	s_waitcnt lgkmcnt(2)
	v_mfma_f32_16x16x32_bf16 v[96:99], v[120:123], v[8:11], v[76:79]
	s_waitcnt lgkmcnt(1)
	v_mfma_f32_16x16x32_bf16 v[88:91], v[124:127], v[8:11], v[88:91]
	s_waitcnt lgkmcnt(0)
	v_mfma_f32_16x16x32_bf16 v[92:95], v[206:209], v[8:11], v[92:95]
	s_setprio 0
	ds_write_b128 v191, v[80:83]
	ds_write_b128 v191, v[84:87] offset:8704
	ds_write_b128 v191, v[104:107] offset:17408
	ds_write_b128 v191, v[108:111] offset:26112
	s_mov_b64 s[62:63], s[16:17]
	s_waitcnt lgkmcnt(0)
	s_barrier
	s_mov_b64 s[64:65], -1
	v_lshl_add_u64 v[80:81], s[62:63], 0, v[176:177]
	v_add_co_u32_e32 v76, vcc, 0x8000, v80
	global_load_dwordx4 v[72:75], v[80:81], off
	s_nop 0
	v_addc_co_u32_e32 v77, vcc, 0, v81, vcc
	v_add_co_u32_e32 v82, vcc, 0x10000, v80
	global_load_dwordx4 v[76:79], v[76:77], off
	s_nop 0
	v_addc_co_u32_e32 v83, vcc, 0, v81, vcc
	v_add_co_u32_e32 v84, vcc, 0x18000, v80
	s_nop 1
	v_addc_co_u32_e32 v85, vcc, 0, v81, vcc
	global_load_dwordx4 v[80:83], v[82:83], off
	s_and_b64 vcc, exec, s[6:7]
	global_load_dwordx4 v[84:87], v[84:85], off
	s_cbranch_vccnz .LBB0_2060
	s_waitcnt vmcnt(8)
	v_add_u32_e32 v128, m0, v200
	v_and_b32_e32 v128, 0xffffefff, v128
	ds_read_b128 v[140:143], v128
	ds_read_b128 v[136:139], v128 offset:1024
	ds_read_b128 v[132:135], v128 offset:2048
	ds_read_b128 v[128:131], v128 offset:3072
	s_waitcnt lgkmcnt(0)
	v_mov_b32_e32 v108, s69
	ds_read_b128 v[104:107], v108 offset:1280
	ds_read_b128 v[108:111], v108 offset:256
	s_mov_b64 s[62:63], s[34:35]
	s_mov_b64 s[64:65], 0
	s_waitcnt lgkmcnt(1)
	v_sub_f32_e32 v104, v104, v193
	v_sub_f32_e32 v105, v105, v193
	v_exp_f32_e32 v104, v104
	v_exp_f32_e32 v105, v105
	v_sub_f32_e32 v106, v106, v193
	v_exp_f32_e32 v122, v106
	v_mul_f32_e32 v104, v182, v104
	v_mul_f32_e32 v106, v182, v105
	s_waitcnt vmcnt(8)
	v_pk_fma_f32 v[120:121], v[154:155], v[104:105], v[114:115] op_sel_hi:[1,0,1]
	v_pk_fma_f32 v[104:105], v[152:153], v[104:105], v[112:113] op_sel_hi:[1,0,1]
	v_pk_fma_f32 v[120:121], v[146:147], v[106:107], v[120:121] op_sel_hi:[1,0,1]
	v_pk_fma_f32 v[104:105], v[144:145], v[106:107], v[104:105] op_sel_hi:[1,0,1]
	v_sub_f32_e32 v106, v107, v193
	v_exp_f32_e32 v107, v106
	v_mul_f32_e32 v106, v182, v122
	s_waitcnt vmcnt(8)
	v_pk_fma_f32 v[120:121], v[138:139], v[106:107], v[120:121] op_sel_hi:[1,0,1]
	v_pk_fma_f32 v[104:105], v[136:137], v[106:107], v[104:105] op_sel_hi:[1,0,1]
	v_mul_f32_e32 v106, v182, v107
	s_waitcnt vmcnt(8)
	v_pk_fma_f32 v[122:123], v[130:131], v[106:107], v[120:121] op_sel_hi:[1,0,1]
	s_waitcnt lgkmcnt(0)
	v_sub_f32_e32 v107, v108, v192
	v_exp_f32_e32 v107, v107
	s_nop 0
	v_pk_fma_f32 v[120:121], v[128:129], v[106:107], v[104:105] op_sel_hi:[1,0,1]
	v_sub_f32_e32 v104, v109, v192
	v_exp_f32_e32 v108, v104
	v_mul_f32_e32 v104, v169, v107
	v_pk_fma_f32 v[106:107], v[158:159], v[104:105], v[118:119] op_sel_hi:[1,0,1]
	v_pk_fma_f32 v[104:105], v[156:157], v[104:105], v[116:117] op_sel_hi:[1,0,1]
	v_mul_f32_e32 v108, v169, v108
	v_pk_fma_f32 v[106:107], v[150:151], v[108:109], v[106:107] op_sel_hi:[1,0,1]
	v_sub_f32_e32 v109, v110, v192
	v_exp_f32_e32 v109, v109
	s_nop 0
	v_pk_fma_f32 v[104:105], v[148:149], v[108:109], v[104:105] op_sel_hi:[1,0,1]
	v_sub_f32_e32 v108, v111, v192
	v_exp_f32_e32 v110, v108
	v_mul_f32_e32 v108, v169, v109
	v_pk_fma_f32 v[106:107], v[142:143], v[108:109], v[106:107] op_sel_hi:[1,0,1]
	v_pk_fma_f32 v[104:105], v[140:141], v[108:109], v[104:105] op_sel_hi:[1,0,1]
	v_mul_f32_e32 v108, v169, v110
	v_pk_fma_f32 v[126:127], v[134:135], v[108:109], v[106:107] op_sel_hi:[1,0,1]
	v_pk_fma_f32 v[124:125], v[132:133], v[108:109], v[104:105] op_sel_hi:[1,0,1]
; __device__ __forceinline__ float dot4(f32x4 a, f32x4 b) { return (a[0] * b[0] + a[1] * b[1]) + (a[2] * b[2] + a[3] * b[3]); }
; #define dpp_mov(v, ctrl, row_mask) __builtin_bit_cast(float, __builtin_amdgcn_update_dpp(0, __builtin_bit_cast(int, (float)(v)), (ctrl), (row_mask), 0xf, false))
; __device__ __forceinline__ float wave_sum_dpp(float x) {
;     x += dpp_mov(x, 0xB1, 0xf);
;     x += dpp_mov(x, 0x4E, 0xf);
;     x += dpp_mov(x, 0x141, 0xf);
;     x += dpp_mov(x, 0x140, 0xf);
;     x += dpp_mov(x, 0x142, 0xa);
;     x += dpp_mov(x, 0x143, 0xc);
;     return x;
; }
; __device__ __forceinline__ void attn_fused(Frame& F0, int layer) {
;     ...
;             if (ui == 0) {
; #pragma unroll
;                 for (int r = 0; r < 4; ++r) {
;                     const int m = 32 * c + 4 * w + r;
;                     const float d0 = wave_sum_dpp(dot4(sv[2 * r], q0)), d1 = wave_sum_dpp(dot4(sv[2 * r + 1], q1));
;                     if (lane == 63) { sc[m] = d0; sc[256 + m] = d1; }
;                 }
;                 if (c < 7) FA_SLOAD(kp, c + 1); else FA_SLOAD(vp, 0);
.LBB0_2060:
	s_andn2_b64 vcc, exec, s[64:65]
	s_cbranch_vccnz .LBB0_2070
	s_waitcnt vmcnt(8)
	v_add_u32_e32 v128, m0, v200
	v_and_b32_e32 v128, 0xffffefff, v128
	ds_read_b128 v[140:143], v128
	ds_read_b128 v[136:139], v128 offset:1024
	ds_read_b128 v[132:135], v128 offset:2048
	ds_read_b128 v[128:131], v128 offset:3072
	s_waitcnt lgkmcnt(0)
	s_waitcnt vmcnt(11)
	v_mul_f32_e32 v104, v1, v157
	v_mul_f32_e32 v105, v3, v159
	s_waitcnt vmcnt(8)
	v_mul_f32_e32 v106, v5, v153
	v_mul_f32_e32 v107, v7, v155
	v_fmac_f32_e32 v104, v0, v156
	v_fmac_f32_e32 v105, v2, v158
	v_fmac_f32_e32 v106, v4, v152
	v_fmac_f32_e32 v107, v6, v154
	v_add_f32_e32 v104, v104, v105
	v_add_f32_e32 v106, v106, v107
	v_mov_b32_e32 v105, v201
	v_add_f32_dpp v104, v104, v104 quad_perm:[1,0,3,2] row_mask:0xf bank_mask:0xf bound_ctrl:1
	v_add_f32_dpp v106, v106, v106 quad_perm:[1,0,3,2] row_mask:0xf bank_mask:0xf bound_ctrl:1
	v_mov_b32_e32 v107, v201
	v_add_f32_dpp v104, v104, v104 quad_perm:[2,3,0,1] row_mask:0xf bank_mask:0xf bound_ctrl:1
	v_add_f32_dpp v106, v106, v106 quad_perm:[2,3,0,1] row_mask:0xf bank_mask:0xf bound_ctrl:1
	s_nop 0
	v_add_f32_dpp v104, v104, v104 row_half_mirror row_mask:0xf bank_mask:0xf bound_ctrl:1
	v_add_f32_dpp v106, v106, v106 row_half_mirror row_mask:0xf bank_mask:0xf bound_ctrl:1
	s_nop 0
	v_add_f32_dpp v104, v104, v104 row_mirror row_mask:0xf bank_mask:0xf bound_ctrl:1
	v_add_f32_dpp v106, v106, v106 row_mirror row_mask:0xf bank_mask:0xf bound_ctrl:1
	s_nop 0
	v_mov_b32_dpp v105, v104 row_bcast:15 row_mask:0xa bank_mask:0xf
	v_mov_b32_dpp v107, v106 row_bcast:15 row_mask:0xa bank_mask:0xf
	v_add_f32_e32 v104, v104, v105
	v_mov_b32_e32 v105, v201
	v_add_f32_e32 v106, v106, v107
	v_mov_b32_e32 v107, v201
	v_mov_b32_dpp v105, v104 row_bcast:31 row_mask:0xc bank_mask:0xf
	s_nop 0
	v_mov_b32_dpp v107, v106 row_bcast:31 row_mask:0xc bank_mask:0xf
	s_and_saveexec_b64 s[62:63], s[4:5]
	v_add_f32_e32 v104, v104, v105
	v_add_f32_e32 v105, v106, v107
	v_mov_b32_e32 v106, s69
	ds_write2st64_b32 v106, v104, v105 offset0:1 offset1:5
	s_or_b64 exec, exec, s[62:63]
	v_mul_f32_e32 v104, v1, v149
	v_mul_f32_e32 v105, v3, v151
	v_mul_f32_e32 v106, v5, v145
	v_mul_f32_e32 v107, v7, v147
	v_fmac_f32_e32 v104, v0, v148
	v_fmac_f32_e32 v105, v2, v150
	v_fmac_f32_e32 v106, v4, v144
	v_fmac_f32_e32 v107, v6, v146
	v_add_f32_e32 v104, v104, v105
	v_add_f32_e32 v106, v106, v107
	v_mov_b32_e32 v105, v201
	v_add_f32_dpp v104, v104, v104 quad_perm:[1,0,3,2] row_mask:0xf bank_mask:0xf bound_ctrl:1
	v_add_f32_dpp v106, v106, v106 quad_perm:[1,0,3,2] row_mask:0xf bank_mask:0xf bound_ctrl:1
	v_mov_b32_e32 v107, v201
	v_add_f32_dpp v104, v104, v104 quad_perm:[2,3,0,1] row_mask:0xf bank_mask:0xf bound_ctrl:1
	v_add_f32_dpp v106, v106, v106 quad_perm:[2,3,0,1] row_mask:0xf bank_mask:0xf bound_ctrl:1
	s_nop 0
	v_add_f32_dpp v104, v104, v104 row_half_mirror row_mask:0xf bank_mask:0xf bound_ctrl:1
	v_add_f32_dpp v106, v106, v106 row_half_mirror row_mask:0xf bank_mask:0xf bound_ctrl:1
	s_nop 0
	v_add_f32_dpp v104, v104, v104 row_mirror row_mask:0xf bank_mask:0xf bound_ctrl:1
	v_add_f32_dpp v106, v106, v106 row_mirror row_mask:0xf bank_mask:0xf bound_ctrl:1
	s_nop 0
	v_mov_b32_dpp v105, v104 row_bcast:15 row_mask:0xa bank_mask:0xf
	v_mov_b32_dpp v107, v106 row_bcast:15 row_mask:0xa bank_mask:0xf
	v_add_f32_e32 v104, v104, v105
	v_mov_b32_e32 v105, v201
	v_add_f32_e32 v106, v106, v107
	v_mov_b32_e32 v107, v201
	v_mov_b32_dpp v105, v104 row_bcast:31 row_mask:0xc bank_mask:0xf
	s_nop 0
	v_mov_b32_dpp v107, v106 row_bcast:31 row_mask:0xc bank_mask:0xf
	s_and_saveexec_b64 s[62:63], s[4:5]
	v_add_f32_e32 v104, v104, v105
	v_add_f32_e32 v105, v106, v107
	v_add_u32_e64 v106, 4, s69
	ds_write2st64_b32 v106, v104, v105 offset0:1 offset1:5
	s_or_b64 exec, exec, s[62:63]
	s_waitcnt vmcnt(8)
	v_mul_f32_e32 v104, v1, v141
	v_mul_f32_e32 v105, v3, v143
	s_waitcnt vmcnt(8)
	v_mul_f32_e32 v106, v5, v137
	v_mul_f32_e32 v107, v7, v139
	v_fmac_f32_e32 v104, v0, v140
	v_fmac_f32_e32 v105, v2, v142
	v_fmac_f32_e32 v106, v4, v136
	v_fmac_f32_e32 v107, v6, v138
	v_add_f32_e32 v104, v104, v105
	v_add_f32_e32 v106, v106, v107
	v_mov_b32_e32 v105, v201
	v_add_f32_dpp v104, v104, v104 quad_perm:[1,0,3,2] row_mask:0xf bank_mask:0xf bound_ctrl:1
	v_add_f32_dpp v106, v106, v106 quad_perm:[1,0,3,2] row_mask:0xf bank_mask:0xf bound_ctrl:1
	v_mov_b32_e32 v107, v201
	v_add_f32_dpp v104, v104, v104 quad_perm:[2,3,0,1] row_mask:0xf bank_mask:0xf bound_ctrl:1
	v_add_f32_dpp v106, v106, v106 quad_perm:[2,3,0,1] row_mask:0xf bank_mask:0xf bound_ctrl:1
	s_nop 0
	v_add_f32_dpp v104, v104, v104 row_half_mirror row_mask:0xf bank_mask:0xf bound_ctrl:1
	v_add_f32_dpp v106, v106, v106 row_half_mirror row_mask:0xf bank_mask:0xf bound_ctrl:1
	s_nop 0
	v_add_f32_dpp v104, v104, v104 row_mirror row_mask:0xf bank_mask:0xf bound_ctrl:1
	v_add_f32_dpp v106, v106, v106 row_mirror row_mask:0xf bank_mask:0xf bound_ctrl:1
	s_nop 0
	v_mov_b32_dpp v105, v104 row_bcast:15 row_mask:0xa bank_mask:0xf
	v_mov_b32_dpp v107, v106 row_bcast:15 row_mask:0xa bank_mask:0xf
	v_add_f32_e32 v104, v104, v105
	v_mov_b32_e32 v105, v201
	v_add_f32_e32 v106, v106, v107
	v_mov_b32_e32 v107, v201
	v_mov_b32_dpp v105, v104 row_bcast:31 row_mask:0xc bank_mask:0xf
	s_nop 0
	v_mov_b32_dpp v107, v106 row_bcast:31 row_mask:0xc bank_mask:0xf
	s_and_saveexec_b64 s[62:63], s[4:5]
	v_add_f32_e32 v104, v104, v105
	v_add_f32_e32 v105, v106, v107
	v_add_u32_e64 v106, 8, s69
	ds_write2st64_b32 v106, v104, v105 offset0:1 offset1:5
	s_or_b64 exec, exec, s[62:63]
	s_waitcnt vmcnt(8)
	v_mul_f32_e32 v104, v1, v133
	v_mul_f32_e32 v105, v3, v135
	s_waitcnt vmcnt(8)
; #define LAS __attribute__((address_space(3)))
; __device__ __forceinline__ float dot4(f32x4 a, f32x4 b) { return (a[0] * b[0] + a[1] * b[1]) + (a[2] * b[2] + a[3] * b[3]); }
; #define MFMA16(a, b, c) __builtin_amdgcn_mfma_f32_16x16x32_bf16((a), (b), (c), 0, 0, 0)
; __device__ __forceinline__ void attn_fused(Frame& F0, int layer) {
;     ...
;             if (ui == 0) {
; #pragma unroll
;                 for (int r = 0; r < 4; ++r) {
;                     const int m = 32 * c + 4 * w + r;
;                     const float d0 = wave_sum_dpp(dot4(sv[2 * r], q0)), d1 = wave_sum_dpp(dot4(sv[2 * r + 1], q1));
;                     if (lane == 63) { sc[m] = d0; sc[256 + m] = d1; }
;                 }
;                 if (c < 7) FA_SLOAD(kp, c + 1); else FA_SLOAD(vp, 0);
;             } else {
; #pragma unroll
;                 for (int r = 0; r < 4; ++r) {
;                     const int m = 32 * c + 4 * w + r;
;                     const float p0 = __builtin_amdgcn_exp2f(sc[m] - mx0) * iv0, p1 = __builtin_amdgcn_exp2f(sc[256 + m] - mx1) * iv1;
;                     a0 += sv[2 * r] * p0; a1 += sv[2 * r + 1] * p1;
;                 }
;                 if (c < 7) FA_SLOAD(vp, c + 1);
;             }
;             LAS unsigned char* slot = lds + (c & 1) * ATT_SLOT;
;             if (c < 4) {
;                 {
;                     bf16x8 Kf[2][4];
;                     __builtin_amdgcn_s_setprio(1);
; #pragma unroll
;                     for (int ml = 0; ml < 4; ++ml) Kf[0][ml] = *(LAS bf16x8*)(slot + (16 * ml + fr) * 544 + (8 * fq) * 2);
;                     __builtin_amdgcn_sched_group_barrier(0x100, 4, 0);
; #pragma unroll
;                     for (int ks = 0; ks < 8; ++ks) {
;                         if (ks < 7) {
; #pragma unroll
;                             for (int ml = 0; ml < 4; ++ml) Kf[(ks + 1) & 1][ml] = *(LAS bf16x8*)(slot + (16 * ml + fr) * 544 + (32 * (ks + 1) + 8 * fq) * 2);
;                         }
; #pragma unroll
;                         for (int ml = 0; ml < 4; ++ml) S[4 * c + ml] = MFMA16(Kf[ks & 1][ml], Qf[ks], ks == 0 ? zero4 : S[4 * c + ml]);
;                         __builtin_amdgcn_sched_group_barrier(0x100, 4, 0); __builtin_amdgcn_sched_group_barrier(0x008, 4, 0);
	v_mul_f32_e32 v106, v5, v129
	v_mul_f32_e32 v107, v7, v131
	v_fmac_f32_e32 v104, v0, v132
	v_fmac_f32_e32 v105, v2, v134
	v_fmac_f32_e32 v106, v4, v128
	v_fmac_f32_e32 v107, v6, v130
	v_add_f32_e32 v104, v104, v105
	v_add_f32_e32 v106, v106, v107
	v_mov_b32_e32 v105, v201
	v_add_f32_dpp v104, v104, v104 quad_perm:[1,0,3,2] row_mask:0xf bank_mask:0xf bound_ctrl:1
	v_add_f32_dpp v106, v106, v106 quad_perm:[1,0,3,2] row_mask:0xf bank_mask:0xf bound_ctrl:1
	v_mov_b32_e32 v107, v201
	v_add_f32_dpp v104, v104, v104 quad_perm:[2,3,0,1] row_mask:0xf bank_mask:0xf bound_ctrl:1
	v_add_f32_dpp v106, v106, v106 quad_perm:[2,3,0,1] row_mask:0xf bank_mask:0xf bound_ctrl:1
	s_nop 0
	v_add_f32_dpp v104, v104, v104 row_half_mirror row_mask:0xf bank_mask:0xf bound_ctrl:1
	v_add_f32_dpp v106, v106, v106 row_half_mirror row_mask:0xf bank_mask:0xf bound_ctrl:1
	s_nop 0
	v_add_f32_dpp v104, v104, v104 row_mirror row_mask:0xf bank_mask:0xf bound_ctrl:1
	v_add_f32_dpp v106, v106, v106 row_mirror row_mask:0xf bank_mask:0xf bound_ctrl:1
	s_nop 0
	v_mov_b32_dpp v105, v104 row_bcast:15 row_mask:0xa bank_mask:0xf
	v_mov_b32_dpp v107, v106 row_bcast:15 row_mask:0xa bank_mask:0xf
	v_add_f32_e32 v104, v104, v105
	v_mov_b32_e32 v105, v201
	v_add_f32_e32 v106, v106, v107
	v_mov_b32_e32 v107, v201
	v_mov_b32_dpp v105, v104 row_bcast:31 row_mask:0xc bank_mask:0xf
	s_nop 0
	v_mov_b32_dpp v107, v106 row_bcast:31 row_mask:0xc bank_mask:0xf
	s_and_saveexec_b64 s[62:63], s[4:5]
	v_add_f32_e32 v104, v104, v105
	v_add_f32_e32 v105, v106, v107
	v_add_u32_e64 v106, 12, s69
	ds_write2st64_b32 v106, v104, v105 offset0:1 offset1:5
	s_or_b64 exec, exec, s[62:63]
	v_mov_b64_e32 v[126:127], v[118:119]
	v_mov_b64_e32 v[122:123], v[114:115]
	s_mov_b64 s[62:63], s[36:37]
	v_mov_b64_e32 v[124:125], v[116:117]
	v_mov_b64_e32 v[120:121], v[112:113]
.LBB0_2070:
	s_nop 0
	s_add_u32 s100, s62, 0x20000
	s_addc_u32 s101, s63, 0
	v_lshl_add_u64 v[104:105], s[62:63], 0, v[200:201]
	v_add_co_u32_e32 v106, vcc, 0x1000, v104
	global_load_dwordx4 v[164:167], v[104:105], off nt
	s_nop 0
	v_addc_co_u32_e32 v107, vcc, 0, v105, vcc
	global_load_dwordx4 v[156:159], v[106:107], off nt
	global_load_dwordx4 v[152:155], v[106:107], off offset:1024 nt
	v_add_co_u32_e32 v106, vcc, 0x2000, v104
	global_load_dwordx4 v[160:163], v[104:105], off offset:1024 nt
	s_nop 0
	v_addc_co_u32_e32 v107, vcc, 0, v105, vcc
	v_add_co_u32_e32 v104, vcc, 0x3000, v104
	s_nop 0
	v_addc_co_u32_e32 v105, vcc, 0, v105, vcc
	s_bitset0_b32 m0, 12
	v_add_u32_e32 v130, 0x2000, v200
	v_add_u32_e32 v131, 0x2800, v200
	global_load_lds_dwordx4 v130, s[100:101] nt
	global_load_lds_dwordx4 v130, s[100:101] offset:1024 nt
	global_load_lds_dwordx4 v131, s[100:101] offset:2048 nt
	global_load_lds_dwordx4 v131, s[100:101] offset:3072 nt
	s_setprio 1
	ds_read_b128 v[104:107], v189
	ds_read_b128 v[108:111], v189 offset:8704
	ds_read_b128 v[112:115], v189 offset:17408
	ds_read_b128 v[116:119], v189 offset:26112
	s_waitcnt vmcnt(16)
	ds_read_b128 v[136:139], v189 offset:64
	ds_read_b128 v[144:147], v189 offset:8768
	ds_read_b128 v[194:197], v189 offset:17472
	ds_read_b128 v[202:205], v189 offset:26176
	s_waitcnt lgkmcnt(7)
	v_mfma_f32_16x16x32_bf16 v[104:107], v[104:107], v[36:39], 0
	s_waitcnt lgkmcnt(6)
	v_mfma_f32_16x16x32_bf16 v[108:111], v[108:111], v[36:39], 0
	s_waitcnt lgkmcnt(5)
	v_mfma_f32_16x16x32_bf16 v[112:115], v[112:115], v[36:39], 0
	s_waitcnt lgkmcnt(4)
	v_mfma_f32_16x16x32_bf16 v[116:119], v[116:119], v[36:39], 0
	ds_read_b128 v[206:209], v189 offset:128
	ds_read_b128 v[212:215], v189 offset:8832
	ds_read_b128 v[216:219], v189 offset:17536
	ds_read_b128 v[220:223], v189 offset:26240
	s_waitcnt lgkmcnt(7)
	v_mfma_f32_16x16x32_bf16 v[104:107], v[136:139], v[32:35], v[104:107]
	s_waitcnt lgkmcnt(6)
	v_mfma_f32_16x16x32_bf16 v[108:111], v[144:147], v[32:35], v[108:111]
	s_waitcnt lgkmcnt(5)
	v_mfma_f32_16x16x32_bf16 v[112:115], v[194:197], v[32:35], v[112:115]
	s_waitcnt lgkmcnt(4)
	v_mfma_f32_16x16x32_bf16 v[116:119], v[202:205], v[32:35], v[116:119]
	ds_read_b128 v[136:139], v189 offset:192
	ds_read_b128 v[144:147], v189 offset:8896
	ds_read_b128 v[194:197], v189 offset:17600
	ds_read_b128 v[202:205], v189 offset:26304
	s_waitcnt lgkmcnt(7)
	v_mfma_f32_16x16x32_bf16 v[104:107], v[206:209], v[28:31], v[104:107]
	s_waitcnt lgkmcnt(6)
	v_mfma_f32_16x16x32_bf16 v[108:111], v[212:215], v[28:31], v[108:111]
	s_waitcnt lgkmcnt(5)
	v_mfma_f32_16x16x32_bf16 v[112:115], v[216:219], v[28:31], v[112:115]
	s_waitcnt lgkmcnt(4)
	v_mfma_f32_16x16x32_bf16 v[116:119], v[220:223], v[28:31], v[116:119]
	ds_read_b128 v[206:209], v189 offset:256
	ds_read_b128 v[212:215], v189 offset:8960
	ds_read_b128 v[216:219], v189 offset:17664
	ds_read_b128 v[220:223], v189 offset:26368
	s_waitcnt lgkmcnt(7)
	v_mfma_f32_16x16x32_bf16 v[104:107], v[136:139], v[24:27], v[104:107]
	s_waitcnt lgkmcnt(6)
	v_mfma_f32_16x16x32_bf16 v[108:111], v[144:147], v[24:27], v[108:111]
	s_waitcnt lgkmcnt(5)
	v_mfma_f32_16x16x32_bf16 v[112:115], v[194:197], v[24:27], v[112:115]
	s_waitcnt lgkmcnt(4)
	v_mfma_f32_16x16x32_bf16 v[116:119], v[202:205], v[24:27], v[116:119]
	ds_read_b128 v[136:139], v189 offset:320
	ds_read_b128 v[144:147], v189 offset:9024
	ds_read_b128 v[194:197], v189 offset:17728
	ds_read_b128 v[202:205], v189 offset:26432
	s_waitcnt lgkmcnt(7)
	v_mfma_f32_16x16x32_bf16 v[104:107], v[206:209], v[20:23], v[104:107]
	s_waitcnt lgkmcnt(6)
	v_mfma_f32_16x16x32_bf16 v[108:111], v[212:215], v[20:23], v[108:111]
	s_waitcnt lgkmcnt(5)
	v_mfma_f32_16x16x32_bf16 v[112:115], v[216:219], v[20:23], v[112:115]
	s_waitcnt lgkmcnt(4)
; #define LAS __attribute__((address_space(3)))
; __device__ __forceinline__ float dot4(f32x4 a, f32x4 b) { return (a[0] * b[0] + a[1] * b[1]) + (a[2] * b[2] + a[3] * b[3]); }
; #define MFMA16(a, b, c) __builtin_amdgcn_mfma_f32_16x16x32_bf16((a), (b), (c), 0, 0, 0)
; __device__ __forceinline__ void attn_fused(Frame& F0, int layer) {
;     ...
;             if (c < 6) ATT_GLOAD(c + 2);
;             if (ui == 0) {
; #pragma unroll
;                 for (int r = 0; r < 4; ++r) {
;                     const int m = 32 * c + 4 * w + r;
;                     const float d0 = wave_sum_dpp(dot4(sv[2 * r], q0)), d1 = wave_sum_dpp(dot4(sv[2 * r + 1], q1));
;                     if (lane == 63) { sc[m] = d0; sc[256 + m] = d1; }
;                 }
;                 if (c < 7) FA_SLOAD(kp, c + 1); else FA_SLOAD(vp, 0);
;             } else {
; #pragma unroll
;                 for (int r = 0; r < 4; ++r) {
;                     const int m = 32 * c + 4 * w + r;
;                     const float p0 = __builtin_amdgcn_exp2f(sc[m] - mx0) * iv0, p1 = __builtin_amdgcn_exp2f(sc[256 + m] - mx1) * iv1;
;                     a0 += sv[2 * r] * p0; a1 += sv[2 * r + 1] * p1;
;                 }
;                 if (c < 7) FA_SLOAD(vp, c + 1);
;             }
;             LAS unsigned char* slot = lds + (c & 1) * ATT_SLOT;
;             if (c < 4) {
;                 {
;                     bf16x8 Kf[2][4];
;                     __builtin_amdgcn_s_setprio(1);
; #pragma unroll
;                     for (int ml = 0; ml < 4; ++ml) Kf[0][ml] = *(LAS bf16x8*)(slot + (16 * ml + fr) * 544 + (8 * fq) * 2);
;                     __builtin_amdgcn_sched_group_barrier(0x100, 4, 0);
; #pragma unroll
;                     for (int ks = 0; ks < 8; ++ks) {
;                         if (ks < 7) {
; #pragma unroll
;                             for (int ml = 0; ml < 4; ++ml) Kf[(ks + 1) & 1][ml] = *(LAS bf16x8*)(slot + (16 * ml + fr) * 544 + (32 * (ks + 1) + 8 * fq) * 2);
;                         }
; #pragma unroll
;                         for (int ml = 0; ml < 4; ++ml) S[4 * c + ml] = MFMA16(Kf[ks & 1][ml], Qf[ks], ks == 0 ? zero4 : S[4 * c + ml]);
;                         __builtin_amdgcn_sched_group_barrier(0x100, 4, 0); __builtin_amdgcn_sched_group_barrier(0x008, 4, 0);
	v_mfma_f32_16x16x32_bf16 v[116:119], v[220:223], v[20:23], v[116:119]
	ds_read_b128 v[206:209], v189 offset:384
	ds_read_b128 v[212:215], v189 offset:9088
	ds_read_b128 v[216:219], v189 offset:17792
	ds_read_b128 v[220:223], v189 offset:26496
	s_waitcnt lgkmcnt(7)
	v_mfma_f32_16x16x32_bf16 v[104:107], v[136:139], v[16:19], v[104:107]
	s_waitcnt lgkmcnt(6)
	v_mfma_f32_16x16x32_bf16 v[108:111], v[144:147], v[16:19], v[108:111]
	s_waitcnt lgkmcnt(5)
	v_mfma_f32_16x16x32_bf16 v[112:115], v[194:197], v[16:19], v[112:115]
	s_waitcnt lgkmcnt(4)
	v_mfma_f32_16x16x32_bf16 v[116:119], v[202:205], v[16:19], v[116:119]
	ds_read_b128 v[136:139], v189 offset:448
	ds_read_b128 v[194:197], v189 offset:9152
	ds_read_b128 v[202:205], v189 offset:17856
	ds_read_b128 v[224:227], v189 offset:26560
	s_waitcnt lgkmcnt(7)
	v_mfma_f32_16x16x32_bf16 v[104:107], v[206:209], v[12:15], v[104:107]
	s_waitcnt lgkmcnt(6)
	v_mfma_f32_16x16x32_bf16 v[108:111], v[212:215], v[12:15], v[108:111]
	s_waitcnt lgkmcnt(5)
	v_mfma_f32_16x16x32_bf16 v[112:115], v[216:219], v[12:15], v[112:115]
	s_waitcnt lgkmcnt(4)
	v_mfma_f32_16x16x32_bf16 v[116:119], v[220:223], v[12:15], v[116:119]
	s_waitcnt lgkmcnt(3)
	v_mfma_f32_16x16x32_bf16 v[144:147], v[136:139], v[8:11], v[104:107]
	s_waitcnt lgkmcnt(2)
	v_mfma_f32_16x16x32_bf16 v[136:139], v[194:197], v[8:11], v[108:111]
	s_waitcnt lgkmcnt(1)
	v_mfma_f32_16x16x32_bf16 v[112:115], v[202:205], v[8:11], v[112:115]
	s_waitcnt lgkmcnt(0)
	v_mfma_f32_16x16x32_bf16 v[116:119], v[224:227], v[8:11], v[116:119]
	s_setprio 0
	ds_write_b128 v191, v[56:59] offset:34816
	ds_write_b128 v191, v[60:63] offset:43520
	ds_write_b128 v191, v[64:67] offset:52224
	ds_write_b128 v191, v[68:71] offset:60928
	s_mov_b64 s[62:63], s[38:39]
	s_waitcnt lgkmcnt(0)
	s_barrier
	s_mov_b64 s[64:65], -1
	v_lshl_add_u64 v[64:65], s[62:63], 0, v[176:177]
	v_add_co_u32_e32 v60, vcc, 0x8000, v64
	global_load_dwordx4 v[56:59], v[64:65], off
	s_nop 0
	v_addc_co_u32_e32 v61, vcc, 0, v65, vcc
	v_add_co_u32_e32 v66, vcc, 0x10000, v64
	global_load_dwordx4 v[60:63], v[60:61], off
	s_nop 0
	v_addc_co_u32_e32 v67, vcc, 0, v65, vcc
	v_add_co_u32_e32 v68, vcc, 0x18000, v64
	s_nop 1
	v_addc_co_u32_e32 v69, vcc, 0, v65, vcc
	global_load_dwordx4 v[64:67], v[66:67], off
	s_and_b64 vcc, exec, s[6:7]
	global_load_dwordx4 v[68:71], v[68:69], off
	s_cbranch_vccnz .LBB0_2072
	s_waitcnt vmcnt(8)
	v_add_u32_e32 v128, m0, v200
	v_and_b32_e32 v128, 0xffffefff, v128
	ds_read_b128 v[148:151], v128 offset:4096
	ds_read_b128 v[140:143], v128 offset:5120
	ds_read_b128 v[132:135], v128 offset:6144
	ds_read_b128 v[128:131], v128 offset:7168
	s_waitcnt lgkmcnt(0)
	v_mov_b32_e32 v108, s69
	ds_read_b128 v[104:107], v108 offset:1408
	ds_read_b128 v[108:111], v108 offset:384
	s_mov_b64 s[62:63], s[40:41]
	s_mov_b64 s[64:65], 0
	s_waitcnt lgkmcnt(1)
	v_sub_f32_e32 v104, v104, v193
	v_sub_f32_e32 v105, v105, v193
	v_exp_f32_e32 v104, v104
	v_exp_f32_e32 v105, v105
	v_sub_f32_e32 v106, v106, v193
	v_exp_f32_e32 v196, v106
	v_mul_f32_e32 v104, v182, v104
	v_mul_f32_e32 v106, v182, v105
	s_waitcnt vmcnt(8)
	v_pk_fma_f32 v[194:195], v[162:163], v[104:105], v[122:123] op_sel_hi:[1,0,1]
	v_pk_fma_f32 v[104:105], v[160:161], v[104:105], v[120:121] op_sel_hi:[1,0,1]
	v_pk_fma_f32 v[194:195], v[154:155], v[106:107], v[194:195] op_sel_hi:[1,0,1]
	v_pk_fma_f32 v[104:105], v[152:153], v[106:107], v[104:105] op_sel_hi:[1,0,1]
	v_sub_f32_e32 v106, v107, v193
	v_exp_f32_e32 v107, v106
	v_mul_f32_e32 v106, v182, v196
	s_waitcnt lgkmcnt(0)
	v_sub_f32_e32 v108, v108, v192
	v_exp_f32_e32 v108, v108
	s_waitcnt vmcnt(8)
	v_pk_fma_f32 v[194:195], v[142:143], v[106:107], v[194:195] op_sel_hi:[1,0,1]
	v_pk_fma_f32 v[104:105], v[140:141], v[106:107], v[104:105] op_sel_hi:[1,0,1]
	v_mul_f32_e32 v196, v182, v107
	v_sub_f32_e32 v109, v109, v192
	s_waitcnt vmcnt(8)
	v_pk_fma_f32 v[106:107], v[130:131], v[196:197], v[194:195] op_sel_hi:[1,0,1]
	v_pk_fma_f32 v[104:105], v[128:129], v[196:197], v[104:105] op_sel_hi:[1,0,1]
	v_exp_f32_e32 v196, v109
	v_sub_f32_e32 v110, v110, v192
	v_exp_f32_e32 v110, v110
	v_sub_f32_e32 v111, v111, v192
	v_exp_f32_e32 v111, v111
	v_mul_f32_e32 v108, v169, v108
	v_pk_fma_f32 v[194:195], v[166:167], v[108:109], v[126:127] op_sel_hi:[1,0,1]
	v_pk_fma_f32 v[108:109], v[164:165], v[108:109], v[124:125] op_sel_hi:[1,0,1]
	v_mul_f32_e32 v196, v169, v196
	v_pk_fma_f32 v[194:195], v[158:159], v[196:197], v[194:195] op_sel_hi:[1,0,1]
	v_pk_fma_f32 v[108:109], v[156:157], v[196:197], v[108:109] op_sel_hi:[1,0,1]
	v_mul_f32_e32 v110, v169, v110
	v_pk_fma_f32 v[194:195], v[150:151], v[110:111], v[194:195] op_sel_hi:[1,0,1]
	v_pk_fma_f32 v[108:109], v[148:149], v[110:111], v[108:109] op_sel_hi:[1,0,1]
	v_mul_f32_e32 v196, v169, v111
	v_pk_fma_f32 v[110:111], v[134:135], v[196:197], v[194:195] op_sel_hi:[1,0,1]
	v_pk_fma_f32 v[108:109], v[132:133], v[196:197], v[108:109] op_sel_hi:[1,0,1]
; __device__ __forceinline__ float dot4(f32x4 a, f32x4 b) { return (a[0] * b[0] + a[1] * b[1]) + (a[2] * b[2] + a[3] * b[3]); }
; #define dpp_mov(v, ctrl, row_mask) __builtin_bit_cast(float, __builtin_amdgcn_update_dpp(0, __builtin_bit_cast(int, (float)(v)), (ctrl), (row_mask), 0xf, false))
; __device__ __forceinline__ float wave_sum_dpp(float x) {
;     x += dpp_mov(x, 0xB1, 0xf);
;     x += dpp_mov(x, 0x4E, 0xf);
;     x += dpp_mov(x, 0x141, 0xf);
;     x += dpp_mov(x, 0x140, 0xf);
;     x += dpp_mov(x, 0x142, 0xa);
;     x += dpp_mov(x, 0x143, 0xc);
;     return x;
; }
; __device__ __forceinline__ void attn_fused(Frame& F0, int layer) {
;     ...
;             if (ui == 0) {
; #pragma unroll
;                 for (int r = 0; r < 4; ++r) {
;                     const int m = 32 * c + 4 * w + r;
;                     const float d0 = wave_sum_dpp(dot4(sv[2 * r], q0)), d1 = wave_sum_dpp(dot4(sv[2 * r + 1], q1));
;                     if (lane == 63) { sc[m] = d0; sc[256 + m] = d1; }
;                 }
;                 if (c < 7) FA_SLOAD(kp, c + 1); else FA_SLOAD(vp, 0);
.LBB0_2072:
	s_andn2_b64 vcc, exec, s[64:65]
	s_cbranch_vccnz .LBB0_2082
	s_waitcnt vmcnt(8)
	v_add_u32_e32 v128, m0, v200
	v_and_b32_e32 v128, 0xffffefff, v128
	ds_read_b128 v[148:151], v128 offset:4096
	ds_read_b128 v[140:143], v128 offset:5120
	ds_read_b128 v[132:135], v128 offset:6144
	ds_read_b128 v[128:131], v128 offset:7168
	s_waitcnt lgkmcnt(0)
	s_waitcnt vmcnt(11)
	v_mul_f32_e32 v104, v1, v165
	v_mul_f32_e32 v105, v3, v167
	s_waitcnt vmcnt(8)
	v_mul_f32_e32 v106, v5, v161
	v_mul_f32_e32 v107, v7, v163
	v_fmac_f32_e32 v104, v0, v164
	v_fmac_f32_e32 v105, v2, v166
	v_fmac_f32_e32 v106, v4, v160
	v_fmac_f32_e32 v107, v6, v162
	v_add_f32_e32 v104, v104, v105
	v_add_f32_e32 v106, v106, v107
	v_mov_b32_e32 v105, v201
	v_add_f32_dpp v104, v104, v104 quad_perm:[1,0,3,2] row_mask:0xf bank_mask:0xf bound_ctrl:1
	v_add_f32_dpp v106, v106, v106 quad_perm:[1,0,3,2] row_mask:0xf bank_mask:0xf bound_ctrl:1
	v_mov_b32_e32 v107, v201
	v_add_f32_dpp v104, v104, v104 quad_perm:[2,3,0,1] row_mask:0xf bank_mask:0xf bound_ctrl:1
	v_add_f32_dpp v106, v106, v106 quad_perm:[2,3,0,1] row_mask:0xf bank_mask:0xf bound_ctrl:1
	s_nop 0
	v_add_f32_dpp v104, v104, v104 row_half_mirror row_mask:0xf bank_mask:0xf bound_ctrl:1
	v_add_f32_dpp v106, v106, v106 row_half_mirror row_mask:0xf bank_mask:0xf bound_ctrl:1
	s_nop 0
	v_add_f32_dpp v104, v104, v104 row_mirror row_mask:0xf bank_mask:0xf bound_ctrl:1
	v_add_f32_dpp v106, v106, v106 row_mirror row_mask:0xf bank_mask:0xf bound_ctrl:1
	s_nop 0
	v_mov_b32_dpp v105, v104 row_bcast:15 row_mask:0xa bank_mask:0xf
	v_mov_b32_dpp v107, v106 row_bcast:15 row_mask:0xa bank_mask:0xf
	v_add_f32_e32 v104, v104, v105
	v_mov_b32_e32 v105, v201
	v_add_f32_e32 v106, v106, v107
	v_mov_b32_e32 v107, v201
	v_mov_b32_dpp v105, v104 row_bcast:31 row_mask:0xc bank_mask:0xf
	s_nop 0
	v_mov_b32_dpp v107, v106 row_bcast:31 row_mask:0xc bank_mask:0xf
	s_and_saveexec_b64 s[62:63], s[4:5]
	v_add_f32_e32 v104, v104, v105
	v_add_f32_e32 v105, v106, v107
	v_mov_b32_e32 v106, s69
	v_add_u32_e32 v106, 0x80, v106
	ds_write2st64_b32 v106, v104, v105 offset0:1 offset1:5
	s_or_b64 exec, exec, s[62:63]
	v_mul_f32_e32 v104, v1, v157
	v_mul_f32_e32 v105, v3, v159
	v_mul_f32_e32 v106, v5, v153
	v_mul_f32_e32 v107, v7, v155
	v_fmac_f32_e32 v104, v0, v156
	v_fmac_f32_e32 v105, v2, v158
	v_fmac_f32_e32 v106, v4, v152
	v_fmac_f32_e32 v107, v6, v154
	v_add_f32_e32 v104, v104, v105
	v_add_f32_e32 v106, v106, v107
	v_mov_b32_e32 v105, v201
	v_add_f32_dpp v104, v104, v104 quad_perm:[1,0,3,2] row_mask:0xf bank_mask:0xf bound_ctrl:1
	v_add_f32_dpp v106, v106, v106 quad_perm:[1,0,3,2] row_mask:0xf bank_mask:0xf bound_ctrl:1
	v_mov_b32_e32 v107, v201
	v_add_f32_dpp v104, v104, v104 quad_perm:[2,3,0,1] row_mask:0xf bank_mask:0xf bound_ctrl:1
	v_add_f32_dpp v106, v106, v106 quad_perm:[2,3,0,1] row_mask:0xf bank_mask:0xf bound_ctrl:1
	s_nop 0
	v_add_f32_dpp v104, v104, v104 row_half_mirror row_mask:0xf bank_mask:0xf bound_ctrl:1
	v_add_f32_dpp v106, v106, v106 row_half_mirror row_mask:0xf bank_mask:0xf bound_ctrl:1
	s_nop 0
	v_add_f32_dpp v104, v104, v104 row_mirror row_mask:0xf bank_mask:0xf bound_ctrl:1
	v_add_f32_dpp v106, v106, v106 row_mirror row_mask:0xf bank_mask:0xf bound_ctrl:1
	s_nop 0
	v_mov_b32_dpp v105, v104 row_bcast:15 row_mask:0xa bank_mask:0xf
	v_mov_b32_dpp v107, v106 row_bcast:15 row_mask:0xa bank_mask:0xf
	v_add_f32_e32 v104, v104, v105
	v_mov_b32_e32 v105, v201
	v_add_f32_e32 v106, v106, v107
	v_mov_b32_e32 v107, v201
	v_mov_b32_dpp v105, v104 row_bcast:31 row_mask:0xc bank_mask:0xf
	s_nop 0
	v_mov_b32_dpp v107, v106 row_bcast:31 row_mask:0xc bank_mask:0xf
	s_and_saveexec_b64 s[62:63], s[4:5]
	v_add_f32_e32 v104, v104, v105
	v_add_f32_e32 v105, v106, v107
	v_mov_b32_e32 v106, s69
	v_add_u32_e32 v106, 0x84, v106
	ds_write2st64_b32 v106, v104, v105 offset0:1 offset1:5
	s_or_b64 exec, exec, s[62:63]
	s_waitcnt vmcnt(8)
	v_mul_f32_e32 v104, v1, v149
	v_mul_f32_e32 v105, v3, v151
	s_waitcnt vmcnt(8)
	v_mul_f32_e32 v106, v5, v141
	v_mul_f32_e32 v107, v7, v143
	v_fmac_f32_e32 v104, v0, v148
	v_fmac_f32_e32 v105, v2, v150
	v_fmac_f32_e32 v106, v4, v140
	v_fmac_f32_e32 v107, v6, v142
	v_add_f32_e32 v104, v104, v105
	v_add_f32_e32 v106, v106, v107
	v_mov_b32_e32 v105, v201
	v_add_f32_dpp v104, v104, v104 quad_perm:[1,0,3,2] row_mask:0xf bank_mask:0xf bound_ctrl:1
	v_add_f32_dpp v106, v106, v106 quad_perm:[1,0,3,2] row_mask:0xf bank_mask:0xf bound_ctrl:1
	v_mov_b32_e32 v107, v201
	v_add_f32_dpp v104, v104, v104 quad_perm:[2,3,0,1] row_mask:0xf bank_mask:0xf bound_ctrl:1
	v_add_f32_dpp v106, v106, v106 quad_perm:[2,3,0,1] row_mask:0xf bank_mask:0xf bound_ctrl:1
	s_nop 0
	v_add_f32_dpp v104, v104, v104 row_half_mirror row_mask:0xf bank_mask:0xf bound_ctrl:1
	v_add_f32_dpp v106, v106, v106 row_half_mirror row_mask:0xf bank_mask:0xf bound_ctrl:1
	s_nop 0
	v_add_f32_dpp v104, v104, v104 row_mirror row_mask:0xf bank_mask:0xf bound_ctrl:1
	v_add_f32_dpp v106, v106, v106 row_mirror row_mask:0xf bank_mask:0xf bound_ctrl:1
	s_nop 0
	v_mov_b32_dpp v105, v104 row_bcast:15 row_mask:0xa bank_mask:0xf
	v_mov_b32_dpp v107, v106 row_bcast:15 row_mask:0xa bank_mask:0xf
	v_add_f32_e32 v104, v104, v105
	v_mov_b32_e32 v105, v201
	v_add_f32_e32 v106, v106, v107
	v_mov_b32_e32 v107, v201
	v_mov_b32_dpp v105, v104 row_bcast:31 row_mask:0xc bank_mask:0xf
	s_nop 0
	v_mov_b32_dpp v107, v106 row_bcast:31 row_mask:0xc bank_mask:0xf
	s_and_saveexec_b64 s[62:63], s[4:5]
	v_add_f32_e32 v104, v104, v105
	v_add_f32_e32 v105, v106, v107
	v_mov_b32_e32 v106, s69
	v_add_u32_e32 v106, 0x88, v106
	ds_write2st64_b32 v106, v104, v105 offset0:1 offset1:5
	s_or_b64 exec, exec, s[62:63]
	s_waitcnt vmcnt(8)
; #define LAS __attribute__((address_space(3)))
; #define MFMA16(a, b, c) __builtin_amdgcn_mfma_f32_16x16x32_bf16((a), (b), (c), 0, 0, 0)
; __device__ __forceinline__ void attn_fused(Frame& F0, int layer) {
;     ...
;                 if (c < 7) FA_SLOAD(kp, c + 1); else FA_SLOAD(vp, 0);
;             } else {
; #pragma unroll
;                 for (int r = 0; r < 4; ++r) {
;                     const int m = 32 * c + 4 * w + r;
;                     const float p0 = __builtin_amdgcn_exp2f(sc[m] - mx0) * iv0, p1 = __builtin_amdgcn_exp2f(sc[256 + m] - mx1) * iv1;
;                     a0 += sv[2 * r] * p0; a1 += sv[2 * r + 1] * p1;
;                 }
;                 if (c < 7) FA_SLOAD(vp, c + 1);
;             }
;             LAS unsigned char* slot = lds + (c & 1) * ATT_SLOT;
;             if (c < 4) {
;                 {
;                     bf16x8 Kf[2][4];
;                     __builtin_amdgcn_s_setprio(1);
; #pragma unroll
;                     for (int ml = 0; ml < 4; ++ml) Kf[0][ml] = *(LAS bf16x8*)(slot + (16 * ml + fr) * 544 + (8 * fq) * 2);
;                     __builtin_amdgcn_sched_group_barrier(0x100, 4, 0);
; #pragma unroll
;                     for (int ks = 0; ks < 8; ++ks) {
;                         if (ks < 7) {
; #pragma unroll
;                             for (int ml = 0; ml < 4; ++ml) Kf[(ks + 1) & 1][ml] = *(LAS bf16x8*)(slot + (16 * ml + fr) * 544 + (32 * (ks + 1) + 8 * fq) * 2);
;                         }
; #pragma unroll
;                         for (int ml = 0; ml < 4; ++ml) S[4 * c + ml] = MFMA16(Kf[ks & 1][ml], Qf[ks], ks == 0 ? zero4 : S[4 * c + ml]);
;                         __builtin_amdgcn_sched_group_barrier(0x100, 4, 0); __builtin_amdgcn_sched_group_barrier(0x008, 4, 0);
	v_mul_f32_e32 v104, v1, v133
	v_mul_f32_e32 v105, v3, v135
	s_waitcnt vmcnt(8)
	v_mul_f32_e32 v106, v5, v129
	v_mul_f32_e32 v107, v7, v131
	v_fmac_f32_e32 v104, v0, v132
	v_fmac_f32_e32 v105, v2, v134
	v_fmac_f32_e32 v106, v4, v128
	v_fmac_f32_e32 v107, v6, v130
	v_add_f32_e32 v104, v104, v105
	v_add_f32_e32 v106, v106, v107
	v_mov_b32_e32 v105, v201
	v_add_f32_dpp v104, v104, v104 quad_perm:[1,0,3,2] row_mask:0xf bank_mask:0xf bound_ctrl:1
	v_add_f32_dpp v106, v106, v106 quad_perm:[1,0,3,2] row_mask:0xf bank_mask:0xf bound_ctrl:1
	v_mov_b32_e32 v107, v201
	v_add_f32_dpp v104, v104, v104 quad_perm:[2,3,0,1] row_mask:0xf bank_mask:0xf bound_ctrl:1
	v_add_f32_dpp v106, v106, v106 quad_perm:[2,3,0,1] row_mask:0xf bank_mask:0xf bound_ctrl:1
	s_nop 0
	v_add_f32_dpp v104, v104, v104 row_half_mirror row_mask:0xf bank_mask:0xf bound_ctrl:1
	v_add_f32_dpp v106, v106, v106 row_half_mirror row_mask:0xf bank_mask:0xf bound_ctrl:1
	s_nop 0
	v_add_f32_dpp v104, v104, v104 row_mirror row_mask:0xf bank_mask:0xf bound_ctrl:1
	v_add_f32_dpp v106, v106, v106 row_mirror row_mask:0xf bank_mask:0xf bound_ctrl:1
	s_nop 0
	v_mov_b32_dpp v105, v104 row_bcast:15 row_mask:0xa bank_mask:0xf
	v_mov_b32_dpp v107, v106 row_bcast:15 row_mask:0xa bank_mask:0xf
	v_add_f32_e32 v104, v104, v105
	v_mov_b32_e32 v105, v201
	v_add_f32_e32 v106, v106, v107
	v_mov_b32_e32 v107, v201
	v_mov_b32_dpp v105, v104 row_bcast:31 row_mask:0xc bank_mask:0xf
	s_nop 0
	v_mov_b32_dpp v107, v106 row_bcast:31 row_mask:0xc bank_mask:0xf
	s_and_saveexec_b64 s[62:63], s[4:5]
	v_add_f32_e32 v104, v104, v105
	v_add_f32_e32 v105, v106, v107
	v_mov_b32_e32 v106, s69
	v_add_u32_e32 v106, 0x8c, v106
	ds_write2st64_b32 v106, v104, v105 offset0:1 offset1:5
	s_or_b64 exec, exec, s[62:63]
	v_mov_b64_e32 v[108:109], v[124:125]
	v_mov_b64_e32 v[104:105], v[120:121]
	s_mov_b64 s[62:63], s[42:43]
	v_mov_b64_e32 v[110:111], v[126:127]
	v_mov_b64_e32 v[106:107], v[122:123]
.LBB0_2082:
	s_nop 0
	s_add_u32 s100, s62, 0x20000
	s_addc_u32 s101, s63, 0
	v_lshl_add_u64 v[120:121], s[62:63], 0, v[200:201]
	v_add_co_u32_e32 v122, vcc, 0x1000, v120
	global_load_dwordx4 v[156:159], v[120:121], off nt
	s_nop 0
	v_addc_co_u32_e32 v123, vcc, 0, v121, vcc
	global_load_dwordx4 v[148:151], v[122:123], off nt
	global_load_dwordx4 v[140:143], v[122:123], off offset:1024 nt
	v_add_co_u32_e32 v122, vcc, 0x2000, v120
	global_load_dwordx4 v[152:155], v[120:121], off offset:1024 nt
	s_nop 0
	v_addc_co_u32_e32 v123, vcc, 0, v121, vcc
	v_add_co_u32_e32 v120, vcc, 0x3000, v120
	s_nop 0
	v_addc_co_u32_e32 v121, vcc, 0, v121, vcc
	s_nop 0
	s_bitset1_b32 m0, 12
	v_add_u32_e32 v122, 0x2000, v200
	v_add_u32_e32 v123, 0x2800, v200
	global_load_lds_dwordx4 v122, s[100:101] nt
	global_load_lds_dwordx4 v122, s[100:101] offset:1024 nt
	global_load_lds_dwordx4 v123, s[100:101] offset:2048 nt
	global_load_lds_dwordx4 v123, s[100:101] offset:3072 nt
	s_setprio 1
	s_waitcnt vmcnt(16)
	ds_read_b128 v[160:163], v189 offset:34816
	ds_read_b128 v[164:167], v189 offset:43520
	ds_read_b128 v[194:197], v189 offset:52224
	ds_read_b128 v[202:205], v189 offset:60928
	ds_read_b128 v[206:209], v189 offset:34880
	ds_read_b128 v[212:215], v189 offset:43584
	ds_read_b128 v[216:219], v189 offset:52288
	ds_read_b128 v[220:223], v189 offset:60992
	s_waitcnt lgkmcnt(7)
	v_mfma_f32_16x16x32_bf16 v[160:163], v[160:163], v[36:39], 0
	s_waitcnt lgkmcnt(6)
	v_mfma_f32_16x16x32_bf16 v[164:167], v[164:167], v[36:39], 0
	s_waitcnt lgkmcnt(5)
	v_mfma_f32_16x16x32_bf16 v[194:197], v[194:197], v[36:39], 0
	s_waitcnt lgkmcnt(4)
	v_mfma_f32_16x16x32_bf16 v[36:39], v[202:205], v[36:39], 0
	ds_read_b128 v[202:205], v189 offset:34944
	ds_read_b128 v[224:227], v189 offset:43648
	ds_read_b128 v[228:231], v189 offset:52352
	ds_read_b128 v[232:235], v189 offset:61056
	s_waitcnt lgkmcnt(7)
	v_mfma_f32_16x16x32_bf16 v[160:163], v[206:209], v[32:35], v[160:163]
	s_waitcnt lgkmcnt(6)
	v_mfma_f32_16x16x32_bf16 v[164:167], v[212:215], v[32:35], v[164:167]
	s_waitcnt lgkmcnt(5)
	v_mfma_f32_16x16x32_bf16 v[194:197], v[216:219], v[32:35], v[194:197]
	s_waitcnt lgkmcnt(4)
	v_mfma_f32_16x16x32_bf16 v[32:35], v[220:223], v[32:35], v[36:39]
	ds_read_b128 v[206:209], v189 offset:43712
	ds_read_b128 v[212:215], v189 offset:52416
	ds_read_b128 v[216:219], v189 offset:61120
	ds_read_b128 v[36:39], v189 offset:35008
	s_waitcnt lgkmcnt(7)
	v_mfma_f32_16x16x32_bf16 v[160:163], v[202:205], v[28:31], v[160:163]
	s_waitcnt lgkmcnt(6)
	v_mfma_f32_16x16x32_bf16 v[164:167], v[224:227], v[28:31], v[164:167]
	s_waitcnt lgkmcnt(5)
	v_mfma_f32_16x16x32_bf16 v[194:197], v[228:231], v[28:31], v[194:197]
	s_waitcnt lgkmcnt(4)
	v_mfma_f32_16x16x32_bf16 v[28:31], v[232:235], v[28:31], v[32:35]
	ds_read_b128 v[202:205], v189 offset:43776
	ds_read_b128 v[220:223], v189 offset:52480
	ds_read_b128 v[224:227], v189 offset:61184
	ds_read_b128 v[32:35], v189 offset:35072
	s_waitcnt lgkmcnt(4)
	v_mfma_f32_16x16x32_bf16 v[36:39], v[36:39], v[24:27], v[160:163]
	v_mfma_f32_16x16x32_bf16 v[160:163], v[206:209], v[24:27], v[164:167]
	v_mfma_f32_16x16x32_bf16 v[164:167], v[212:215], v[24:27], v[194:197]
	v_mfma_f32_16x16x32_bf16 v[24:27], v[216:219], v[24:27], v[28:31]
	s_nop 1
	ds_read_b128 v[194:197], v189 offset:43840
	ds_read_b128 v[206:209], v189 offset:52544
	ds_read_b128 v[212:215], v189 offset:61248
	ds_read_b128 v[28:31], v189 offset:35136
	s_waitcnt lgkmcnt(4)
	v_mfma_f32_16x16x32_bf16 v[32:35], v[32:35], v[20:23], v[36:39]
	v_mfma_f32_16x16x32_bf16 v[36:39], v[202:205], v[20:23], v[160:163]
	v_mfma_f32_16x16x32_bf16 v[160:163], v[220:223], v[20:23], v[164:167]
	v_mfma_f32_16x16x32_bf16 v[20:23], v[224:227], v[20:23], v[24:27]
	s_nop 1
	ds_read_b128 v[164:167], v189 offset:43904
	ds_read_b128 v[202:205], v189 offset:52608
	ds_read_b128 v[216:219], v189 offset:61312
	ds_read_b128 v[24:27], v189 offset:35200
	s_waitcnt lgkmcnt(4)
; #define LDS_BARRIER() asm volatile("s_waitcnt lgkmcnt(0)\n\ts_barrier" ::: "memory")
; __device__ __forceinline__ float shx(float v, int mask, int lane) { return __builtin_bit_cast(float, __builtin_amdgcn_ds_bpermute((lane ^ mask) << 2, __builtin_bit_cast(int, v))); }
; #define MFMA16(a, b, c) __builtin_amdgcn_mfma_f32_16x16x32_bf16((a), (b), (c), 0, 0, 0)
; #define ATT_LSTORE(slot) do { _Pragma("unroll") for (int i_ = 0; i_ < 4; ++i_) { const int idx_ = tid + 512 * i_; *(LAS u32x4*)(lds + (slot) * ATT_SLOT + (idx_ >> 5) * 544 + (idx_ & 31) * 16) = st[i_]; } } while (0)
; #define ATT_LSTORE(c) do { _Pragma("unroll") for (int i_ = 0; i_ < 4; ++i_) *(LAS u32x4*)(lds + ((c) & 1) * ATT_SLOT + 16 * i_ * 544 + loff) = st[(c) & 1][i_]; } while (0)
; __device__ __forceinline__ void attn_fused(Frame& F0, int layer) {
;     ...
;                         for (int ml = 0; ml < 4; ++ml) S[4 * c + ml] = MFMA16(Kf[ks & 1][ml], Qf[ks], ks == 0 ? zero4 : S[4 * c + ml]);
;                         __builtin_amdgcn_sched_group_barrier(0x100, 4, 0); __builtin_amdgcn_sched_group_barrier(0x008, 4, 0);
;                     }
;                     __builtin_amdgcn_s_setprio(0);
;                 }
;                 if (c == 3) {
;                     float mx = S[0][0];
; #pragma unroll
;                     for (int i = 0; i < 16; ++i) { mx = fmaxf(mx, fmaxf(fmaxf(S[i][0], S[i][1]), fmaxf(S[i][2], S[i][3]))); }
;                     mx = fmaxf(mx, shx(mx, 16, lane)); mx = fmaxf(mx, shx(mx, 32, lane));
;                     float sum = 0.f;
; #pragma unroll
;                     for (int i = 0; i < 16; ++i) {
; #pragma unroll
;                         for (int e = 0; e < 4; ++e) { S[i][e] = __builtin_amdgcn_exp2f(S[i][e] - mx); sum += S[i][e]; }
;                     }
;                     sum += shx(sum, 16, lane); sum += shx(sum, 32, lane);
;                     inv = 1.0f / sum;
;     ...
;             if (c < 7) ATT_LSTORE(c + 1);
;             LDS_BARRIER();
	v_mfma_f32_16x16x32_bf16 v[28:31], v[28:31], v[16:19], v[32:35]
	v_mfma_f32_16x16x32_bf16 v[32:35], v[194:197], v[16:19], v[36:39]
	v_mfma_f32_16x16x32_bf16 v[36:39], v[206:209], v[16:19], v[160:163]
	v_mfma_f32_16x16x32_bf16 v[16:19], v[212:215], v[16:19], v[20:23]
	s_nop 1
	ds_read_b128 v[160:163], v189 offset:43968
	ds_read_b128 v[194:197], v189 offset:52672
	ds_read_b128 v[206:209], v189 offset:61376
	ds_read_b128 v[20:23], v189 offset:35264
	s_waitcnt lgkmcnt(4)
	v_mfma_f32_16x16x32_bf16 v[24:27], v[24:27], v[12:15], v[28:31]
	v_mfma_f32_16x16x32_bf16 v[28:31], v[164:167], v[12:15], v[32:35]
	v_mfma_f32_16x16x32_bf16 v[164:167], v[202:205], v[12:15], v[36:39]
	v_mfma_f32_16x16x32_bf16 v[12:15], v[216:219], v[12:15], v[16:19]
	s_waitcnt lgkmcnt(0)
	v_mfma_f32_16x16x32_bf16 v[36:39], v[20:23], v[8:11], v[24:27]
	v_mfma_f32_16x16x32_bf16 v[32:35], v[160:163], v[8:11], v[28:31]
	v_mfma_f32_16x16x32_bf16 v[24:27], v[194:197], v[8:11], v[164:167]
	v_mfma_f32_16x16x32_bf16 v[28:31], v[206:209], v[8:11], v[12:15]
	s_setprio 0
	v_max_f32_e32 v8, v55, v55
	v_max_f32_e32 v9, v54, v54
	v_max_f32_e32 v8, v9, v8
	v_max_f32_e32 v9, v51, v51
	v_max_f32_e32 v10, v50, v50
	v_max_f32_e32 v9, v10, v9
	v_max3_f32 v8, v52, v53, v8
	v_max3_f32 v9, v48, v49, v9
	v_max3_f32 v8, v52, v8, v9
	v_max_f32_e32 v9, v43, v43
	v_max_f32_e32 v10, v42, v42
	v_max_f32_e32 v9, v10, v9
	v_max_f32_e32 v10, v47, v47
	v_max_f32_e32 v11, v46, v46
	v_max_f32_e32 v10, v11, v10
	v_max3_f32 v9, v40, v41, v9
	v_max3_f32 v10, v44, v45, v10
	v_max3_f32 v8, v8, v9, v10
	v_max_f32_e32 v9, v103, v103
	v_max_f32_e32 v10, v102, v102
	v_max_f32_e32 v9, v10, v9
	v_max_f32_e32 v10, v99, v99
	v_max_f32_e32 v11, v98, v98
	v_max_f32_e32 v10, v11, v10
	v_max3_f32 v9, v100, v101, v9
	v_max3_f32 v10, v96, v97, v10
	v_max3_f32 v8, v8, v9, v10
	v_max_f32_e32 v9, v91, v91
	v_max_f32_e32 v10, v90, v90
	v_max_f32_e32 v9, v10, v9
	v_max_f32_e32 v10, v95, v95
	v_max_f32_e32 v11, v94, v94
	v_max_f32_e32 v10, v11, v10
	v_max3_f32 v9, v88, v89, v9
	v_max3_f32 v10, v92, v93, v10
	v_max3_f32 v8, v8, v9, v10
	v_max_f32_e32 v9, v147, v147
	v_max_f32_e32 v10, v146, v146
	v_max_f32_e32 v9, v10, v9
	v_max_f32_e32 v10, v139, v139
	v_max_f32_e32 v11, v138, v138
	v_max_f32_e32 v10, v11, v10
	v_max3_f32 v9, v144, v145, v9
	v_max3_f32 v10, v136, v137, v10
	v_max3_f32 v8, v8, v9, v10
	v_max_f32_e32 v9, v115, v115
	v_max_f32_e32 v10, v114, v114
	v_max_f32_e32 v9, v10, v9
	v_max_f32_e32 v10, v119, v119
	v_max_f32_e32 v11, v118, v118
	v_max_f32_e32 v10, v11, v10
	v_max3_f32 v9, v112, v113, v9
	v_max3_f32 v10, v116, v117, v10
	v_max3_f32 v8, v8, v9, v10
	v_max_f32_e32 v9, v39, v39
	v_max_f32_e32 v10, v38, v38
	v_max_f32_e32 v9, v10, v9
	v_max_f32_e32 v10, v35, v35
	v_max_f32_e32 v11, v34, v34
	v_max_f32_e32 v10, v11, v10
	v_max3_f32 v9, v36, v37, v9
	v_max3_f32 v10, v32, v33, v10
	v_max3_f32 v8, v8, v9, v10
	v_max_f32_e32 v9, v27, v27
	v_max_f32_e32 v10, v26, v26
	v_max_f32_e32 v9, v10, v9
	v_max_f32_e32 v10, v31, v31
	v_max_f32_e32 v11, v30, v30
	v_max_f32_e32 v10, v11, v10
	v_max3_f32 v9, v24, v25, v9
	v_max3_f32 v10, v28, v29, v10
	v_max3_f32 v8, v8, v9, v10
	ds_bpermute_b32 v9, v187, v8
	ds_write_b128 v191, v[72:75]
	ds_write_b128 v191, v[76:79] offset:8704
	ds_write_b128 v191, v[80:83] offset:17408
	ds_write_b128 v191, v[84:87] offset:26112
	s_waitcnt lgkmcnt(4)
	v_max_f32_e32 v9, v9, v9
	v_max_f32_e32 v8, v8, v9
	ds_bpermute_b32 v9, v188, v8
	s_mov_b64 s[62:63], s[44:45]
	s_waitcnt lgkmcnt(0)
	s_barrier
	s_mov_b64 s[64:65], -1
	s_waitcnt lgkmcnt(0)
	v_max_f32_e32 v9, v9, v9
	v_max_f32_e32 v164, v8, v9
	v_sub_f32_e32 v8, v52, v164
	v_exp_f32_e32 v203, v8
	v_sub_f32_e32 v8, v53, v164
	v_exp_f32_e32 v204, v8
	v_sub_f32_e32 v8, v54, v164
	v_exp_f32_e32 v205, v8
	v_sub_f32_e32 v8, v55, v164
	v_exp_f32_e32 v231, v8
	v_sub_f32_e32 v9, v48, v164
	v_add_f32_e32 v8, 0, v203
	v_exp_f32_e32 v160, v9
	v_sub_f32_e32 v9, v49, v164
	v_add_f32_e32 v8, v204, v8
	v_exp_f32_e32 v161, v9
	v_sub_f32_e32 v9, v50, v164
	v_add_f32_e32 v8, v205, v8
	v_exp_f32_e32 v162, v9
	v_sub_f32_e32 v9, v51, v164
	v_add_f32_e32 v8, v231, v8
	v_exp_f32_e32 v163, v9
	v_sub_f32_e32 v9, v40, v164
	v_add_f32_e32 v8, v160, v8
	v_exp_f32_e32 v52, v9
	v_sub_f32_e32 v9, v41, v164
	v_add_f32_e32 v8, v161, v8
	v_exp_f32_e32 v53, v9
	v_sub_f32_e32 v9, v42, v164
	v_add_f32_e32 v8, v162, v8
	v_exp_f32_e32 v54, v9
	v_sub_f32_e32 v9, v43, v164
	v_add_f32_e32 v8, v163, v8
	v_exp_f32_e32 v55, v9
	v_sub_f32_e32 v9, v44, v164
	v_add_f32_e32 v8, v52, v8
	v_exp_f32_e32 v44, v9
	v_sub_f32_e32 v9, v45, v164
	v_add_f32_e32 v8, v53, v8
	v_exp_f32_e32 v45, v9
	v_sub_f32_e32 v9, v46, v164
	v_add_f32_e32 v8, v54, v8
	v_exp_f32_e32 v46, v9
	v_sub_f32_e32 v9, v47, v164
	v_add_f32_e32 v8, v55, v8
	v_exp_f32_e32 v47, v9
	v_sub_f32_e32 v9, v100, v164
	v_add_f32_e32 v8, v44, v8
	v_exp_f32_e32 v229, v9
	v_sub_f32_e32 v9, v101, v164
	v_add_f32_e32 v8, v45, v8
	v_exp_f32_e32 v233, v9
	v_sub_f32_e32 v9, v102, v164
	v_add_f32_e32 v8, v46, v8
	v_exp_f32_e32 v234, v9
	v_sub_f32_e32 v9, v103, v164
	v_add_f32_e32 v8, v47, v8
	v_exp_f32_e32 v202, v9
	v_sub_f32_e32 v9, v96, v164
	v_add_f32_e32 v8, v229, v8
	v_exp_f32_e32 v250, v9
	v_sub_f32_e32 v9, v97, v164
	v_add_f32_e32 v8, v233, v8
	v_exp_f32_e32 v251, v9
	v_sub_f32_e32 v9, v98, v164
	v_add_f32_e32 v8, v234, v8
	v_exp_f32_e32 v252, v9
	v_sub_f32_e32 v9, v99, v164
	v_add_f32_e32 v8, v202, v8
	v_exp_f32_e32 v253, v9
	v_sub_f32_e32 v9, v88, v164
	v_add_f32_e32 v8, v250, v8
	v_exp_f32_e32 v242, v9
	v_sub_f32_e32 v9, v89, v164
	v_add_f32_e32 v8, v251, v8
	v_exp_f32_e32 v243, v9
	v_sub_f32_e32 v9, v90, v164
	v_add_f32_e32 v8, v252, v8
; __device__ __forceinline__ float shx(float v, int mask, int lane) { return __builtin_bit_cast(float, __builtin_amdgcn_ds_bpermute((lane ^ mask) << 2, __builtin_bit_cast(int, v))); }
; __device__ __forceinline__ void attn_fused(Frame& F0, int layer) {
;     ...
; #pragma unroll
;                 for (int r = 0; r < 4; ++r) {
;                     const int m = 32 * c + 4 * w + r;
;                     const float p0 = __builtin_amdgcn_exp2f(sc[m] - mx0) * iv0, p1 = __builtin_amdgcn_exp2f(sc[256 + m] - mx1) * iv1;
;                     a0 += sv[2 * r] * p0; a1 += sv[2 * r + 1] * p1;
;                 }
;                 if (c < 7) FA_SLOAD(vp, c + 1);
;     ...
;                 if (c == 3) {
;                     float mx = S[0][0];
; #pragma unroll
;                     for (int i = 0; i < 16; ++i) { mx = fmaxf(mx, fmaxf(fmaxf(S[i][0], S[i][1]), fmaxf(S[i][2], S[i][3]))); }
;                     mx = fmaxf(mx, shx(mx, 16, lane)); mx = fmaxf(mx, shx(mx, 32, lane));
;                     float sum = 0.f;
; #pragma unroll
;                     for (int i = 0; i < 16; ++i) {
; #pragma unroll
;                         for (int e = 0; e < 4; ++e) { S[i][e] = __builtin_amdgcn_exp2f(S[i][e] - mx); sum += S[i][e]; }
;                     }
;                     sum += shx(sum, 16, lane); sum += shx(sum, 32, lane);
;                     inv = 1.0f / sum;
	v_exp_f32_e32 v244, v9
	v_sub_f32_e32 v9, v91, v164
	v_add_f32_e32 v8, v253, v8
	v_exp_f32_e32 v245, v9
	v_sub_f32_e32 v9, v92, v164
	v_add_f32_e32 v8, v242, v8
	v_exp_f32_e32 v246, v9
	v_sub_f32_e32 v9, v93, v164
	v_add_f32_e32 v8, v243, v8
	v_exp_f32_e32 v247, v9
	v_sub_f32_e32 v9, v94, v164
	v_add_f32_e32 v8, v244, v8
	v_exp_f32_e32 v248, v9
	v_sub_f32_e32 v9, v95, v164
	v_add_f32_e32 v8, v245, v8
	v_exp_f32_e32 v249, v9
	v_sub_f32_e32 v9, v144, v164
	v_add_f32_e32 v8, v246, v8
	v_exp_f32_e32 v238, v9
	v_sub_f32_e32 v9, v145, v164
	v_add_f32_e32 v8, v247, v8
	v_exp_f32_e32 v239, v9
	v_sub_f32_e32 v9, v146, v164
	v_add_f32_e32 v8, v248, v8
	v_exp_f32_e32 v240, v9
	v_sub_f32_e32 v9, v147, v164
	v_add_f32_e32 v8, v249, v8
	v_exp_f32_e32 v241, v9
	v_sub_f32_e32 v9, v136, v164
	v_add_f32_e32 v8, v238, v8
	v_exp_f32_e32 v222, v9
	v_sub_f32_e32 v9, v137, v164
	v_add_f32_e32 v8, v239, v8
	v_exp_f32_e32 v223, v9
	v_sub_f32_e32 v9, v138, v164
	v_add_f32_e32 v8, v240, v8
	v_exp_f32_e32 v225, v9
	v_sub_f32_e32 v9, v139, v164
	v_lshl_add_u64 v[16:17], s[62:63], 0, v[176:177]
	v_add_f32_e32 v8, v241, v8
	v_exp_f32_e32 v230, v9
	v_add_co_u32_e32 v12, vcc, 0x8000, v16
	v_add_f32_e32 v8, v222, v8
	s_nop 0
	v_addc_co_u32_e32 v13, vcc, 0, v17, vcc
	v_add_f32_e32 v8, v223, v8
	v_add_co_u32_e32 v18, vcc, 0x10000, v16
	v_add_f32_e32 v8, v225, v8
	s_nop 0
	v_addc_co_u32_e32 v19, vcc, 0, v17, vcc
	v_add_f32_e32 v40, v230, v8
	v_sub_f32_e32 v8, v112, v164
	v_add_co_u32_e32 v20, vcc, 0x18000, v16
	v_exp_f32_e32 v220, v8
	v_sub_f32_e32 v8, v113, v164
	v_addc_co_u32_e32 v21, vcc, 0, v17, vcc
	v_exp_f32_e32 v221, v8
	global_load_dwordx4 v[8:11], v[16:17], off
	v_sub_f32_e32 v41, v114, v164
	global_load_dwordx4 v[12:15], v[12:13], off
	v_exp_f32_e32 v224, v41
	global_load_dwordx4 v[16:19], v[18:19], off
	v_sub_f32_e32 v41, v115, v164
	global_load_dwordx4 v[20:23], v[20:21], off
	v_exp_f32_e32 v226, v41
	v_sub_f32_e32 v41, v116, v164
	v_add_f32_e32 v40, v220, v40
	v_exp_f32_e32 v228, v41
	v_sub_f32_e32 v41, v117, v164
	v_add_f32_e32 v40, v221, v40
	v_exp_f32_e32 v232, v41
	v_sub_f32_e32 v41, v118, v164
	v_add_f32_e32 v40, v224, v40
	v_exp_f32_e32 v236, v41
	v_sub_f32_e32 v41, v119, v164
	v_add_f32_e32 v40, v226, v40
	v_exp_f32_e32 v237, v41
	v_sub_f32_e32 v36, v36, v164
	v_add_f32_e32 v40, v228, v40
	v_exp_f32_e32 v216, v36
	v_sub_f32_e32 v36, v37, v164
	v_add_f32_e32 v40, v232, v40
	v_exp_f32_e32 v217, v36
	v_sub_f32_e32 v36, v38, v164
	v_add_f32_e32 v40, v236, v40
	v_exp_f32_e32 v218, v36
	v_sub_f32_e32 v36, v39, v164
	v_add_f32_e32 v40, v237, v40
	v_exp_f32_e32 v219, v36
	v_sub_f32_e32 v32, v32, v164
	v_add_f32_e32 v36, v216, v40
	v_exp_f32_e32 v212, v32
	v_sub_f32_e32 v32, v33, v164
	v_add_f32_e32 v36, v217, v36
	v_exp_f32_e32 v213, v32
	v_sub_f32_e32 v32, v34, v164
	v_add_f32_e32 v36, v218, v36
	v_exp_f32_e32 v214, v32
	v_sub_f32_e32 v32, v35, v164
	v_add_f32_e32 v36, v219, v36
	v_exp_f32_e32 v215, v32
	v_sub_f32_e32 v24, v24, v164
	v_add_f32_e32 v32, v212, v36
	v_exp_f32_e32 v166, v24
	v_sub_f32_e32 v24, v25, v164
	v_add_f32_e32 v32, v213, v32
	v_exp_f32_e32 v167, v24
	v_sub_f32_e32 v24, v26, v164
	v_add_f32_e32 v32, v214, v32
	v_exp_f32_e32 v194, v24
	v_sub_f32_e32 v24, v27, v164
	v_add_f32_e32 v32, v215, v32
	v_exp_f32_e32 v195, v24
	v_sub_f32_e32 v25, v28, v164
	v_add_f32_e32 v24, v166, v32
	v_exp_f32_e32 v196, v25
	v_sub_f32_e32 v25, v29, v164
	v_add_f32_e32 v24, v167, v24
	v_exp_f32_e32 v197, v25
	v_sub_f32_e32 v25, v30, v164
	v_add_f32_e32 v24, v194, v24
	v_exp_f32_e32 v198, v25
	v_sub_f32_e32 v25, v31, v164
	v_add_f32_e32 v24, v195, v24
	v_exp_f32_e32 v199, v25
	v_add_f32_e32 v24, v196, v24
	v_add_f32_e32 v24, v197, v24
	v_add_f32_e32 v24, v198, v24
	v_add_f32_e32 v24, v199, v24
	ds_bpermute_b32 v25, v187, v24
	s_and_b64 vcc, exec, s[6:7]
	s_waitcnt lgkmcnt(0)
	v_add_f32_e32 v164, v24, v25
	ds_bpermute_b32 v165, v188, v164
	s_cbranch_vccnz .LBB0_2084
	s_waitcnt vmcnt(8)
	v_add_u32_e32 v120, m0, v200
	v_and_b32_e32 v120, 0xffffefff, v120
	ds_read_b128 v[132:135], v120
	ds_read_b128 v[128:131], v120 offset:1024
	ds_read_b128 v[124:127], v120 offset:2048
	ds_read_b128 v[120:123], v120 offset:3072
	s_waitcnt lgkmcnt(0)
	v_mov_b32_e32 v28, s69
	ds_read_b128 v[24:27], v28 offset:1536
	ds_read_b128 v[28:31], v28 offset:512
	s_mov_b64 s[62:63], s[46:47]
	s_mov_b64 s[64:65], 0
	s_waitcnt lgkmcnt(1)
	v_sub_f32_e32 v24, v24, v193
	v_sub_f32_e32 v25, v25, v193
	v_exp_f32_e32 v24, v24
	v_exp_f32_e32 v25, v25
	v_sub_f32_e32 v26, v26, v193
	v_exp_f32_e32 v34, v26
	v_mul_f32_e32 v24, v182, v24
	v_mul_f32_e32 v26, v182, v25
	s_waitcnt vmcnt(8)
	v_pk_fma_f32 v[32:33], v[154:155], v[24:25], v[106:107] op_sel_hi:[1,0,1]
	v_pk_fma_f32 v[24:25], v[152:153], v[24:25], v[104:105] op_sel_hi:[1,0,1]
	v_pk_fma_f32 v[32:33], v[142:143], v[26:27], v[32:33] op_sel_hi:[1,0,1]
	v_pk_fma_f32 v[24:25], v[140:141], v[26:27], v[24:25] op_sel_hi:[1,0,1]
	v_sub_f32_e32 v26, v27, v193
	v_exp_f32_e32 v27, v26
	v_mul_f32_e32 v26, v182, v34
	s_waitcnt vmcnt(8)
	v_pk_fma_f32 v[32:33], v[130:131], v[26:27], v[32:33] op_sel_hi:[1,0,1]
	v_pk_fma_f32 v[24:25], v[128:129], v[26:27], v[24:25] op_sel_hi:[1,0,1]
	v_mul_f32_e32 v26, v182, v27
	s_waitcnt vmcnt(8)
	v_pk_fma_f32 v[42:43], v[122:123], v[26:27], v[32:33] op_sel_hi:[1,0,1]
	s_waitcnt lgkmcnt(0)
	v_sub_f32_e32 v27, v28, v192
	v_exp_f32_e32 v27, v27
	s_nop 0
	v_pk_fma_f32 v[40:41], v[120:121], v[26:27], v[24:25] op_sel_hi:[1,0,1]
	v_sub_f32_e32 v24, v29, v192
	v_exp_f32_e32 v28, v24
	v_mul_f32_e32 v24, v169, v27
	v_pk_fma_f32 v[26:27], v[158:159], v[24:25], v[110:111] op_sel_hi:[1,0,1]
	v_pk_fma_f32 v[24:25], v[156:157], v[24:25], v[108:109] op_sel_hi:[1,0,1]
	v_mul_f32_e32 v28, v169, v28
	v_pk_fma_f32 v[26:27], v[150:151], v[28:29], v[26:27] op_sel_hi:[1,0,1]
	v_sub_f32_e32 v29, v30, v192
	v_exp_f32_e32 v29, v29
	s_nop 0
	v_pk_fma_f32 v[24:25], v[148:149], v[28:29], v[24:25] op_sel_hi:[1,0,1]
	v_sub_f32_e32 v28, v31, v192
	v_exp_f32_e32 v30, v28
	v_mul_f32_e32 v28, v169, v29
	v_pk_fma_f32 v[26:27], v[134:135], v[28:29], v[26:27] op_sel_hi:[1,0,1]
	v_pk_fma_f32 v[24:25], v[132:133], v[28:29], v[24:25] op_sel_hi:[1,0,1]
	v_mul_f32_e32 v28, v169, v30
	v_pk_fma_f32 v[50:51], v[126:127], v[28:29], v[26:27] op_sel_hi:[1,0,1]
	v_pk_fma_f32 v[48:49], v[124:125], v[28:29], v[24:25] op_sel_hi:[1,0,1]
; __device__ __forceinline__ float dot4(f32x4 a, f32x4 b) { return (a[0] * b[0] + a[1] * b[1]) + (a[2] * b[2] + a[3] * b[3]); }
; #define dpp_mov(v, ctrl, row_mask) __builtin_bit_cast(float, __builtin_amdgcn_update_dpp(0, __builtin_bit_cast(int, (float)(v)), (ctrl), (row_mask), 0xf, false))
; __device__ __forceinline__ float wave_sum_dpp(float x) {
;     x += dpp_mov(x, 0xB1, 0xf);
;     x += dpp_mov(x, 0x4E, 0xf);
;     x += dpp_mov(x, 0x141, 0xf);
;     x += dpp_mov(x, 0x140, 0xf);
;     x += dpp_mov(x, 0x142, 0xa);
;     x += dpp_mov(x, 0x143, 0xc);
;     return x;
; }
; __device__ __forceinline__ void attn_fused(Frame& F0, int layer) {
;     ...
;             if (ui == 0) {
; #pragma unroll
;                 for (int r = 0; r < 4; ++r) {
;                     const int m = 32 * c + 4 * w + r;
;                     const float d0 = wave_sum_dpp(dot4(sv[2 * r], q0)), d1 = wave_sum_dpp(dot4(sv[2 * r + 1], q1));
;                     if (lane == 63) { sc[m] = d0; sc[256 + m] = d1; }
;                 }
;                 if (c < 7) FA_SLOAD(kp, c + 1); else FA_SLOAD(vp, 0);
.LBB0_2084:
	s_andn2_b64 vcc, exec, s[64:65]
	s_cbranch_vccnz .LBB0_2094
	s_waitcnt vmcnt(8)
	v_add_u32_e32 v120, m0, v200
	v_and_b32_e32 v120, 0xffffefff, v120
	ds_read_b128 v[132:135], v120
	ds_read_b128 v[128:131], v120 offset:1024
	ds_read_b128 v[124:127], v120 offset:2048
	ds_read_b128 v[120:123], v120 offset:3072
	s_waitcnt lgkmcnt(0)
	s_waitcnt vmcnt(11)
	v_mul_f32_e32 v24, v1, v157
	v_mul_f32_e32 v25, v3, v159
	s_waitcnt vmcnt(8)
	v_mul_f32_e32 v26, v5, v153
	v_mul_f32_e32 v27, v7, v155
	v_fmac_f32_e32 v24, v0, v156
	v_fmac_f32_e32 v25, v2, v158
	v_fmac_f32_e32 v26, v4, v152
	v_fmac_f32_e32 v27, v6, v154
	v_add_f32_e32 v24, v24, v25
	v_add_f32_e32 v26, v26, v27
	v_mov_b32_e32 v25, v201
	v_add_f32_dpp v24, v24, v24 quad_perm:[1,0,3,2] row_mask:0xf bank_mask:0xf bound_ctrl:1
	v_add_f32_dpp v26, v26, v26 quad_perm:[1,0,3,2] row_mask:0xf bank_mask:0xf bound_ctrl:1
	v_mov_b32_e32 v27, v201
	v_add_f32_dpp v24, v24, v24 quad_perm:[2,3,0,1] row_mask:0xf bank_mask:0xf bound_ctrl:1
	v_add_f32_dpp v26, v26, v26 quad_perm:[2,3,0,1] row_mask:0xf bank_mask:0xf bound_ctrl:1
	s_nop 0
	v_add_f32_dpp v24, v24, v24 row_half_mirror row_mask:0xf bank_mask:0xf bound_ctrl:1
	v_add_f32_dpp v26, v26, v26 row_half_mirror row_mask:0xf bank_mask:0xf bound_ctrl:1
	s_nop 0
	v_add_f32_dpp v24, v24, v24 row_mirror row_mask:0xf bank_mask:0xf bound_ctrl:1
	v_add_f32_dpp v26, v26, v26 row_mirror row_mask:0xf bank_mask:0xf bound_ctrl:1
	s_nop 0
	v_mov_b32_dpp v25, v24 row_bcast:15 row_mask:0xa bank_mask:0xf
	v_mov_b32_dpp v27, v26 row_bcast:15 row_mask:0xa bank_mask:0xf
	v_add_f32_e32 v24, v24, v25
	v_mov_b32_e32 v25, v201
	v_add_f32_e32 v26, v26, v27
	v_mov_b32_e32 v27, v201
	v_mov_b32_dpp v25, v24 row_bcast:31 row_mask:0xc bank_mask:0xf
	s_nop 0
	v_mov_b32_dpp v27, v26 row_bcast:31 row_mask:0xc bank_mask:0xf
	s_and_saveexec_b64 s[62:63], s[4:5]
	v_add_f32_e32 v24, v24, v25
	v_add_f32_e32 v25, v26, v27
	v_mov_b32_e32 v26, s69
	ds_write2st64_b32 v26, v24, v25 offset0:2 offset1:6
	s_or_b64 exec, exec, s[62:63]
	v_mul_f32_e32 v24, v1, v149
	v_mul_f32_e32 v25, v3, v151
	v_mul_f32_e32 v26, v5, v141
	v_mul_f32_e32 v27, v7, v143
	v_fmac_f32_e32 v24, v0, v148
	v_fmac_f32_e32 v25, v2, v150
	v_fmac_f32_e32 v26, v4, v140
	v_fmac_f32_e32 v27, v6, v142
	v_add_f32_e32 v24, v24, v25
	v_add_f32_e32 v26, v26, v27
	v_mov_b32_e32 v25, v201
	v_add_f32_dpp v24, v24, v24 quad_perm:[1,0,3,2] row_mask:0xf bank_mask:0xf bound_ctrl:1
	v_add_f32_dpp v26, v26, v26 quad_perm:[1,0,3,2] row_mask:0xf bank_mask:0xf bound_ctrl:1
	v_mov_b32_e32 v27, v201
	v_add_f32_dpp v24, v24, v24 quad_perm:[2,3,0,1] row_mask:0xf bank_mask:0xf bound_ctrl:1
	v_add_f32_dpp v26, v26, v26 quad_perm:[2,3,0,1] row_mask:0xf bank_mask:0xf bound_ctrl:1
	s_nop 0
	v_add_f32_dpp v24, v24, v24 row_half_mirror row_mask:0xf bank_mask:0xf bound_ctrl:1
	v_add_f32_dpp v26, v26, v26 row_half_mirror row_mask:0xf bank_mask:0xf bound_ctrl:1
	s_nop 0
	v_add_f32_dpp v24, v24, v24 row_mirror row_mask:0xf bank_mask:0xf bound_ctrl:1
	v_add_f32_dpp v26, v26, v26 row_mirror row_mask:0xf bank_mask:0xf bound_ctrl:1
	s_nop 0
	v_mov_b32_dpp v25, v24 row_bcast:15 row_mask:0xa bank_mask:0xf
	v_mov_b32_dpp v27, v26 row_bcast:15 row_mask:0xa bank_mask:0xf
	v_add_f32_e32 v24, v24, v25
	v_mov_b32_e32 v25, v201
	v_add_f32_e32 v26, v26, v27
	v_mov_b32_e32 v27, v201
	v_mov_b32_dpp v25, v24 row_bcast:31 row_mask:0xc bank_mask:0xf
	s_nop 0
	v_mov_b32_dpp v27, v26 row_bcast:31 row_mask:0xc bank_mask:0xf
	s_and_saveexec_b64 s[62:63], s[4:5]
	v_add_f32_e32 v24, v24, v25
	v_add_f32_e32 v25, v26, v27
	v_add_u32_e64 v26, 4, s69
	ds_write2st64_b32 v26, v24, v25 offset0:2 offset1:6
	s_or_b64 exec, exec, s[62:63]
	s_waitcnt vmcnt(8)
	v_mul_f32_e32 v24, v1, v133
	v_mul_f32_e32 v25, v3, v135
	s_waitcnt vmcnt(8)
	v_mul_f32_e32 v26, v5, v129
	v_mul_f32_e32 v27, v7, v131
	v_fmac_f32_e32 v24, v0, v132
	v_fmac_f32_e32 v25, v2, v134
	v_fmac_f32_e32 v26, v4, v128
	v_fmac_f32_e32 v27, v6, v130
	v_add_f32_e32 v24, v24, v25
	v_add_f32_e32 v26, v26, v27
	v_mov_b32_e32 v25, v201
	v_add_f32_dpp v24, v24, v24 quad_perm:[1,0,3,2] row_mask:0xf bank_mask:0xf bound_ctrl:1
	v_add_f32_dpp v26, v26, v26 quad_perm:[1,0,3,2] row_mask:0xf bank_mask:0xf bound_ctrl:1
	v_mov_b32_e32 v27, v201
	v_add_f32_dpp v24, v24, v24 quad_perm:[2,3,0,1] row_mask:0xf bank_mask:0xf bound_ctrl:1
	v_add_f32_dpp v26, v26, v26 quad_perm:[2,3,0,1] row_mask:0xf bank_mask:0xf bound_ctrl:1
	s_nop 0
	v_add_f32_dpp v24, v24, v24 row_half_mirror row_mask:0xf bank_mask:0xf bound_ctrl:1
	v_add_f32_dpp v26, v26, v26 row_half_mirror row_mask:0xf bank_mask:0xf bound_ctrl:1
	s_nop 0
	v_add_f32_dpp v24, v24, v24 row_mirror row_mask:0xf bank_mask:0xf bound_ctrl:1
	v_add_f32_dpp v26, v26, v26 row_mirror row_mask:0xf bank_mask:0xf bound_ctrl:1
	s_nop 0
	v_mov_b32_dpp v25, v24 row_bcast:15 row_mask:0xa bank_mask:0xf
	v_mov_b32_dpp v27, v26 row_bcast:15 row_mask:0xa bank_mask:0xf
	v_add_f32_e32 v24, v24, v25
	v_mov_b32_e32 v25, v201
	v_add_f32_e32 v26, v26, v27
	v_mov_b32_e32 v27, v201
	v_mov_b32_dpp v25, v24 row_bcast:31 row_mask:0xc bank_mask:0xf
	s_nop 0
	v_mov_b32_dpp v27, v26 row_bcast:31 row_mask:0xc bank_mask:0xf
	s_and_saveexec_b64 s[62:63], s[4:5]
	v_add_f32_e32 v24, v24, v25
	v_add_f32_e32 v25, v26, v27
	v_add_u32_e64 v26, 8, s69
	ds_write2st64_b32 v26, v24, v25 offset0:2 offset1:6
	s_or_b64 exec, exec, s[62:63]
	s_waitcnt vmcnt(8)
	v_mul_f32_e32 v24, v1, v125
	v_mul_f32_e32 v25, v3, v127
	s_waitcnt vmcnt(8)
; __device__ __forceinline__ unsigned cvt_pk_bf16(float lo, float hi) { const f32x2cv v = {lo, hi}; return __builtin_bit_cast(unsigned, __builtin_convertvector(v, bf16x2cv)); }
; #define MFMA16(a, b, c) __builtin_amdgcn_mfma_f32_16x16x32_bf16((a), (b), (c), 0, 0, 0)
; #define ATT_VREAD(n_) do { _Pragma("unroll") for (int d_ = 0; d_ < 4; ++d_) { LAS unsigned char* p_ = slot + (32 * ((n_) >> 2) + 4 * fq + (fr >> 2)) * 544 + (16 * (4 * ((n_) & 3) + d_) + 4 * (fr & 3)) * 2; Vf[d_] = tr_frag(p_, p_ + 16 * 544); } } while (0)
; __device__ __forceinline__ void attn_fused(Frame& F0, int layer) {
;     ...
;                     for (int a = 0; a < 8; ++a) {
;                         u32x4 pw; pw.x = cvt_pk_bf16(S[2 * a][0], S[2 * a][1]); pw.y = cvt_pk_bf16(S[2 * a][2], S[2 * a][3]); pw.z = cvt_pk_bf16(S[2 * a + 1][0], S[2 * a + 1][1]); pw.w = cvt_pk_bf16(S[2 * a + 1][2], S[2 * a + 1][3]);
;                         Pf[a] = __builtin_bit_cast(bf16x8, pw);
;                     }
;                 }
;             } else {
;                 {
;                     bf16x8 Vf[4];
;     ...
; #pragma unroll
;                     for (int n = 0; n < 8; ++n) {
;                         ATT_VREAD(n);
; #pragma unroll
;                         for (int d = 0; d < 4; ++d) { const int al = n >> 2, dt = 4 * (n & 3) + d; Oa[dt] = MFMA16(Vf[d], Pf[2 * (c - 4) + al], (c == 4 && al == 0) ? zero4 : Oa[dt]); }
;                         __builtin_amdgcn_sched_group_barrier(0x100, 8, 0); __builtin_amdgcn_sched_group_barrier(0x008, 4, 0);
	v_mul_f32_e32 v26, v5, v121
	v_mul_f32_e32 v27, v7, v123
	v_fmac_f32_e32 v24, v0, v124
	v_fmac_f32_e32 v25, v2, v126
	v_fmac_f32_e32 v26, v4, v120
	v_fmac_f32_e32 v27, v6, v122
	v_add_f32_e32 v24, v24, v25
	v_add_f32_e32 v26, v26, v27
	v_mov_b32_e32 v25, v201
	v_add_f32_dpp v24, v24, v24 quad_perm:[1,0,3,2] row_mask:0xf bank_mask:0xf bound_ctrl:1
	v_add_f32_dpp v26, v26, v26 quad_perm:[1,0,3,2] row_mask:0xf bank_mask:0xf bound_ctrl:1
	v_mov_b32_e32 v27, v201
	v_add_f32_dpp v24, v24, v24 quad_perm:[2,3,0,1] row_mask:0xf bank_mask:0xf bound_ctrl:1
	v_add_f32_dpp v26, v26, v26 quad_perm:[2,3,0,1] row_mask:0xf bank_mask:0xf bound_ctrl:1
	s_nop 0
	v_add_f32_dpp v24, v24, v24 row_half_mirror row_mask:0xf bank_mask:0xf bound_ctrl:1
	v_add_f32_dpp v26, v26, v26 row_half_mirror row_mask:0xf bank_mask:0xf bound_ctrl:1
	s_nop 0
	v_add_f32_dpp v24, v24, v24 row_mirror row_mask:0xf bank_mask:0xf bound_ctrl:1
	v_add_f32_dpp v26, v26, v26 row_mirror row_mask:0xf bank_mask:0xf bound_ctrl:1
	s_nop 0
	v_mov_b32_dpp v25, v24 row_bcast:15 row_mask:0xa bank_mask:0xf
	v_mov_b32_dpp v27, v26 row_bcast:15 row_mask:0xa bank_mask:0xf
	v_add_f32_e32 v24, v24, v25
	v_mov_b32_e32 v25, v201
	v_add_f32_e32 v26, v26, v27
	v_mov_b32_e32 v27, v201
	v_mov_b32_dpp v25, v24 row_bcast:31 row_mask:0xc bank_mask:0xf
	s_nop 0
	v_mov_b32_dpp v27, v26 row_bcast:31 row_mask:0xc bank_mask:0xf
	s_and_saveexec_b64 s[62:63], s[4:5]
	v_add_f32_e32 v24, v24, v25
	v_add_f32_e32 v25, v26, v27
	v_add_u32_e64 v26, 12, s69
	ds_write2st64_b32 v26, v24, v25 offset0:2 offset1:6
	s_or_b64 exec, exec, s[62:63]
	v_mov_b64_e32 v[48:49], v[108:109]
	v_mov_b64_e32 v[40:41], v[104:105]
	s_mov_b64 s[62:63], s[48:49]
	v_mov_b64_e32 v[50:51], v[110:111]
	v_mov_b64_e32 v[42:43], v[106:107]
.LBB0_2094:
	ds_read_b64_tr_b16 v[30:31], v190 offset:8704
	ds_read_b64_tr_b16 v[28:29], v190
	ds_read_b64_tr_b16 v[32:33], v190 offset:32
	ds_read_b64_tr_b16 v[34:35], v190 offset:8736
	ds_read_b64_tr_b16 v[36:37], v190 offset:64
	ds_read_b64_tr_b16 v[38:39], v190 offset:8768
	ds_read_b64_tr_b16 v[72:73], v190 offset:96
	ds_read_b64_tr_b16 v[74:75], v190 offset:8800
	v_cvt_pk_bf16_f32 v24, v203, v204
	v_cvt_pk_bf16_f32 v25, v205, v231
	v_cvt_pk_bf16_f32 v26, v160, v161
	v_cvt_pk_bf16_f32 v27, v162, v163
	v_cvt_pk_bf16_f32 v52, v52, v53
	v_cvt_pk_bf16_f32 v53, v54, v55
	s_waitcnt lgkmcnt(6)
	v_mfma_f32_16x16x32_bf16 v[28:31], v[28:31], v[24:27], 0
	v_cvt_pk_bf16_f32 v54, v44, v45
	v_cvt_pk_bf16_f32 v55, v46, v47
	s_waitcnt vmcnt(8)
	s_add_u32 s100, s62, 0x20000
	s_addc_u32 s101, s63, 0
	v_lshl_add_u64 v[132:133], s[62:63], 0, v[200:201]
	s_waitcnt lgkmcnt(4)
	v_mfma_f32_16x16x32_bf16 v[32:35], v[32:35], v[24:27], 0
	s_mov_b64 s[62:63], s[50:51]
	global_load_dwordx4 v[152:155], v[132:133], off nt
	global_load_dwordx4 v[160:163], v[132:133], off offset:1024 nt
	s_waitcnt lgkmcnt(2)
	v_mfma_f32_16x16x32_bf16 v[36:39], v[36:39], v[24:27], 0
	s_mov_b64 s[64:65], -1
	s_waitcnt lgkmcnt(0)
	v_mfma_f32_16x16x32_bf16 v[84:87], v[72:75], v[24:27], 0
	ds_read_b64_tr_b16 v[74:75], v190 offset:8832
	ds_read_b64_tr_b16 v[72:73], v190 offset:128
	ds_read_b64_tr_b16 v[76:77], v190 offset:160
	ds_read_b64_tr_b16 v[78:79], v190 offset:8864
	ds_read_b64_tr_b16 v[80:81], v190 offset:192
	ds_read_b64_tr_b16 v[82:83], v190 offset:8896
	ds_read_b64_tr_b16 v[88:89], v190 offset:224
	ds_read_b64_tr_b16 v[90:91], v190 offset:8928
	s_waitcnt lgkmcnt(6)
	v_mfma_f32_16x16x32_bf16 v[92:95], v[72:75], v[24:27], 0
	s_waitcnt lgkmcnt(4)
	v_mfma_f32_16x16x32_bf16 v[96:99], v[76:79], v[24:27], 0
	s_waitcnt lgkmcnt(2)
	v_mfma_f32_16x16x32_bf16 v[100:103], v[80:83], v[24:27], 0
	s_waitcnt lgkmcnt(0)
	v_mfma_f32_16x16x32_bf16 v[104:107], v[88:91], v[24:27], 0
	ds_read_b64_tr_b16 v[74:75], v190 offset:8960
	ds_read_b64_tr_b16 v[72:73], v190 offset:256
	ds_read_b64_tr_b16 v[76:77], v190 offset:288
	ds_read_b64_tr_b16 v[78:79], v190 offset:8992
	ds_read_b64_tr_b16 v[80:81], v190 offset:320
	ds_read_b64_tr_b16 v[82:83], v190 offset:9024
	ds_read_b64_tr_b16 v[88:89], v190 offset:352
	ds_read_b64_tr_b16 v[90:91], v190 offset:9056
	s_waitcnt lgkmcnt(6)
	v_mfma_f32_16x16x32_bf16 v[108:111], v[72:75], v[24:27], 0
	s_waitcnt lgkmcnt(4)
	v_mfma_f32_16x16x32_bf16 v[112:115], v[76:79], v[24:27], 0
	s_waitcnt lgkmcnt(2)
	v_mfma_f32_16x16x32_bf16 v[116:119], v[80:83], v[24:27], 0
	s_waitcnt vmcnt(10) lgkmcnt(0)
	v_mfma_f32_16x16x32_bf16 v[120:123], v[88:91], v[24:27], 0
	ds_read_b64_tr_b16 v[74:75], v190 offset:9088
	ds_read_b64_tr_b16 v[72:73], v190 offset:384
	ds_read_b64_tr_b16 v[76:77], v190 offset:416
	ds_read_b64_tr_b16 v[78:79], v190 offset:9120
	ds_read_b64_tr_b16 v[80:81], v190 offset:448
	ds_read_b64_tr_b16 v[82:83], v190 offset:9152
	ds_read_b64_tr_b16 v[88:89], v190 offset:480
	ds_read_b64_tr_b16 v[90:91], v190 offset:9184
	s_waitcnt lgkmcnt(6)
	v_mfma_f32_16x16x32_bf16 v[124:127], v[72:75], v[24:27], 0
	s_waitcnt lgkmcnt(4)
	v_mfma_f32_16x16x32_bf16 v[128:131], v[76:79], v[24:27], 0
	s_waitcnt lgkmcnt(2)
	v_mfma_f32_16x16x32_bf16 v[204:207], v[80:83], v[24:27], 0
	s_waitcnt lgkmcnt(0)
	v_mfma_f32_16x16x32_bf16 v[208:211], v[88:91], v[24:27], 0
	ds_read_b64_tr_b16 v[26:27], v190 offset:26112
	ds_read_b64_tr_b16 v[24:25], v190 offset:17408
	ds_read_b64_tr_b16 v[44:45], v190 offset:17440
	ds_read_b64_tr_b16 v[46:47], v190 offset:26144
	ds_read_b64_tr_b16 v[80:81], v190 offset:17472
	ds_read_b64_tr_b16 v[82:83], v190 offset:26176
	ds_read_b64_tr_b16 v[88:89], v190 offset:17504
	ds_read_b64_tr_b16 v[90:91], v190 offset:26208
	s_waitcnt lgkmcnt(6)
	v_mfma_f32_16x16x32_bf16 v[72:75], v[24:27], v[52:55], v[28:31]
	s_waitcnt lgkmcnt(4)
; #define LDS_BARRIER() asm volatile("s_waitcnt lgkmcnt(0)\n\ts_barrier" ::: "memory")
; #define MFMA16(a, b, c) __builtin_amdgcn_mfma_f32_16x16x32_bf16((a), (b), (c), 0, 0, 0)
; #define ATT_LSTORE(slot) do { _Pragma("unroll") for (int i_ = 0; i_ < 4; ++i_) { const int idx_ = tid + 512 * i_; *(LAS u32x4*)(lds + (slot) * ATT_SLOT + (idx_ >> 5) * 544 + (idx_ & 31) * 16) = st[i_]; } } while (0)
; #define ATT_LSTORE(c) do { _Pragma("unroll") for (int i_ = 0; i_ < 4; ++i_) *(LAS u32x4*)(lds + ((c) & 1) * ATT_SLOT + 16 * i_ * 544 + loff) = st[(c) & 1][i_]; } while (0)
; #define ATT_VREAD(n_) do { _Pragma("unroll") for (int d_ = 0; d_ < 4; ++d_) { LAS unsigned char* p_ = slot + (32 * ((n_) >> 2) + 4 * fq + (fr >> 2)) * 544 + (16 * (4 * ((n_) & 3) + d_) + 4 * (fr & 3)) * 2; Vf[d_] = tr_frag(p_, p_ + 16 * 544); } } while (0)
; __device__ __forceinline__ void attn_fused(Frame& F0, int layer) {
;     ...
; #pragma unroll
;                 for (int r = 0; r < 4; ++r) {
;                     const int m = 32 * c + 4 * w + r;
;                     const float p0 = __builtin_amdgcn_exp2f(sc[m] - mx0) * iv0, p1 = __builtin_amdgcn_exp2f(sc[256 + m] - mx1) * iv1;
;                     a0 += sv[2 * r] * p0; a1 += sv[2 * r + 1] * p1;
;                 }
;                 if (c < 7) FA_SLOAD(vp, c + 1);
;     ...
;                 {
;                     bf16x8 Vf[4];
;     ...
; #pragma unroll
;                     for (int n = 0; n < 8; ++n) {
;                         ATT_VREAD(n);
; #pragma unroll
;                         for (int d = 0; d < 4; ++d) { const int al = n >> 2, dt = 4 * (n & 3) + d; Oa[dt] = MFMA16(Vf[d], Pf[2 * (c - 4) + al], (c == 4 && al == 0) ? zero4 : Oa[dt]); }
;                         __builtin_amdgcn_sched_group_barrier(0x100, 8, 0); __builtin_amdgcn_sched_group_barrier(0x008, 4, 0);
;                     }
;     ...
;                 }
;             }
;             if (c < 7) ATT_LSTORE(c + 1);
;             LDS_BARRIER();
	v_mfma_f32_16x16x32_bf16 v[76:79], v[44:47], v[52:55], v[32:35]
	v_add_co_u32_e32 v44, vcc, s33, v132
	s_waitcnt lgkmcnt(2)
	v_mfma_f32_16x16x32_bf16 v[80:83], v[80:83], v[52:55], v[36:39]
	v_addc_co_u32_e32 v45, vcc, 0, v133, vcc
	v_add_co_u32_e32 v134, vcc, s70, v132
	s_waitcnt lgkmcnt(0)
	v_mfma_f32_16x16x32_bf16 v[84:87], v[88:91], v[52:55], v[84:87]
	ds_read_b64_tr_b16 v[26:27], v190 offset:26240
	ds_read_b64_tr_b16 v[24:25], v190 offset:17536
	ds_read_b64_tr_b16 v[28:29], v190 offset:17568
	ds_read_b64_tr_b16 v[30:31], v190 offset:26272
	ds_read_b64_tr_b16 v[32:33], v190 offset:17600
	ds_read_b64_tr_b16 v[34:35], v190 offset:26304
	ds_read_b64_tr_b16 v[36:37], v190 offset:17632
	ds_read_b64_tr_b16 v[38:39], v190 offset:26336
	s_waitcnt lgkmcnt(6)
	v_mfma_f32_16x16x32_bf16 v[88:91], v[24:27], v[52:55], v[92:95]
	v_addc_co_u32_e32 v135, vcc, 0, v133, vcc
	global_load_dwordx4 v[148:151], v[44:45], off offset:1024 nt
	s_waitcnt lgkmcnt(4)
	v_mfma_f32_16x16x32_bf16 v[92:95], v[28:31], v[52:55], v[96:99]
	global_load_dwordx4 v[156:159], v[134:135], off offset:-4096 nt
	s_waitcnt lgkmcnt(2)
	v_mfma_f32_16x16x32_bf16 v[96:99], v[32:35], v[52:55], v[100:103]
	s_waitcnt lgkmcnt(0)
	v_mfma_f32_16x16x32_bf16 v[100:103], v[36:39], v[52:55], v[104:107]
	ds_read_b64_tr_b16 v[26:27], v190 offset:26368
	ds_read_b64_tr_b16 v[24:25], v190 offset:17664
	ds_read_b64_tr_b16 v[28:29], v190 offset:17696
	ds_read_b64_tr_b16 v[30:31], v190 offset:26400
	ds_read_b64_tr_b16 v[32:33], v190 offset:17728
	ds_read_b64_tr_b16 v[34:35], v190 offset:26432
	ds_read_b64_tr_b16 v[36:37], v190 offset:17760
	ds_read_b64_tr_b16 v[38:39], v190 offset:26464
	s_waitcnt lgkmcnt(6)
	v_mfma_f32_16x16x32_bf16 v[104:107], v[24:27], v[52:55], v[108:111]
	s_waitcnt lgkmcnt(4)
	v_mfma_f32_16x16x32_bf16 v[108:111], v[28:31], v[52:55], v[112:115]
	s_waitcnt lgkmcnt(2)
	v_mfma_f32_16x16x32_bf16 v[112:115], v[32:35], v[52:55], v[116:119]
	s_waitcnt lgkmcnt(0)
	v_mfma_f32_16x16x32_bf16 v[116:119], v[36:39], v[52:55], v[120:123]
	ds_read_b64_tr_b16 v[26:27], v190 offset:26496
	ds_read_b64_tr_b16 v[24:25], v190 offset:17792
	ds_read_b64_tr_b16 v[28:29], v190 offset:17824
	ds_read_b64_tr_b16 v[30:31], v190 offset:26528
	ds_read_b64_tr_b16 v[32:33], v190 offset:17856
	ds_read_b64_tr_b16 v[34:35], v190 offset:26560
	ds_read_b64_tr_b16 v[44:45], v190 offset:17888
	ds_read_b64_tr_b16 v[46:47], v190 offset:26592
	s_waitcnt lgkmcnt(6)
	v_mfma_f32_16x16x32_bf16 v[120:123], v[24:27], v[52:55], v[124:127]
	v_add_co_u32_e32 v24, vcc, s95, v132
	ds_write_b128 v191, v[56:59] offset:34816
	s_nop 0
	v_addc_co_u32_e32 v25, vcc, 0, v133, vcc
	ds_write_b128 v191, v[60:63] offset:43520
	ds_write_b128 v191, v[64:67] offset:52224
	ds_write_b128 v191, v[68:71] offset:60928
	s_bitset0_b32 m0, 12
	v_add_u32_e32 v134, 0x2000, v200
	v_add_u32_e32 v135, 0x2800, v200
	global_load_lds_dwordx4 v134, s[100:101] nt
	global_load_lds_dwordx4 v134, s[100:101] offset:1024 nt
	global_load_lds_dwordx4 v135, s[100:101] offset:2048 nt
	global_load_lds_dwordx4 v135, s[100:101] offset:3072 nt
	s_waitcnt lgkmcnt(0)
	s_barrier
	s_waitcnt lgkmcnt(8)
	v_mfma_f32_16x16x32_bf16 v[124:127], v[28:31], v[52:55], v[128:131]
	v_lshl_add_u64 v[36:37], s[62:63], 0, v[176:177]
	v_add_co_u32_e32 v28, vcc, 0x8000, v36
	s_waitcnt lgkmcnt(6)
	v_mfma_f32_16x16x32_bf16 v[128:131], v[32:35], v[52:55], v[204:207]
	v_addc_co_u32_e32 v29, vcc, 0, v37, vcc
	v_add_co_u32_e32 v32, vcc, 0x10000, v36
	global_load_dwordx4 v[24:27], v[36:37], off
	s_nop 0
	v_addc_co_u32_e32 v33, vcc, 0, v37, vcc
	v_add_co_u32_e32 v36, vcc, 0x18000, v36
	global_load_dwordx4 v[28:31], v[28:29], off
	s_nop 0
	v_addc_co_u32_e32 v37, vcc, 0, v37, vcc
	global_load_dwordx4 v[32:35], v[32:33], off
	s_waitcnt lgkmcnt(4)
	v_mfma_f32_16x16x32_bf16 v[56:59], v[44:47], v[52:55], v[208:211]
	global_load_dwordx4 v[36:39], v[36:37], off
	s_and_b64 vcc, exec, s[6:7]
	s_cbranch_vccnz .LBB0_2096
	s_waitcnt vmcnt(8)
	v_add_u32_e32 v132, m0, v200
	v_and_b32_e32 v132, 0xffffefff, v132
	ds_read_b128 v[140:143], v132 offset:4096
	ds_read_b128 v[144:147], v132 offset:5120
	ds_read_b128 v[136:139], v132 offset:6144
	ds_read_b128 v[132:135], v132 offset:7168
	s_waitcnt lgkmcnt(0)
	v_mov_b32_e32 v52, s69
	ds_read_b128 v[44:47], v52 offset:1664
	ds_read_b128 v[52:55], v52 offset:640
	s_mov_b64 s[62:63], s[52:53]
	s_mov_b64 s[64:65], 0
	s_waitcnt lgkmcnt(1)
	v_sub_f32_e32 v44, v44, v193
	v_sub_f32_e32 v45, v45, v193
	v_exp_f32_e32 v44, v44
	v_exp_f32_e32 v45, v45
	v_sub_f32_e32 v46, v46, v193
	v_exp_f32_e32 v62, v46
	v_mul_f32_e32 v44, v182, v44
	v_mul_f32_e32 v46, v182, v45
	s_waitcnt vmcnt(10)
	v_pk_fma_f32 v[60:61], v[162:163], v[44:45], v[42:43] op_sel_hi:[1,0,1]
	v_pk_fma_f32 v[44:45], v[160:161], v[44:45], v[40:41] op_sel_hi:[1,0,1]
	s_waitcnt vmcnt(9)
	v_pk_fma_f32 v[60:61], v[150:151], v[46:47], v[60:61] op_sel_hi:[1,0,1]
	v_pk_fma_f32 v[44:45], v[148:149], v[46:47], v[44:45] op_sel_hi:[1,0,1]
	v_sub_f32_e32 v46, v47, v193
	v_exp_f32_e32 v47, v46
	v_mul_f32_e32 v46, v182, v62
	s_waitcnt lgkmcnt(0)
	v_sub_f32_e32 v52, v52, v192
	v_exp_f32_e32 v52, v52
	s_waitcnt vmcnt(8)
	v_pk_fma_f32 v[60:61], v[146:147], v[46:47], v[60:61] op_sel_hi:[1,0,1]
	v_pk_fma_f32 v[44:45], v[144:145], v[46:47], v[44:45] op_sel_hi:[1,0,1]
	v_mul_f32_e32 v62, v182, v47
	v_sub_f32_e32 v53, v53, v192
	s_waitcnt vmcnt(8)
	v_pk_fma_f32 v[46:47], v[134:135], v[62:63], v[60:61] op_sel_hi:[1,0,1]
	v_pk_fma_f32 v[44:45], v[132:133], v[62:63], v[44:45] op_sel_hi:[1,0,1]
	v_exp_f32_e32 v62, v53
	v_sub_f32_e32 v54, v54, v192
	v_exp_f32_e32 v54, v54
	v_sub_f32_e32 v55, v55, v192
	v_exp_f32_e32 v55, v55
	v_mul_f32_e32 v52, v169, v52
	v_pk_fma_f32 v[60:61], v[154:155], v[52:53], v[50:51] op_sel_hi:[1,0,1]
	v_pk_fma_f32 v[52:53], v[152:153], v[52:53], v[48:49] op_sel_hi:[1,0,1]
	v_mul_f32_e32 v62, v169, v62
	v_pk_fma_f32 v[60:61], v[158:159], v[62:63], v[60:61] op_sel_hi:[1,0,1]
	v_pk_fma_f32 v[52:53], v[156:157], v[62:63], v[52:53] op_sel_hi:[1,0,1]
	v_mul_f32_e32 v54, v169, v54
	v_pk_fma_f32 v[60:61], v[142:143], v[54:55], v[60:61] op_sel_hi:[1,0,1]
	v_pk_fma_f32 v[52:53], v[140:141], v[54:55], v[52:53] op_sel_hi:[1,0,1]
	v_mul_f32_e32 v62, v169, v55
	v_pk_fma_f32 v[54:55], v[138:139], v[62:63], v[60:61] op_sel_hi:[1,0,1]
	v_pk_fma_f32 v[52:53], v[136:137], v[62:63], v[52:53] op_sel_hi:[1,0,1]
; __device__ __forceinline__ float dot4(f32x4 a, f32x4 b) { return (a[0] * b[0] + a[1] * b[1]) + (a[2] * b[2] + a[3] * b[3]); }
; #define dpp_mov(v, ctrl, row_mask) __builtin_bit_cast(float, __builtin_amdgcn_update_dpp(0, __builtin_bit_cast(int, (float)(v)), (ctrl), (row_mask), 0xf, false))
; __device__ __forceinline__ float wave_sum_dpp(float x) {
;     x += dpp_mov(x, 0xB1, 0xf);
;     x += dpp_mov(x, 0x4E, 0xf);
;     x += dpp_mov(x, 0x141, 0xf);
;     x += dpp_mov(x, 0x140, 0xf);
;     x += dpp_mov(x, 0x142, 0xa);
;     x += dpp_mov(x, 0x143, 0xc);
;     return x;
; }
; __device__ __forceinline__ void attn_fused(Frame& F0, int layer) {
;     ...
;             if (ui == 0) {
; #pragma unroll
;                 for (int r = 0; r < 4; ++r) {
;                     const int m = 32 * c + 4 * w + r;
;                     const float d0 = wave_sum_dpp(dot4(sv[2 * r], q0)), d1 = wave_sum_dpp(dot4(sv[2 * r + 1], q1));
;                     if (lane == 63) { sc[m] = d0; sc[256 + m] = d1; }
;                 }
;                 if (c < 7) FA_SLOAD(kp, c + 1); else FA_SLOAD(vp, 0);
.LBB0_2096:
	s_andn2_b64 vcc, exec, s[64:65]
	s_cbranch_vccnz .LBB0_2106
	s_waitcnt vmcnt(8)
	v_add_u32_e32 v132, m0, v200
	v_and_b32_e32 v132, 0xffffefff, v132
	ds_read_b128 v[140:143], v132 offset:4096
	ds_read_b128 v[144:147], v132 offset:5120
	ds_read_b128 v[136:139], v132 offset:6144
	ds_read_b128 v[132:135], v132 offset:7168
	s_waitcnt lgkmcnt(0)
	s_waitcnt vmcnt(11)
	v_mul_f32_e32 v44, v1, v153
	v_mul_f32_e32 v45, v3, v155
	s_waitcnt vmcnt(10)
	v_mul_f32_e32 v46, v5, v161
	v_mul_f32_e32 v47, v7, v163
	v_fmac_f32_e32 v44, v0, v152
	v_fmac_f32_e32 v45, v2, v154
	v_fmac_f32_e32 v46, v4, v160
	v_fmac_f32_e32 v47, v6, v162
	v_add_f32_e32 v44, v44, v45
	v_add_f32_e32 v46, v46, v47
	v_mov_b32_e32 v45, v201
	v_add_f32_dpp v44, v44, v44 quad_perm:[1,0,3,2] row_mask:0xf bank_mask:0xf bound_ctrl:1
	v_add_f32_dpp v46, v46, v46 quad_perm:[1,0,3,2] row_mask:0xf bank_mask:0xf bound_ctrl:1
	v_mov_b32_e32 v47, v201
	v_add_f32_dpp v44, v44, v44 quad_perm:[2,3,0,1] row_mask:0xf bank_mask:0xf bound_ctrl:1
	v_add_f32_dpp v46, v46, v46 quad_perm:[2,3,0,1] row_mask:0xf bank_mask:0xf bound_ctrl:1
	s_nop 0
	v_add_f32_dpp v44, v44, v44 row_half_mirror row_mask:0xf bank_mask:0xf bound_ctrl:1
	v_add_f32_dpp v46, v46, v46 row_half_mirror row_mask:0xf bank_mask:0xf bound_ctrl:1
	s_nop 0
	v_add_f32_dpp v44, v44, v44 row_mirror row_mask:0xf bank_mask:0xf bound_ctrl:1
	v_add_f32_dpp v46, v46, v46 row_mirror row_mask:0xf bank_mask:0xf bound_ctrl:1
	s_nop 0
	v_mov_b32_dpp v45, v44 row_bcast:15 row_mask:0xa bank_mask:0xf
	v_mov_b32_dpp v47, v46 row_bcast:15 row_mask:0xa bank_mask:0xf
	v_add_f32_e32 v44, v44, v45
	v_mov_b32_e32 v45, v201
	v_add_f32_e32 v46, v46, v47
	v_mov_b32_e32 v47, v201
	v_mov_b32_dpp v45, v44 row_bcast:31 row_mask:0xc bank_mask:0xf
	s_nop 0
	v_mov_b32_dpp v47, v46 row_bcast:31 row_mask:0xc bank_mask:0xf
	s_and_saveexec_b64 s[62:63], s[4:5]
	v_add_f32_e32 v44, v44, v45
	v_add_f32_e32 v45, v46, v47
	v_mov_b32_e32 v46, s69
	v_add_u32_e32 v46, 0x80, v46
	ds_write2st64_b32 v46, v44, v45 offset0:2 offset1:6
	s_or_b64 exec, exec, s[62:63]
	s_waitcnt vmcnt(8)
	v_mul_f32_e32 v44, v1, v157
	v_mul_f32_e32 v45, v3, v159
	v_mul_f32_e32 v46, v5, v149
	v_mul_f32_e32 v47, v7, v151
	v_fmac_f32_e32 v44, v0, v156
	v_fmac_f32_e32 v45, v2, v158
	v_fmac_f32_e32 v46, v4, v148
	v_fmac_f32_e32 v47, v6, v150
	v_add_f32_e32 v44, v44, v45
	v_add_f32_e32 v46, v46, v47
	v_mov_b32_e32 v45, v201
	v_add_f32_dpp v44, v44, v44 quad_perm:[1,0,3,2] row_mask:0xf bank_mask:0xf bound_ctrl:1
	v_add_f32_dpp v46, v46, v46 quad_perm:[1,0,3,2] row_mask:0xf bank_mask:0xf bound_ctrl:1
	v_mov_b32_e32 v47, v201
	v_add_f32_dpp v44, v44, v44 quad_perm:[2,3,0,1] row_mask:0xf bank_mask:0xf bound_ctrl:1
	v_add_f32_dpp v46, v46, v46 quad_perm:[2,3,0,1] row_mask:0xf bank_mask:0xf bound_ctrl:1
	s_nop 0
	v_add_f32_dpp v44, v44, v44 row_half_mirror row_mask:0xf bank_mask:0xf bound_ctrl:1
	v_add_f32_dpp v46, v46, v46 row_half_mirror row_mask:0xf bank_mask:0xf bound_ctrl:1
	s_nop 0
	v_add_f32_dpp v44, v44, v44 row_mirror row_mask:0xf bank_mask:0xf bound_ctrl:1
	v_add_f32_dpp v46, v46, v46 row_mirror row_mask:0xf bank_mask:0xf bound_ctrl:1
	s_nop 0
	v_mov_b32_dpp v45, v44 row_bcast:15 row_mask:0xa bank_mask:0xf
	v_mov_b32_dpp v47, v46 row_bcast:15 row_mask:0xa bank_mask:0xf
	v_add_f32_e32 v44, v44, v45
	v_mov_b32_e32 v45, v201
	v_add_f32_e32 v46, v46, v47
	v_mov_b32_e32 v47, v201
	v_mov_b32_dpp v45, v44 row_bcast:31 row_mask:0xc bank_mask:0xf
	s_nop 0
	v_mov_b32_dpp v47, v46 row_bcast:31 row_mask:0xc bank_mask:0xf
	s_and_saveexec_b64 s[62:63], s[4:5]
	v_add_f32_e32 v44, v44, v45
	v_add_f32_e32 v45, v46, v47
	v_mov_b32_e32 v46, s69
	v_add_u32_e32 v46, 0x84, v46
	ds_write2st64_b32 v46, v44, v45 offset0:2 offset1:6
	s_or_b64 exec, exec, s[62:63]
	s_waitcnt vmcnt(8)
	v_mul_f32_e32 v44, v1, v141
	v_mul_f32_e32 v45, v3, v143
	s_waitcnt vmcnt(8)
	v_mul_f32_e32 v46, v5, v145
	v_mul_f32_e32 v47, v7, v147
	v_fmac_f32_e32 v44, v0, v140
	v_fmac_f32_e32 v45, v2, v142
	v_fmac_f32_e32 v46, v4, v144
	v_fmac_f32_e32 v47, v6, v146
	v_add_f32_e32 v44, v44, v45
	v_add_f32_e32 v46, v46, v47
	v_mov_b32_e32 v45, v201
	v_add_f32_dpp v44, v44, v44 quad_perm:[1,0,3,2] row_mask:0xf bank_mask:0xf bound_ctrl:1
	v_add_f32_dpp v46, v46, v46 quad_perm:[1,0,3,2] row_mask:0xf bank_mask:0xf bound_ctrl:1
	v_mov_b32_e32 v47, v201
	v_add_f32_dpp v44, v44, v44 quad_perm:[2,3,0,1] row_mask:0xf bank_mask:0xf bound_ctrl:1
	v_add_f32_dpp v46, v46, v46 quad_perm:[2,3,0,1] row_mask:0xf bank_mask:0xf bound_ctrl:1
	s_nop 0
	v_add_f32_dpp v44, v44, v44 row_half_mirror row_mask:0xf bank_mask:0xf bound_ctrl:1
	v_add_f32_dpp v46, v46, v46 row_half_mirror row_mask:0xf bank_mask:0xf bound_ctrl:1
	s_nop 0
	v_add_f32_dpp v44, v44, v44 row_mirror row_mask:0xf bank_mask:0xf bound_ctrl:1
	v_add_f32_dpp v46, v46, v46 row_mirror row_mask:0xf bank_mask:0xf bound_ctrl:1
	s_nop 0
	v_mov_b32_dpp v45, v44 row_bcast:15 row_mask:0xa bank_mask:0xf
	v_mov_b32_dpp v47, v46 row_bcast:15 row_mask:0xa bank_mask:0xf
	v_add_f32_e32 v44, v44, v45
	v_mov_b32_e32 v45, v201
	v_add_f32_e32 v46, v46, v47
	v_mov_b32_e32 v47, v201
	v_mov_b32_dpp v45, v44 row_bcast:31 row_mask:0xc bank_mask:0xf
	s_nop 0
	v_mov_b32_dpp v47, v46 row_bcast:31 row_mask:0xc bank_mask:0xf
	s_and_saveexec_b64 s[62:63], s[4:5]
	v_add_f32_e32 v44, v44, v45
	v_add_f32_e32 v45, v46, v47
	v_mov_b32_e32 v46, s69
	v_add_u32_e32 v46, 0x88, v46
	ds_write2st64_b32 v46, v44, v45 offset0:2 offset1:6
	s_or_b64 exec, exec, s[62:63]
	s_waitcnt vmcnt(8)
	v_mul_f32_e32 v44, v1, v137
	v_mul_f32_e32 v45, v3, v139
	s_waitcnt vmcnt(8)
; #define MFMA16(a, b, c) __builtin_amdgcn_mfma_f32_16x16x32_bf16((a), (b), (c), 0, 0, 0)
; #define ATT_VREAD(n_) do { _Pragma("unroll") for (int d_ = 0; d_ < 4; ++d_) { LAS unsigned char* p_ = slot + (32 * ((n_) >> 2) + 4 * fq + (fr >> 2)) * 544 + (16 * (4 * ((n_) & 3) + d_) + 4 * (fr & 3)) * 2; Vf[d_] = tr_frag(p_, p_ + 16 * 544); } } while (0)
; __device__ __forceinline__ void attn_fused(Frame& F0, int layer) {
;     ...
;             } else {
;                 {
;                     bf16x8 Vf[4];
;     ...
; #pragma unroll
;                     for (int n = 0; n < 8; ++n) {
;                         ATT_VREAD(n);
; #pragma unroll
;                         for (int d = 0; d < 4; ++d) { const int al = n >> 2, dt = 4 * (n & 3) + d; Oa[dt] = MFMA16(Vf[d], Pf[2 * (c - 4) + al], (c == 4 && al == 0) ? zero4 : Oa[dt]); }
;                         __builtin_amdgcn_sched_group_barrier(0x100, 8, 0); __builtin_amdgcn_sched_group_barrier(0x008, 4, 0);
	v_mul_f32_e32 v46, v5, v133
	v_mul_f32_e32 v47, v7, v135
	v_fmac_f32_e32 v44, v0, v136
	v_fmac_f32_e32 v45, v2, v138
	v_fmac_f32_e32 v46, v4, v132
	v_fmac_f32_e32 v47, v6, v134
	v_add_f32_e32 v44, v44, v45
	v_add_f32_e32 v46, v46, v47
	v_mov_b32_e32 v45, v201
	v_add_f32_dpp v44, v44, v44 quad_perm:[1,0,3,2] row_mask:0xf bank_mask:0xf bound_ctrl:1
	v_add_f32_dpp v46, v46, v46 quad_perm:[1,0,3,2] row_mask:0xf bank_mask:0xf bound_ctrl:1
	v_mov_b32_e32 v47, v201
	v_add_f32_dpp v44, v44, v44 quad_perm:[2,3,0,1] row_mask:0xf bank_mask:0xf bound_ctrl:1
	v_add_f32_dpp v46, v46, v46 quad_perm:[2,3,0,1] row_mask:0xf bank_mask:0xf bound_ctrl:1
	s_nop 0
	v_add_f32_dpp v44, v44, v44 row_half_mirror row_mask:0xf bank_mask:0xf bound_ctrl:1
	v_add_f32_dpp v46, v46, v46 row_half_mirror row_mask:0xf bank_mask:0xf bound_ctrl:1
	s_nop 0
	v_add_f32_dpp v44, v44, v44 row_mirror row_mask:0xf bank_mask:0xf bound_ctrl:1
	v_add_f32_dpp v46, v46, v46 row_mirror row_mask:0xf bank_mask:0xf bound_ctrl:1
	s_nop 0
	v_mov_b32_dpp v45, v44 row_bcast:15 row_mask:0xa bank_mask:0xf
	v_mov_b32_dpp v47, v46 row_bcast:15 row_mask:0xa bank_mask:0xf
	v_add_f32_e32 v44, v44, v45
	v_mov_b32_e32 v45, v201
	v_add_f32_e32 v46, v46, v47
	v_mov_b32_e32 v47, v201
	v_mov_b32_dpp v45, v44 row_bcast:31 row_mask:0xc bank_mask:0xf
	s_nop 0
	v_mov_b32_dpp v47, v46 row_bcast:31 row_mask:0xc bank_mask:0xf
	s_and_saveexec_b64 s[62:63], s[4:5]
	v_add_f32_e32 v44, v44, v45
	v_add_f32_e32 v45, v46, v47
	v_mov_b32_e32 v46, s69
	v_add_u32_e32 v46, 0x8c, v46
	ds_write2st64_b32 v46, v44, v45 offset0:2 offset1:6
	s_or_b64 exec, exec, s[62:63]
	v_mov_b64_e32 v[54:55], v[50:51]
	v_mov_b64_e32 v[46:47], v[42:43]
	s_mov_b64 s[62:63], s[54:55]
	v_mov_b64_e32 v[52:53], v[48:49]
	v_mov_b64_e32 v[44:45], v[40:41]
.LBB0_2106:
	ds_read_b64_tr_b16 v[50:51], v190 offset:43520
	ds_read_b64_tr_b16 v[48:49], v190 offset:34816
	ds_read_b64_tr_b16 v[60:61], v190 offset:34848
	ds_read_b64_tr_b16 v[62:63], v190 offset:43552
	ds_read_b64_tr_b16 v[64:65], v190 offset:34880
	ds_read_b64_tr_b16 v[66:67], v190 offset:43584
	ds_read_b64_tr_b16 v[68:69], v190 offset:34912
	ds_read_b64_tr_b16 v[70:71], v190 offset:43616
	v_cvt_pk_bf16_f32 v40, v229, v233
	v_cvt_pk_bf16_f32 v41, v234, v202
	v_cvt_pk_bf16_f32 v42, v250, v251
	v_cvt_pk_bf16_f32 v43, v252, v253
	s_waitcnt vmcnt(8)
	v_cvt_pk_bf16_f32 v144, v242, v243
	v_cvt_pk_bf16_f32 v145, v244, v245
	s_waitcnt lgkmcnt(6)
	v_mfma_f32_16x16x32_bf16 v[48:51], v[48:51], v[40:43], v[72:75]
	v_cvt_pk_bf16_f32 v146, v246, v247
	v_cvt_pk_bf16_f32 v147, v248, v249
	s_add_u32 s100, s62, 0x20000
	s_addc_u32 s101, s63, 0
	v_lshl_add_u64 v[160:161], s[62:63], 0, v[200:201]
	s_waitcnt lgkmcnt(4)
	v_mfma_f32_16x16x32_bf16 v[60:63], v[60:63], v[40:43], v[76:79]
	global_load_dwordx4 v[132:135], v[160:161], off nt
	global_load_dwordx4 v[140:143], v[160:161], off offset:1024 nt
	s_mov_b64 s[62:63], -1
	s_waitcnt lgkmcnt(2)
	v_mfma_f32_16x16x32_bf16 v[64:67], v[64:67], v[40:43], v[80:83]
	s_waitcnt lgkmcnt(0)
	v_mfma_f32_16x16x32_bf16 v[68:71], v[68:71], v[40:43], v[84:87]
	ds_read_b64_tr_b16 v[74:75], v190 offset:43648
	ds_read_b64_tr_b16 v[72:73], v190 offset:34944
	ds_read_b64_tr_b16 v[76:77], v190 offset:34976
	ds_read_b64_tr_b16 v[78:79], v190 offset:43680
	ds_read_b64_tr_b16 v[80:81], v190 offset:35008
	ds_read_b64_tr_b16 v[82:83], v190 offset:43712
	ds_read_b64_tr_b16 v[84:85], v190 offset:35040
	ds_read_b64_tr_b16 v[86:87], v190 offset:43744
	s_waitcnt lgkmcnt(6)
	v_mfma_f32_16x16x32_bf16 v[72:75], v[72:75], v[40:43], v[88:91]
	s_waitcnt lgkmcnt(4)
	v_mfma_f32_16x16x32_bf16 v[76:79], v[76:79], v[40:43], v[92:95]
	s_waitcnt lgkmcnt(2)
	v_mfma_f32_16x16x32_bf16 v[80:83], v[80:83], v[40:43], v[96:99]
	s_waitcnt lgkmcnt(0)
	v_mfma_f32_16x16x32_bf16 v[84:87], v[84:87], v[40:43], v[100:103]
	ds_read_b64_tr_b16 v[90:91], v190 offset:43776
	ds_read_b64_tr_b16 v[88:89], v190 offset:35072
	ds_read_b64_tr_b16 v[92:93], v190 offset:35104
	ds_read_b64_tr_b16 v[94:95], v190 offset:43808
	ds_read_b64_tr_b16 v[96:97], v190 offset:35136
	ds_read_b64_tr_b16 v[98:99], v190 offset:43840
	ds_read_b64_tr_b16 v[100:101], v190 offset:35168
	ds_read_b64_tr_b16 v[102:103], v190 offset:43872
	s_waitcnt lgkmcnt(6)
	v_mfma_f32_16x16x32_bf16 v[88:91], v[88:91], v[40:43], v[104:107]
	s_waitcnt lgkmcnt(4)
	v_mfma_f32_16x16x32_bf16 v[92:95], v[92:95], v[40:43], v[108:111]
	s_waitcnt lgkmcnt(2)
	v_mfma_f32_16x16x32_bf16 v[96:99], v[96:99], v[40:43], v[112:115]
	s_waitcnt lgkmcnt(0)
	v_mfma_f32_16x16x32_bf16 v[100:103], v[100:103], v[40:43], v[116:119]
	ds_read_b64_tr_b16 v[106:107], v190 offset:43904
	ds_read_b64_tr_b16 v[104:105], v190 offset:35200
	ds_read_b64_tr_b16 v[108:109], v190 offset:35232
	ds_read_b64_tr_b16 v[110:111], v190 offset:43936
	ds_read_b64_tr_b16 v[112:113], v190 offset:35264
	ds_read_b64_tr_b16 v[114:115], v190 offset:43968
	ds_read_b64_tr_b16 v[116:117], v190 offset:35296
	ds_read_b64_tr_b16 v[118:119], v190 offset:44000
	s_waitcnt lgkmcnt(6)
	v_mfma_f32_16x16x32_bf16 v[104:107], v[104:107], v[40:43], v[120:123]
	s_waitcnt lgkmcnt(4)
	v_mfma_f32_16x16x32_bf16 v[108:111], v[108:111], v[40:43], v[124:127]
	s_waitcnt lgkmcnt(2)
	v_mfma_f32_16x16x32_bf16 v[112:115], v[112:115], v[40:43], v[128:131]
	s_nop 0
	v_add_co_u32_e32 v124, vcc, s33, v160
	s_waitcnt lgkmcnt(0)
	v_mfma_f32_16x16x32_bf16 v[148:151], v[116:119], v[40:43], v[56:59]
	ds_read_b64_tr_b16 v[42:43], v190 offset:60928
	ds_read_b64_tr_b16 v[40:41], v190 offset:52224
	ds_read_b64_tr_b16 v[116:117], v190 offset:52288
	ds_read_b64_tr_b16 v[56:57], v190 offset:52256
	ds_read_b64_tr_b16 v[58:59], v190 offset:60960
	ds_read_b64_tr_b16 v[118:119], v190 offset:60992
	ds_read_b64_tr_b16 v[120:121], v190 offset:52320
	ds_read_b64_tr_b16 v[122:123], v190 offset:61024
	s_waitcnt lgkmcnt(6)
; #define LDS_BARRIER() asm volatile("s_waitcnt lgkmcnt(0)\n\ts_barrier" ::: "memory")
; #define MFMA16(a, b, c) __builtin_amdgcn_mfma_f32_16x16x32_bf16((a), (b), (c), 0, 0, 0)
; #define ATT_LSTORE(slot) do { _Pragma("unroll") for (int i_ = 0; i_ < 4; ++i_) { const int idx_ = tid + 512 * i_; *(LAS u32x4*)(lds + (slot) * ATT_SLOT + (idx_ >> 5) * 544 + (idx_ & 31) * 16) = st[i_]; } } while (0)
; #define ATT_LSTORE(c) do { _Pragma("unroll") for (int i_ = 0; i_ < 4; ++i_) *(LAS u32x4*)(lds + ((c) & 1) * ATT_SLOT + 16 * i_ * 544 + loff) = st[(c) & 1][i_]; } while (0)
; #define ATT_VREAD(n_) do { _Pragma("unroll") for (int d_ = 0; d_ < 4; ++d_) { LAS unsigned char* p_ = slot + (32 * ((n_) >> 2) + 4 * fq + (fr >> 2)) * 544 + (16 * (4 * ((n_) & 3) + d_) + 4 * (fr & 3)) * 2; Vf[d_] = tr_frag(p_, p_ + 16 * 544); } } while (0)
; __device__ __forceinline__ void attn_fused(Frame& F0, int layer) {
;     ...
; #pragma unroll
;                 for (int r = 0; r < 4; ++r) {
;                     const int m = 32 * c + 4 * w + r;
;                     const float p0 = __builtin_amdgcn_exp2f(sc[m] - mx0) * iv0, p1 = __builtin_amdgcn_exp2f(sc[256 + m] - mx1) * iv1;
;                     a0 += sv[2 * r] * p0; a1 += sv[2 * r + 1] * p1;
;                 }
;                 if (c < 7) FA_SLOAD(vp, c + 1);
;     ...
;             } else {
;                 {
;                     bf16x8 Vf[4];
;     ...
; #pragma unroll
;                     for (int n = 0; n < 8; ++n) {
;                         ATT_VREAD(n);
; #pragma unroll
;                         for (int d = 0; d < 4; ++d) { const int al = n >> 2, dt = 4 * (n & 3) + d; Oa[dt] = MFMA16(Vf[d], Pf[2 * (c - 4) + al], (c == 4 && al == 0) ? zero4 : Oa[dt]); }
;                         __builtin_amdgcn_sched_group_barrier(0x100, 8, 0); __builtin_amdgcn_sched_group_barrier(0x008, 4, 0);
;                     }
;     ...
;                 }
;             }
;             if (c < 7) ATT_LSTORE(c + 1);
;             LDS_BARRIER();
	v_mfma_f32_16x16x32_bf16 v[40:43], v[40:43], v[144:147], v[48:51]
	v_addc_co_u32_e32 v125, vcc, 0, v161, vcc
	v_add_co_u32_e32 v126, vcc, s70, v160
	s_waitcnt lgkmcnt(3)
	v_mfma_f32_16x16x32_bf16 v[48:51], v[56:59], v[144:147], v[60:63]
	v_addc_co_u32_e32 v127, vcc, 0, v161, vcc
	v_add_co_u32_e32 v160, vcc, s95, v160
	s_waitcnt lgkmcnt(2)
	v_mfma_f32_16x16x32_bf16 v[56:59], v[116:119], v[144:147], v[64:67]
	v_addc_co_u32_e32 v161, vcc, 0, v161, vcc
	global_load_dwordx4 v[136:139], v[126:127], off offset:-4096 nt
	s_waitcnt lgkmcnt(0)
	v_mfma_f32_16x16x32_bf16 v[60:63], v[120:123], v[144:147], v[68:71]
	ds_read_b64_tr_b16 v[66:67], v190 offset:61056
	ds_read_b64_tr_b16 v[64:65], v190 offset:52352
	ds_read_b64_tr_b16 v[116:117], v190 offset:52416
	ds_read_b64_tr_b16 v[68:69], v190 offset:52384
	ds_read_b64_tr_b16 v[70:71], v190 offset:61088
	ds_read_b64_tr_b16 v[118:119], v190 offset:61120
	ds_read_b64_tr_b16 v[120:121], v190 offset:52448
	ds_read_b64_tr_b16 v[122:123], v190 offset:61152
	s_waitcnt lgkmcnt(6)
	v_mfma_f32_16x16x32_bf16 v[64:67], v[64:67], v[144:147], v[72:75]
	global_load_dwordx4 v[128:131], v[124:125], off offset:1024 nt
	s_and_b64 vcc, exec, s[60:61]
	s_waitcnt lgkmcnt(3)
	v_mfma_f32_16x16x32_bf16 v[68:71], v[68:71], v[144:147], v[76:79]
	s_waitcnt lgkmcnt(2)
	v_mfma_f32_16x16x32_bf16 v[72:75], v[116:119], v[144:147], v[80:83]
	s_waitcnt lgkmcnt(0)
	v_mfma_f32_16x16x32_bf16 v[76:79], v[120:123], v[144:147], v[84:87]
	s_nop 0
	ds_read_b64_tr_b16 v[82:83], v190 offset:61184
	ds_read_b64_tr_b16 v[80:81], v190 offset:52480
	ds_read_b64_tr_b16 v[116:117], v190 offset:52544
	ds_read_b64_tr_b16 v[84:85], v190 offset:52512
	ds_read_b64_tr_b16 v[86:87], v190 offset:61216
	ds_read_b64_tr_b16 v[118:119], v190 offset:61248
	ds_read_b64_tr_b16 v[120:121], v190 offset:52576
	ds_read_b64_tr_b16 v[122:123], v190 offset:61280
	s_waitcnt lgkmcnt(6)
	v_mfma_f32_16x16x32_bf16 v[80:83], v[80:83], v[144:147], v[88:91]
	s_waitcnt lgkmcnt(3)
	v_mfma_f32_16x16x32_bf16 v[84:87], v[84:87], v[144:147], v[92:95]
	s_waitcnt lgkmcnt(2)
	v_mfma_f32_16x16x32_bf16 v[88:91], v[116:119], v[144:147], v[96:99]
	s_waitcnt lgkmcnt(0)
	v_mfma_f32_16x16x32_bf16 v[92:95], v[120:123], v[144:147], v[100:103]
	ds_read_b64_tr_b16 v[98:99], v190 offset:61312
	ds_read_b64_tr_b16 v[96:97], v190 offset:52608
	ds_read_b64_tr_b16 v[152:153], v190 offset:52672
	ds_read_b64_tr_b16 v[154:155], v190 offset:61376
	ds_read_b64_tr_b16 v[100:101], v190 offset:52640
	ds_read_b64_tr_b16 v[102:103], v190 offset:61344
	ds_read_b64_tr_b16 v[156:157], v190 offset:52704
	ds_read_b64_tr_b16 v[158:159], v190 offset:61408
	s_waitcnt lgkmcnt(6)
	v_mfma_f32_16x16x32_bf16 v[96:99], v[96:99], v[144:147], v[104:107]
	ds_write_b128 v191, v[8:11]
	ds_write_b128 v191, v[12:15] offset:8704
	s_waitcnt lgkmcnt(6)
	v_mfma_f32_16x16x32_bf16 v[104:107], v[152:155], v[144:147], v[112:115]
	ds_write_b128 v191, v[16:19] offset:17408
	ds_write_b128 v191, v[20:23] offset:26112
	s_waitcnt lgkmcnt(6)
	v_mfma_f32_16x16x32_bf16 v[100:103], v[100:103], v[144:147], v[108:111]
	s_bitset1_b32 m0, 12
	v_add_u32_e32 v114, 0x2000, v200
	v_add_u32_e32 v115, 0x2800, v200
	global_load_lds_dwordx4 v114, s[100:101] nt
	global_load_lds_dwordx4 v114, s[100:101] offset:1024 nt
	global_load_lds_dwordx4 v115, s[100:101] offset:2048 nt
	global_load_lds_dwordx4 v115, s[100:101] offset:3072 nt
	s_waitcnt lgkmcnt(0)
	s_barrier
	s_waitcnt lgkmcnt(4)
	v_mfma_f32_16x16x32_bf16 v[108:111], v[156:159], v[144:147], v[148:151]
	s_cbranch_vccz .LBB0_2108
	s_waitcnt vmcnt(4)
	v_add_u32_e32 v112, m0, v200
	v_and_b32_e32 v112, 0xffffefff, v112
	ds_read_b128 v[120:123], v112
	ds_read_b128 v[124:127], v112 offset:1024
	ds_read_b128 v[116:119], v112 offset:2048
	ds_read_b128 v[112:115], v112 offset:3072
	s_waitcnt lgkmcnt(0)
	v_mov_b32_e32 v12, s69
	ds_read_b128 v[8:11], v12 offset:1792
	ds_read_b128 v[12:15], v12 offset:768
	s_mov_b64 s[60:61], s[56:57]
	s_mov_b64 s[62:63], 0
	s_waitcnt lgkmcnt(1)
	v_sub_f32_e32 v8, v8, v193
	v_sub_f32_e32 v9, v9, v193
	v_exp_f32_e32 v8, v8
	v_exp_f32_e32 v9, v9
	v_sub_f32_e32 v10, v10, v193
	v_exp_f32_e32 v18, v10
	v_mul_f32_e32 v8, v182, v8
	v_mul_f32_e32 v10, v182, v9
	s_waitcnt vmcnt(6)
	v_pk_fma_f32 v[16:17], v[142:143], v[8:9], v[46:47] op_sel_hi:[1,0,1]
	v_pk_fma_f32 v[8:9], v[140:141], v[8:9], v[44:45] op_sel_hi:[1,0,1]
	s_waitcnt vmcnt(4)
	v_pk_fma_f32 v[16:17], v[130:131], v[10:11], v[16:17] op_sel_hi:[1,0,1]
	v_pk_fma_f32 v[8:9], v[128:129], v[10:11], v[8:9] op_sel_hi:[1,0,1]
	v_sub_f32_e32 v10, v11, v193
	v_exp_f32_e32 v11, v10
	v_mul_f32_e32 v10, v182, v18
	s_waitcnt lgkmcnt(0)
	v_sub_f32_e32 v12, v12, v192
	v_exp_f32_e32 v12, v12
	s_waitcnt vmcnt(4)
	v_pk_fma_f32 v[16:17], v[126:127], v[10:11], v[16:17] op_sel_hi:[1,0,1]
	v_pk_fma_f32 v[8:9], v[124:125], v[10:11], v[8:9] op_sel_hi:[1,0,1]
	v_mul_f32_e32 v18, v182, v11
	v_sub_f32_e32 v13, v13, v192
	s_waitcnt vmcnt(4)
	v_pk_fma_f32 v[10:11], v[114:115], v[18:19], v[16:17] op_sel_hi:[1,0,1]
	v_pk_fma_f32 v[8:9], v[112:113], v[18:19], v[8:9] op_sel_hi:[1,0,1]
	v_exp_f32_e32 v18, v13
	v_sub_f32_e32 v14, v14, v192
	v_exp_f32_e32 v14, v14
	v_sub_f32_e32 v15, v15, v192
	v_exp_f32_e32 v15, v15
	v_mul_f32_e32 v12, v169, v12
	v_pk_fma_f32 v[16:17], v[134:135], v[12:13], v[54:55] op_sel_hi:[1,0,1]
	v_pk_fma_f32 v[12:13], v[132:133], v[12:13], v[52:53] op_sel_hi:[1,0,1]
	v_mul_f32_e32 v18, v169, v18
	v_pk_fma_f32 v[16:17], v[138:139], v[18:19], v[16:17] op_sel_hi:[1,0,1]
	v_pk_fma_f32 v[12:13], v[136:137], v[18:19], v[12:13] op_sel_hi:[1,0,1]
	v_mul_f32_e32 v14, v169, v14
	v_pk_fma_f32 v[16:17], v[122:123], v[14:15], v[16:17] op_sel_hi:[1,0,1]
	v_pk_fma_f32 v[12:13], v[120:121], v[14:15], v[12:13] op_sel_hi:[1,0,1]
	v_mul_f32_e32 v18, v169, v15
	v_pk_fma_f32 v[14:15], v[118:119], v[18:19], v[16:17] op_sel_hi:[1,0,1]
	v_pk_fma_f32 v[12:13], v[116:117], v[18:19], v[12:13] op_sel_hi:[1,0,1]
; __device__ __forceinline__ float dot4(f32x4 a, f32x4 b) { return (a[0] * b[0] + a[1] * b[1]) + (a[2] * b[2] + a[3] * b[3]); }
; #define dpp_mov(v, ctrl, row_mask) __builtin_bit_cast(float, __builtin_amdgcn_update_dpp(0, __builtin_bit_cast(int, (float)(v)), (ctrl), (row_mask), 0xf, false))
; __device__ __forceinline__ float wave_sum_dpp(float x) {
;     x += dpp_mov(x, 0xB1, 0xf);
;     x += dpp_mov(x, 0x4E, 0xf);
;     x += dpp_mov(x, 0x141, 0xf);
;     x += dpp_mov(x, 0x140, 0xf);
;     x += dpp_mov(x, 0x142, 0xa);
;     x += dpp_mov(x, 0x143, 0xc);
;     return x;
; }
; __device__ __forceinline__ void attn_fused(Frame& F0, int layer) {
;     ...
;             if (ui == 0) {
; #pragma unroll
;                 for (int r = 0; r < 4; ++r) {
;                     const int m = 32 * c + 4 * w + r;
;                     const float d0 = wave_sum_dpp(dot4(sv[2 * r], q0)), d1 = wave_sum_dpp(dot4(sv[2 * r + 1], q1));
;                     if (lane == 63) { sc[m] = d0; sc[256 + m] = d1; }
;                 }
;                 if (c < 7) FA_SLOAD(kp, c + 1); else FA_SLOAD(vp, 0);
.LBB0_2108:
	s_andn2_b64 vcc, exec, s[62:63]
	s_cbranch_vccnz .LBB0_2118
	s_waitcnt vmcnt(4)
	v_add_u32_e32 v112, m0, v200
	v_and_b32_e32 v112, 0xffffefff, v112
	ds_read_b128 v[120:123], v112
	ds_read_b128 v[124:127], v112 offset:1024
	ds_read_b128 v[116:119], v112 offset:2048
	ds_read_b128 v[112:115], v112 offset:3072
	s_waitcnt lgkmcnt(0)
	s_waitcnt vmcnt(7)
	v_mul_f32_e32 v8, v1, v133
	v_mul_f32_e32 v9, v3, v135
	s_waitcnt vmcnt(6)
	v_mul_f32_e32 v10, v5, v141
	v_mul_f32_e32 v11, v7, v143
	v_fmac_f32_e32 v8, v0, v132
	v_fmac_f32_e32 v9, v2, v134
	v_fmac_f32_e32 v10, v4, v140
	v_fmac_f32_e32 v11, v6, v142
	v_add_f32_e32 v8, v8, v9
	v_add_f32_e32 v10, v10, v11
	v_mov_b32_e32 v9, v201
	v_add_f32_dpp v8, v8, v8 quad_perm:[1,0,3,2] row_mask:0xf bank_mask:0xf bound_ctrl:1
	v_add_f32_dpp v10, v10, v10 quad_perm:[1,0,3,2] row_mask:0xf bank_mask:0xf bound_ctrl:1
	v_mov_b32_e32 v11, v201
	v_add_f32_dpp v8, v8, v8 quad_perm:[2,3,0,1] row_mask:0xf bank_mask:0xf bound_ctrl:1
	v_add_f32_dpp v10, v10, v10 quad_perm:[2,3,0,1] row_mask:0xf bank_mask:0xf bound_ctrl:1
	s_nop 0
	v_add_f32_dpp v8, v8, v8 row_half_mirror row_mask:0xf bank_mask:0xf bound_ctrl:1
	v_add_f32_dpp v10, v10, v10 row_half_mirror row_mask:0xf bank_mask:0xf bound_ctrl:1
	s_nop 0
	v_add_f32_dpp v8, v8, v8 row_mirror row_mask:0xf bank_mask:0xf bound_ctrl:1
	v_add_f32_dpp v10, v10, v10 row_mirror row_mask:0xf bank_mask:0xf bound_ctrl:1
	s_nop 0
	v_mov_b32_dpp v9, v8 row_bcast:15 row_mask:0xa bank_mask:0xf
	v_mov_b32_dpp v11, v10 row_bcast:15 row_mask:0xa bank_mask:0xf
	v_add_f32_e32 v8, v8, v9
	v_mov_b32_e32 v9, v201
	v_add_f32_e32 v10, v10, v11
	v_mov_b32_e32 v11, v201
	v_mov_b32_dpp v9, v8 row_bcast:31 row_mask:0xc bank_mask:0xf
	s_nop 0
	v_mov_b32_dpp v11, v10 row_bcast:31 row_mask:0xc bank_mask:0xf
	s_and_saveexec_b64 s[60:61], s[4:5]
	v_add_f32_e32 v8, v8, v9
	v_add_f32_e32 v9, v10, v11
	v_mov_b32_e32 v10, s69
	ds_write2st64_b32 v10, v8, v9 offset0:3 offset1:7
	s_or_b64 exec, exec, s[60:61]
	s_waitcnt vmcnt(5)
	v_mul_f32_e32 v8, v1, v137
	v_mul_f32_e32 v9, v3, v139
	s_waitcnt vmcnt(4)
	v_mul_f32_e32 v10, v5, v129
	v_mul_f32_e32 v11, v7, v131
	v_fmac_f32_e32 v8, v0, v136
	v_fmac_f32_e32 v9, v2, v138
	v_fmac_f32_e32 v10, v4, v128
	v_fmac_f32_e32 v11, v6, v130
	v_add_f32_e32 v8, v8, v9
	v_add_f32_e32 v10, v10, v11
	v_mov_b32_e32 v9, v201
	v_add_f32_dpp v8, v8, v8 quad_perm:[1,0,3,2] row_mask:0xf bank_mask:0xf bound_ctrl:1
	v_add_f32_dpp v10, v10, v10 quad_perm:[1,0,3,2] row_mask:0xf bank_mask:0xf bound_ctrl:1
	v_mov_b32_e32 v11, v201
	v_add_f32_dpp v8, v8, v8 quad_perm:[2,3,0,1] row_mask:0xf bank_mask:0xf bound_ctrl:1
	v_add_f32_dpp v10, v10, v10 quad_perm:[2,3,0,1] row_mask:0xf bank_mask:0xf bound_ctrl:1
	s_nop 0
	v_add_f32_dpp v8, v8, v8 row_half_mirror row_mask:0xf bank_mask:0xf bound_ctrl:1
	v_add_f32_dpp v10, v10, v10 row_half_mirror row_mask:0xf bank_mask:0xf bound_ctrl:1
	s_nop 0
	v_add_f32_dpp v8, v8, v8 row_mirror row_mask:0xf bank_mask:0xf bound_ctrl:1
	v_add_f32_dpp v10, v10, v10 row_mirror row_mask:0xf bank_mask:0xf bound_ctrl:1
	s_nop 0
	v_mov_b32_dpp v9, v8 row_bcast:15 row_mask:0xa bank_mask:0xf
	v_mov_b32_dpp v11, v10 row_bcast:15 row_mask:0xa bank_mask:0xf
	v_add_f32_e32 v8, v8, v9
	v_mov_b32_e32 v9, v201
	v_add_f32_e32 v10, v10, v11
	v_mov_b32_e32 v11, v201
	v_mov_b32_dpp v9, v8 row_bcast:31 row_mask:0xc bank_mask:0xf
	s_nop 0
	v_mov_b32_dpp v11, v10 row_bcast:31 row_mask:0xc bank_mask:0xf
	s_and_saveexec_b64 s[60:61], s[4:5]
	v_add_f32_e32 v8, v8, v9
	v_add_f32_e32 v9, v10, v11
	v_add_u32_e64 v10, 4, s69
	ds_write2st64_b32 v10, v8, v9 offset0:3 offset1:7
	s_or_b64 exec, exec, s[60:61]
	s_waitcnt vmcnt(4)
	v_mul_f32_e32 v8, v1, v121
	v_mul_f32_e32 v9, v3, v123
	s_waitcnt vmcnt(4)
	v_mul_f32_e32 v10, v5, v125
	v_mul_f32_e32 v11, v7, v127
	v_fmac_f32_e32 v8, v0, v120
	v_fmac_f32_e32 v9, v2, v122
	v_fmac_f32_e32 v10, v4, v124
	v_fmac_f32_e32 v11, v6, v126
	v_add_f32_e32 v8, v8, v9
	v_add_f32_e32 v10, v10, v11
	v_mov_b32_e32 v9, v201
	v_add_f32_dpp v8, v8, v8 quad_perm:[1,0,3,2] row_mask:0xf bank_mask:0xf bound_ctrl:1
	v_add_f32_dpp v10, v10, v10 quad_perm:[1,0,3,2] row_mask:0xf bank_mask:0xf bound_ctrl:1
	v_mov_b32_e32 v11, v201
	v_add_f32_dpp v8, v8, v8 quad_perm:[2,3,0,1] row_mask:0xf bank_mask:0xf bound_ctrl:1
	v_add_f32_dpp v10, v10, v10 quad_perm:[2,3,0,1] row_mask:0xf bank_mask:0xf bound_ctrl:1
	s_nop 0
	v_add_f32_dpp v8, v8, v8 row_half_mirror row_mask:0xf bank_mask:0xf bound_ctrl:1
	v_add_f32_dpp v10, v10, v10 row_half_mirror row_mask:0xf bank_mask:0xf bound_ctrl:1
	s_nop 0
	v_add_f32_dpp v8, v8, v8 row_mirror row_mask:0xf bank_mask:0xf bound_ctrl:1
	v_add_f32_dpp v10, v10, v10 row_mirror row_mask:0xf bank_mask:0xf bound_ctrl:1
	s_nop 0
	v_mov_b32_dpp v9, v8 row_bcast:15 row_mask:0xa bank_mask:0xf
	v_mov_b32_dpp v11, v10 row_bcast:15 row_mask:0xa bank_mask:0xf
	v_add_f32_e32 v8, v8, v9
	v_mov_b32_e32 v9, v201
	v_add_f32_e32 v10, v10, v11
	v_mov_b32_e32 v11, v201
	v_mov_b32_dpp v9, v8 row_bcast:31 row_mask:0xc bank_mask:0xf
	s_nop 0
	v_mov_b32_dpp v11, v10 row_bcast:31 row_mask:0xc bank_mask:0xf
	s_and_saveexec_b64 s[60:61], s[4:5]
	v_add_f32_e32 v8, v8, v9
	v_add_f32_e32 v9, v10, v11
	v_add_u32_e64 v10, 8, s69
	ds_write2st64_b32 v10, v8, v9 offset0:3 offset1:7
	s_or_b64 exec, exec, s[60:61]
	v_mul_f32_e32 v8, v1, v117
	v_mul_f32_e32 v9, v3, v119
	s_waitcnt vmcnt(4)
; #define MFMA16(a, b, c) __builtin_amdgcn_mfma_f32_16x16x32_bf16((a), (b), (c), 0, 0, 0)
; #define ATT_VREAD(n_) do { _Pragma("unroll") for (int d_ = 0; d_ < 4; ++d_) { LAS unsigned char* p_ = slot + (32 * ((n_) >> 2) + 4 * fq + (fr >> 2)) * 544 + (16 * (4 * ((n_) & 3) + d_) + 4 * (fr & 3)) * 2; Vf[d_] = tr_frag(p_, p_ + 16 * 544); } } while (0)
; __device__ __forceinline__ void attn_fused(Frame& F0, int layer) {
;     ...
;             } else {
;                 {
;                     bf16x8 Vf[4];
;     ...
; #pragma unroll
;                     for (int n = 0; n < 8; ++n) {
;                         ATT_VREAD(n);
; #pragma unroll
;                         for (int d = 0; d < 4; ++d) { const int al = n >> 2, dt = 4 * (n & 3) + d; Oa[dt] = MFMA16(Vf[d], Pf[2 * (c - 4) + al], (c == 4 && al == 0) ? zero4 : Oa[dt]); }
;                         __builtin_amdgcn_sched_group_barrier(0x100, 8, 0); __builtin_amdgcn_sched_group_barrier(0x008, 4, 0);
	v_mul_f32_e32 v10, v5, v113
	v_mul_f32_e32 v11, v7, v115
	v_fmac_f32_e32 v8, v0, v116
	v_fmac_f32_e32 v9, v2, v118
	v_fmac_f32_e32 v10, v4, v112
	v_fmac_f32_e32 v11, v6, v114
	v_add_f32_e32 v8, v8, v9
	v_add_f32_e32 v10, v10, v11
	v_mov_b32_e32 v9, v201
	v_add_f32_dpp v8, v8, v8 quad_perm:[1,0,3,2] row_mask:0xf bank_mask:0xf bound_ctrl:1
	v_add_f32_dpp v10, v10, v10 quad_perm:[1,0,3,2] row_mask:0xf bank_mask:0xf bound_ctrl:1
	v_mov_b32_e32 v11, v201
	v_add_f32_dpp v8, v8, v8 quad_perm:[2,3,0,1] row_mask:0xf bank_mask:0xf bound_ctrl:1
	v_add_f32_dpp v10, v10, v10 quad_perm:[2,3,0,1] row_mask:0xf bank_mask:0xf bound_ctrl:1
	s_nop 0
	v_add_f32_dpp v8, v8, v8 row_half_mirror row_mask:0xf bank_mask:0xf bound_ctrl:1
	v_add_f32_dpp v10, v10, v10 row_half_mirror row_mask:0xf bank_mask:0xf bound_ctrl:1
	s_nop 0
	v_add_f32_dpp v8, v8, v8 row_mirror row_mask:0xf bank_mask:0xf bound_ctrl:1
	v_add_f32_dpp v10, v10, v10 row_mirror row_mask:0xf bank_mask:0xf bound_ctrl:1
	s_nop 0
	v_mov_b32_dpp v9, v8 row_bcast:15 row_mask:0xa bank_mask:0xf
	v_mov_b32_dpp v11, v10 row_bcast:15 row_mask:0xa bank_mask:0xf
	v_add_f32_e32 v8, v8, v9
	v_mov_b32_e32 v9, v201
	v_add_f32_e32 v10, v10, v11
	v_mov_b32_e32 v11, v201
	v_mov_b32_dpp v9, v8 row_bcast:31 row_mask:0xc bank_mask:0xf
	s_nop 0
	v_mov_b32_dpp v11, v10 row_bcast:31 row_mask:0xc bank_mask:0xf
	s_and_saveexec_b64 s[60:61], s[4:5]
	v_add_f32_e32 v8, v8, v9
	v_add_f32_e32 v9, v10, v11
	v_add_u32_e64 v10, 12, s69
	ds_write2st64_b32 v10, v8, v9 offset0:3 offset1:7
	s_or_b64 exec, exec, s[60:61]
	v_mov_b64_e32 v[12:13], v[52:53]
	v_mov_b64_e32 v[8:9], v[44:45]
	s_mov_b64 s[60:61], s[58:59]
	v_mov_b64_e32 v[14:15], v[54:55]
	v_mov_b64_e32 v[10:11], v[46:47]
.LBB0_2118:
	ds_read_b64_tr_b16 v[22:23], v190 offset:8704
	ds_read_b64_tr_b16 v[20:21], v190
	ds_read_b64_tr_b16 v[44:45], v190 offset:32
	ds_read_b64_tr_b16 v[46:47], v190 offset:8736
	ds_read_b64_tr_b16 v[52:53], v190 offset:64
	ds_read_b64_tr_b16 v[54:55], v190 offset:8768
	s_waitcnt vmcnt(4)
	ds_read_b64_tr_b16 v[112:113], v190 offset:96
	ds_read_b64_tr_b16 v[114:115], v190 offset:8800
	v_cvt_pk_bf16_f32 v16, v238, v239
	v_cvt_pk_bf16_f32 v17, v240, v241
	v_cvt_pk_bf16_f32 v18, v222, v223
	v_cvt_pk_bf16_f32 v19, v225, v230
	v_cvt_pk_bf16_f32 v136, v220, v221
	v_cvt_pk_bf16_f32 v137, v224, v226
	s_waitcnt lgkmcnt(6)
	v_mfma_f32_16x16x32_bf16 v[20:23], v[20:23], v[16:19], v[40:43]
	v_cvt_pk_bf16_f32 v138, v228, v232
	v_cvt_pk_bf16_f32 v139, v236, v237
	s_mov_b64 s[100:101], s[60:61]
	v_lshl_add_u64 v[144:145], s[60:61], 0, v[200:201]
	s_waitcnt lgkmcnt(4)
	v_mfma_f32_16x16x32_bf16 v[40:43], v[44:47], v[16:19], v[48:51]
	s_mov_b64 s[60:61], -1
	s_waitcnt lgkmcnt(2)
	v_mfma_f32_16x16x32_bf16 v[44:47], v[52:55], v[16:19], v[56:59]
	s_waitcnt lgkmcnt(0)
	v_mfma_f32_16x16x32_bf16 v[48:51], v[112:115], v[16:19], v[60:63]
	ds_read_b64_tr_b16 v[54:55], v190 offset:8832
	ds_read_b64_tr_b16 v[52:53], v190 offset:128
	ds_read_b64_tr_b16 v[56:57], v190 offset:160
	ds_read_b64_tr_b16 v[58:59], v190 offset:8864
	ds_read_b64_tr_b16 v[60:61], v190 offset:192
	ds_read_b64_tr_b16 v[62:63], v190 offset:8896
	ds_read_b64_tr_b16 v[112:113], v190 offset:224
	ds_read_b64_tr_b16 v[114:115], v190 offset:8928
	s_waitcnt lgkmcnt(6)
	v_mfma_f32_16x16x32_bf16 v[52:55], v[52:55], v[16:19], v[64:67]
	s_waitcnt lgkmcnt(4)
	v_mfma_f32_16x16x32_bf16 v[56:59], v[56:59], v[16:19], v[68:71]
	s_waitcnt lgkmcnt(2)
	v_mfma_f32_16x16x32_bf16 v[60:63], v[60:63], v[16:19], v[72:75]
	s_waitcnt lgkmcnt(0)
	v_mfma_f32_16x16x32_bf16 v[64:67], v[112:115], v[16:19], v[76:79]
	ds_read_b64_tr_b16 v[70:71], v190 offset:8960
	ds_read_b64_tr_b16 v[68:69], v190 offset:256
	ds_read_b64_tr_b16 v[72:73], v190 offset:288
	ds_read_b64_tr_b16 v[74:75], v190 offset:8992
	ds_read_b64_tr_b16 v[76:77], v190 offset:320
	ds_read_b64_tr_b16 v[78:79], v190 offset:9024
	ds_read_b64_tr_b16 v[112:113], v190 offset:352
	ds_read_b64_tr_b16 v[114:115], v190 offset:9056
	s_waitcnt lgkmcnt(6)
	v_mfma_f32_16x16x32_bf16 v[116:119], v[68:71], v[16:19], v[80:83]
	s_waitcnt lgkmcnt(4)
	v_mfma_f32_16x16x32_bf16 v[72:75], v[72:75], v[16:19], v[84:87]
	s_waitcnt lgkmcnt(2)
	v_mfma_f32_16x16x32_bf16 v[76:79], v[76:79], v[16:19], v[88:91]
	s_waitcnt lgkmcnt(0)
	v_mfma_f32_16x16x32_bf16 v[120:123], v[112:115], v[16:19], v[92:95]
	ds_read_b64_tr_b16 v[70:71], v190 offset:9088
	ds_read_b64_tr_b16 v[68:69], v190 offset:384
	ds_read_b64_tr_b16 v[80:81], v190 offset:416
	ds_read_b64_tr_b16 v[82:83], v190 offset:9120
	ds_read_b64_tr_b16 v[84:85], v190 offset:448
	ds_read_b64_tr_b16 v[86:87], v190 offset:9152
	ds_read_b64_tr_b16 v[88:89], v190 offset:480
	ds_read_b64_tr_b16 v[90:91], v190 offset:9184
	s_waitcnt lgkmcnt(6)
	v_mfma_f32_16x16x32_bf16 v[124:127], v[68:71], v[16:19], v[96:99]
	s_waitcnt lgkmcnt(4)
	v_mfma_f32_16x16x32_bf16 v[128:131], v[80:83], v[16:19], v[100:103]
	s_waitcnt lgkmcnt(2)
	v_mfma_f32_16x16x32_bf16 v[132:135], v[84:87], v[16:19], v[104:107]
	s_waitcnt lgkmcnt(0)
	v_mfma_f32_16x16x32_bf16 v[140:143], v[88:91], v[16:19], v[108:111]
	ds_read_b64_tr_b16 v[18:19], v190 offset:26112
	ds_read_b64_tr_b16 v[16:17], v190 offset:17408
	ds_read_b64_tr_b16 v[68:69], v190 offset:17440
	ds_read_b64_tr_b16 v[70:71], v190 offset:26144
	ds_read_b64_tr_b16 v[80:81], v190 offset:17472
	ds_read_b64_tr_b16 v[82:83], v190 offset:26176
	ds_read_b64_tr_b16 v[84:85], v190 offset:17504
	ds_read_b64_tr_b16 v[86:87], v190 offset:26208
	s_waitcnt lgkmcnt(6)
	v_mfma_f32_16x16x32_bf16 v[16:19], v[16:19], v[136:139], v[20:23]
	s_waitcnt lgkmcnt(4)
	v_mfma_f32_16x16x32_bf16 v[20:23], v[68:71], v[136:139], v[40:43]
	s_waitcnt lgkmcnt(2)
; #define LDS_BARRIER() asm volatile("s_waitcnt lgkmcnt(0)\n\ts_barrier" ::: "memory")
; #define MFMA16(a, b, c) __builtin_amdgcn_mfma_f32_16x16x32_bf16((a), (b), (c), 0, 0, 0)
; #define ATT_LSTORE(slot) do { _Pragma("unroll") for (int i_ = 0; i_ < 4; ++i_) { const int idx_ = tid + 512 * i_; *(LAS u32x4*)(lds + (slot) * ATT_SLOT + (idx_ >> 5) * 544 + (idx_ & 31) * 16) = st[i_]; } } while (0)
; #define ATT_LSTORE(c) do { _Pragma("unroll") for (int i_ = 0; i_ < 4; ++i_) *(LAS u32x4*)(lds + ((c) & 1) * ATT_SLOT + 16 * i_ * 544 + loff) = st[(c) & 1][i_]; } while (0)
; #define ATT_VREAD(n_) do { _Pragma("unroll") for (int d_ = 0; d_ < 4; ++d_) { LAS unsigned char* p_ = slot + (32 * ((n_) >> 2) + 4 * fq + (fr >> 2)) * 544 + (16 * (4 * ((n_) & 3) + d_) + 4 * (fr & 3)) * 2; Vf[d_] = tr_frag(p_, p_ + 16 * 544); } } while (0)
; __device__ __forceinline__ void attn_fused(Frame& F0, int layer) {
;     ...
; #pragma unroll
;                 for (int r = 0; r < 4; ++r) {
;                     const int m = 32 * c + 4 * w + r;
;                     const float p0 = __builtin_amdgcn_exp2f(sc[m] - mx0) * iv0, p1 = __builtin_amdgcn_exp2f(sc[256 + m] - mx1) * iv1;
;                     a0 += sv[2 * r] * p0; a1 += sv[2 * r + 1] * p1;
;                 }
;                 if (c < 7) FA_SLOAD(vp, c + 1);
;     ...
;             } else {
;                 {
;                     bf16x8 Vf[4];
;     ...
; #pragma unroll
;                     for (int n = 0; n < 8; ++n) {
;                         ATT_VREAD(n);
; #pragma unroll
;                         for (int d = 0; d < 4; ++d) { const int al = n >> 2, dt = 4 * (n & 3) + d; Oa[dt] = MFMA16(Vf[d], Pf[2 * (c - 4) + al], (c == 4 && al == 0) ? zero4 : Oa[dt]); }
;                         __builtin_amdgcn_sched_group_barrier(0x100, 8, 0); __builtin_amdgcn_sched_group_barrier(0x008, 4, 0);
;                     }
;     ...
;                 }
;             }
;             if (c < 7) ATT_LSTORE(c + 1);
;             LDS_BARRIER();
	v_mfma_f32_16x16x32_bf16 v[80:83], v[80:83], v[136:139], v[44:47]
	s_waitcnt lgkmcnt(0)
	v_mfma_f32_16x16x32_bf16 v[84:87], v[84:87], v[136:139], v[48:51]
	ds_read_b64_tr_b16 v[42:43], v190 offset:26240
	ds_read_b64_tr_b16 v[40:41], v190 offset:17536
	ds_read_b64_tr_b16 v[44:45], v190 offset:17568
	ds_read_b64_tr_b16 v[46:47], v190 offset:26272
	ds_read_b64_tr_b16 v[48:49], v190 offset:17600
	ds_read_b64_tr_b16 v[50:51], v190 offset:26304
	ds_read_b64_tr_b16 v[68:69], v190 offset:17632
	ds_read_b64_tr_b16 v[70:71], v190 offset:26336
	s_waitcnt lgkmcnt(6)
	v_mfma_f32_16x16x32_bf16 v[88:91], v[40:43], v[136:139], v[52:55]
	s_waitcnt lgkmcnt(4)
	v_mfma_f32_16x16x32_bf16 v[92:95], v[44:47], v[136:139], v[56:59]
	s_waitcnt lgkmcnt(2)
	v_mfma_f32_16x16x32_bf16 v[96:99], v[48:51], v[136:139], v[60:63]
	s_nop 0
	v_add_co_u32_e32 v56, vcc, s33, v144
	s_waitcnt lgkmcnt(0)
	v_mfma_f32_16x16x32_bf16 v[100:103], v[68:71], v[136:139], v[64:67]
	ds_read_b64_tr_b16 v[42:43], v190 offset:26368
	ds_read_b64_tr_b16 v[40:41], v190 offset:17664
	ds_read_b64_tr_b16 v[44:45], v190 offset:17696
	ds_read_b64_tr_b16 v[46:47], v190 offset:26400
	ds_read_b64_tr_b16 v[48:49], v190 offset:17728
	ds_read_b64_tr_b16 v[50:51], v190 offset:26432
	ds_read_b64_tr_b16 v[52:53], v190 offset:17760
	ds_read_b64_tr_b16 v[54:55], v190 offset:26464
	s_waitcnt lgkmcnt(6)
	v_mfma_f32_16x16x32_bf16 v[104:107], v[40:43], v[136:139], v[116:119]
	v_addc_co_u32_e32 v57, vcc, 0, v145, vcc
	v_add_co_u32_e32 v146, vcc, s70, v144
	s_waitcnt lgkmcnt(4)
	v_mfma_f32_16x16x32_bf16 v[108:111], v[44:47], v[136:139], v[72:75]
	v_addc_co_u32_e32 v147, vcc, 0, v145, vcc
	global_load_dwordx4 v[68:71], v[144:145], off nt
	s_waitcnt lgkmcnt(2)
	v_mfma_f32_16x16x32_bf16 v[112:115], v[48:51], v[136:139], v[76:79]
	global_load_dwordx4 v[64:67], v[144:145], off offset:1024 nt
	global_load_dwordx4 v[60:63], v[146:147], off offset:-4096 nt
	s_waitcnt lgkmcnt(0)
	v_mfma_f32_16x16x32_bf16 v[116:119], v[52:55], v[136:139], v[120:123]
	ds_read_b64_tr_b16 v[42:43], v190 offset:26496
	ds_read_b64_tr_b16 v[40:41], v190 offset:17792
	ds_read_b64_tr_b16 v[44:45], v190 offset:17824
	ds_read_b64_tr_b16 v[46:47], v190 offset:26528
	ds_read_b64_tr_b16 v[72:73], v190 offset:17856
	ds_read_b64_tr_b16 v[74:75], v190 offset:26560
	ds_read_b64_tr_b16 v[76:77], v190 offset:17888
	ds_read_b64_tr_b16 v[78:79], v190 offset:26592
	s_waitcnt lgkmcnt(6)
	v_mfma_f32_16x16x32_bf16 v[120:123], v[40:43], v[136:139], v[124:127]
	v_add_co_u32_e32 v40, vcc, s95, v144
	global_load_dwordx4 v[56:59], v[56:57], off offset:1024 nt
	s_nop 0
	v_addc_co_u32_e32 v41, vcc, 0, v145, vcc
	s_waitcnt lgkmcnt(4)
	v_mfma_f32_16x16x32_bf16 v[124:127], v[44:47], v[136:139], v[128:131]
	ds_write_b128 v191, v[24:27] offset:34816
	s_bitset0_b32 m0, 12
	v_add_u32_e32 v42, 0x2000, v200
	v_add_u32_e32 v43, 0x2800, v200
	global_load_lds_dwordx4 v42, s[100:101] nt
	global_load_lds_dwordx4 v42, s[100:101] offset:1024 nt
	global_load_lds_dwordx4 v43, s[100:101] offset:2048 nt
	global_load_lds_dwordx4 v43, s[100:101] offset:3072 nt
	s_waitcnt lgkmcnt(3)
	v_mfma_f32_16x16x32_bf16 v[128:131], v[72:75], v[136:139], v[132:135]
	ds_write_b128 v191, v[28:31] offset:43520
	ds_write_b128 v191, v[32:35] offset:52224
	ds_write_b128 v191, v[36:39] offset:60928
	s_waitcnt lgkmcnt(4)
	v_mfma_f32_16x16x32_bf16 v[132:135], v[76:79], v[136:139], v[140:143]
	s_waitcnt lgkmcnt(0)
	s_barrier
	s_and_b64 vcc, exec, s[6:7]
	s_cbranch_vccnz .LBB0_2120
	s_waitcnt vmcnt(4)
	v_add_u32_e32 v40, m0, v200
	v_and_b32_e32 v40, 0xffffefff, v40
	ds_read_b128 v[52:55], v40 offset:4096
	ds_read_b128 v[48:51], v40 offset:5120
	ds_read_b128 v[44:47], v40 offset:6144
	ds_read_b128 v[40:43], v40 offset:7168
	s_waitcnt lgkmcnt(0)
	v_mov_b32_e32 v28, s69
	ds_read_b128 v[24:27], v28 offset:896
	ds_read_b128 v[28:31], v28 offset:1920
	s_mov_b64 s[60:61], 0
	s_waitcnt lgkmcnt(1)
	v_sub_f32_e32 v24, v24, v192
	v_exp_f32_e32 v24, v24
	v_sub_f32_e32 v25, v25, v192
	v_exp_f32_e32 v36, v25
	s_waitcnt lgkmcnt(0)
	v_sub_f32_e32 v29, v29, v193
	v_sub_f32_e32 v26, v26, v192
	v_exp_f32_e32 v37, v29
	v_exp_f32_e32 v26, v26
	v_mul_f32_e32 v24, v169, v24
	v_sub_f32_e32 v28, v28, v193
	s_waitcnt vmcnt(7)
	v_pk_fma_f32 v[32:33], v[70:71], v[24:25], v[14:15] op_sel_hi:[1,0,1]
	v_pk_fma_f32 v[24:25], v[68:69], v[24:25], v[12:13] op_sel_hi:[1,0,1]
	v_mul_f32_e32 v36, v169, v36
	v_exp_f32_e32 v28, v28
	s_waitcnt vmcnt(5)
	v_pk_fma_f32 v[32:33], v[62:63], v[36:37], v[32:33] op_sel_hi:[1,0,1]
	v_pk_fma_f32 v[24:25], v[60:61], v[36:37], v[24:25] op_sel_hi:[1,0,1]
	v_mul_f32_e32 v26, v169, v26
	v_sub_f32_e32 v30, v30, v193
	s_waitcnt vmcnt(4)
	v_pk_fma_f32 v[32:33], v[54:55], v[26:27], v[32:33] op_sel_hi:[1,0,1]
	v_pk_fma_f32 v[24:25], v[52:53], v[26:27], v[24:25] op_sel_hi:[1,0,1]
	v_sub_f32_e32 v26, v27, v192
	v_exp_f32_e32 v30, v30
	v_exp_f32_e32 v36, v26
	v_sub_f32_e32 v26, v31, v193
	v_exp_f32_e32 v31, v26
	v_mul_f32_e32 v28, v182, v28
	v_pk_fma_f32 v[34:35], v[66:67], v[28:29], v[10:11] op_sel_hi:[1,0,1]
	v_pk_fma_f32 v[28:29], v[64:65], v[28:29], v[8:9] op_sel_hi:[1,0,1]
	v_mul_f32_e32 v38, v182, v37
	v_pk_fma_f32 v[34:35], v[58:59], v[38:39], v[34:35] op_sel_hi:[1,0,1]
	v_pk_fma_f32 v[28:29], v[56:57], v[38:39], v[28:29] op_sel_hi:[1,0,1]
	v_mul_f32_e32 v30, v182, v30
	v_pk_fma_f32 v[26:27], v[50:51], v[30:31], v[34:35] op_sel_hi:[1,0,1]
	v_pk_fma_f32 v[28:29], v[48:49], v[30:31], v[28:29] op_sel_hi:[1,0,1]
	v_mul_f32_e32 v30, v169, v36
	v_mul_f32_e32 v34, v182, v31
	s_waitcnt vmcnt(4)
	v_pk_fma_f32 v[74:75], v[46:47], v[30:31], v[32:33] op_sel_hi:[1,0,1]
	v_pk_fma_f32 v[72:73], v[44:45], v[30:31], v[24:25] op_sel_hi:[1,0,1]
	s_waitcnt vmcnt(4)
	v_pk_fma_f32 v[78:79], v[42:43], v[34:35], v[26:27] op_sel_hi:[1,0,1]
	v_pk_fma_f32 v[76:77], v[40:41], v[34:35], v[28:29] op_sel_hi:[1,0,1]
; __device__ __forceinline__ float dot4(f32x4 a, f32x4 b) { return (a[0] * b[0] + a[1] * b[1]) + (a[2] * b[2] + a[3] * b[3]); }
; #define dpp_mov(v, ctrl, row_mask) __builtin_bit_cast(float, __builtin_amdgcn_update_dpp(0, __builtin_bit_cast(int, (float)(v)), (ctrl), (row_mask), 0xf, false))
; __device__ __forceinline__ float wave_sum_dpp(float x) {
;     x += dpp_mov(x, 0xB1, 0xf);
;     x += dpp_mov(x, 0x4E, 0xf);
;     x += dpp_mov(x, 0x141, 0xf);
;     x += dpp_mov(x, 0x140, 0xf);
;     x += dpp_mov(x, 0x142, 0xa);
;     x += dpp_mov(x, 0x143, 0xc);
;     return x;
; }
; __device__ __forceinline__ void attn_fused(Frame& F0, int layer) {
;     ...
;             if (ui == 0) {
; #pragma unroll
;                 for (int r = 0; r < 4; ++r) {
;                     const int m = 32 * c + 4 * w + r;
;                     const float d0 = wave_sum_dpp(dot4(sv[2 * r], q0)), d1 = wave_sum_dpp(dot4(sv[2 * r + 1], q1));
;                     if (lane == 63) { sc[m] = d0; sc[256 + m] = d1; }
;                 }
;                 if (c < 7) FA_SLOAD(kp, c + 1); else FA_SLOAD(vp, 0);
.LBB0_2120:
	s_andn2_b64 vcc, exec, s[60:61]
	s_cbranch_vccnz .LBB0_2031
	s_waitcnt vmcnt(4)
	v_add_u32_e32 v40, m0, v200
	v_and_b32_e32 v40, 0xffffefff, v40
	ds_read_b128 v[52:55], v40 offset:4096
	ds_read_b128 v[48:51], v40 offset:5120
	ds_read_b128 v[44:47], v40 offset:6144
	ds_read_b128 v[40:43], v40 offset:7168
	s_waitcnt lgkmcnt(0)
	s_waitcnt vmcnt(7)
	v_mul_f32_e32 v24, v1, v69
	v_mul_f32_e32 v25, v3, v71
	s_waitcnt vmcnt(6)
	v_mul_f32_e32 v26, v5, v65
	v_mul_f32_e32 v27, v7, v67
	v_fmac_f32_e32 v24, v0, v68
	v_fmac_f32_e32 v25, v2, v70
	v_fmac_f32_e32 v26, v4, v64
	v_fmac_f32_e32 v27, v6, v66
	v_add_f32_e32 v24, v24, v25
	v_add_f32_e32 v26, v26, v27
	v_mov_b32_e32 v25, v201
	v_add_f32_dpp v24, v24, v24 quad_perm:[1,0,3,2] row_mask:0xf bank_mask:0xf bound_ctrl:1
	v_add_f32_dpp v26, v26, v26 quad_perm:[1,0,3,2] row_mask:0xf bank_mask:0xf bound_ctrl:1
	v_mov_b32_e32 v27, v201
	v_add_f32_dpp v24, v24, v24 quad_perm:[2,3,0,1] row_mask:0xf bank_mask:0xf bound_ctrl:1
	v_add_f32_dpp v26, v26, v26 quad_perm:[2,3,0,1] row_mask:0xf bank_mask:0xf bound_ctrl:1
	s_nop 0
	v_add_f32_dpp v24, v24, v24 row_half_mirror row_mask:0xf bank_mask:0xf bound_ctrl:1
	v_add_f32_dpp v26, v26, v26 row_half_mirror row_mask:0xf bank_mask:0xf bound_ctrl:1
	s_nop 0
	v_add_f32_dpp v24, v24, v24 row_mirror row_mask:0xf bank_mask:0xf bound_ctrl:1
	v_add_f32_dpp v26, v26, v26 row_mirror row_mask:0xf bank_mask:0xf bound_ctrl:1
	s_nop 0
	v_mov_b32_dpp v25, v24 row_bcast:15 row_mask:0xa bank_mask:0xf
	v_mov_b32_dpp v27, v26 row_bcast:15 row_mask:0xa bank_mask:0xf
	v_add_f32_e32 v24, v24, v25
	v_mov_b32_e32 v25, v201
	v_add_f32_e32 v26, v26, v27
	v_mov_b32_e32 v27, v201
	v_mov_b32_dpp v25, v24 row_bcast:31 row_mask:0xc bank_mask:0xf
	s_nop 0
	v_mov_b32_dpp v27, v26 row_bcast:31 row_mask:0xc bank_mask:0xf
	s_and_saveexec_b64 s[60:61], s[4:5]
	v_add_f32_e32 v24, v24, v25
	v_add_f32_e32 v25, v26, v27
	v_mov_b32_e32 v26, s69
	v_add_u32_e32 v26, 0x80, v26
	ds_write2st64_b32 v26, v24, v25 offset0:3 offset1:7
	s_or_b64 exec, exec, s[60:61]
	s_waitcnt vmcnt(5)
	v_mul_f32_e32 v24, v1, v61
	v_mul_f32_e32 v25, v3, v63
	s_waitcnt vmcnt(4)
	v_mul_f32_e32 v26, v5, v57
	v_mul_f32_e32 v27, v7, v59
	v_fmac_f32_e32 v24, v0, v60
	v_fmac_f32_e32 v25, v2, v62
	v_fmac_f32_e32 v26, v4, v56
	v_fmac_f32_e32 v27, v6, v58
	v_add_f32_e32 v24, v24, v25
	v_add_f32_e32 v26, v26, v27
	v_mov_b32_e32 v25, v201
	v_add_f32_dpp v24, v24, v24 quad_perm:[1,0,3,2] row_mask:0xf bank_mask:0xf bound_ctrl:1
	v_add_f32_dpp v26, v26, v26 quad_perm:[1,0,3,2] row_mask:0xf bank_mask:0xf bound_ctrl:1
	v_mov_b32_e32 v27, v201
	v_add_f32_dpp v24, v24, v24 quad_perm:[2,3,0,1] row_mask:0xf bank_mask:0xf bound_ctrl:1
	v_add_f32_dpp v26, v26, v26 quad_perm:[2,3,0,1] row_mask:0xf bank_mask:0xf bound_ctrl:1
	s_nop 0
	v_add_f32_dpp v24, v24, v24 row_half_mirror row_mask:0xf bank_mask:0xf bound_ctrl:1
	v_add_f32_dpp v26, v26, v26 row_half_mirror row_mask:0xf bank_mask:0xf bound_ctrl:1
	s_nop 0
	v_add_f32_dpp v24, v24, v24 row_mirror row_mask:0xf bank_mask:0xf bound_ctrl:1
	v_add_f32_dpp v26, v26, v26 row_mirror row_mask:0xf bank_mask:0xf bound_ctrl:1
	s_nop 0
	v_mov_b32_dpp v25, v24 row_bcast:15 row_mask:0xa bank_mask:0xf
	v_mov_b32_dpp v27, v26 row_bcast:15 row_mask:0xa bank_mask:0xf
	v_add_f32_e32 v24, v24, v25
	v_mov_b32_e32 v25, v201
	v_add_f32_e32 v26, v26, v27
	v_mov_b32_e32 v27, v201
	v_mov_b32_dpp v25, v24 row_bcast:31 row_mask:0xc bank_mask:0xf
	s_nop 0
	v_mov_b32_dpp v27, v26 row_bcast:31 row_mask:0xc bank_mask:0xf
	s_and_saveexec_b64 s[60:61], s[4:5]
	v_add_f32_e32 v24, v24, v25
	v_add_f32_e32 v25, v26, v27
	v_mov_b32_e32 v26, s69
	v_add_u32_e32 v26, 0x84, v26
	ds_write2st64_b32 v26, v24, v25 offset0:3 offset1:7
	s_or_b64 exec, exec, s[60:61]
	s_waitcnt vmcnt(4)
	v_mul_f32_e32 v24, v1, v53
	v_mul_f32_e32 v25, v3, v55
	v_mul_f32_e32 v26, v5, v49
	v_mul_f32_e32 v27, v7, v51
	v_fmac_f32_e32 v24, v0, v52
	v_fmac_f32_e32 v25, v2, v54
	v_fmac_f32_e32 v26, v4, v48
	v_fmac_f32_e32 v27, v6, v50
	v_add_f32_e32 v24, v24, v25
	v_add_f32_e32 v26, v26, v27
	v_mov_b32_e32 v25, v201
	v_add_f32_dpp v24, v24, v24 quad_perm:[1,0,3,2] row_mask:0xf bank_mask:0xf bound_ctrl:1
	v_add_f32_dpp v26, v26, v26 quad_perm:[1,0,3,2] row_mask:0xf bank_mask:0xf bound_ctrl:1
	v_mov_b32_e32 v27, v201
	v_add_f32_dpp v24, v24, v24 quad_perm:[2,3,0,1] row_mask:0xf bank_mask:0xf bound_ctrl:1
	v_add_f32_dpp v26, v26, v26 quad_perm:[2,3,0,1] row_mask:0xf bank_mask:0xf bound_ctrl:1
	s_nop 0
	v_add_f32_dpp v24, v24, v24 row_half_mirror row_mask:0xf bank_mask:0xf bound_ctrl:1
	v_add_f32_dpp v26, v26, v26 row_half_mirror row_mask:0xf bank_mask:0xf bound_ctrl:1
	s_nop 0
	v_add_f32_dpp v24, v24, v24 row_mirror row_mask:0xf bank_mask:0xf bound_ctrl:1
	v_add_f32_dpp v26, v26, v26 row_mirror row_mask:0xf bank_mask:0xf bound_ctrl:1
	s_nop 0
	v_mov_b32_dpp v25, v24 row_bcast:15 row_mask:0xa bank_mask:0xf
	v_mov_b32_dpp v27, v26 row_bcast:15 row_mask:0xa bank_mask:0xf
	v_add_f32_e32 v24, v24, v25
	v_mov_b32_e32 v25, v201
	v_add_f32_e32 v26, v26, v27
	v_mov_b32_e32 v27, v201
	v_mov_b32_dpp v25, v24 row_bcast:31 row_mask:0xc bank_mask:0xf
	s_nop 0
	v_mov_b32_dpp v27, v26 row_bcast:31 row_mask:0xc bank_mask:0xf
	s_and_saveexec_b64 s[60:61], s[4:5]
	v_add_f32_e32 v24, v24, v25
	v_add_f32_e32 v25, v26, v27
	v_mov_b32_e32 v26, s69
	v_add_u32_e32 v26, 0x88, v26
	ds_write2st64_b32 v26, v24, v25 offset0:3 offset1:7
	s_or_b64 exec, exec, s[60:61]
	s_waitcnt vmcnt(4)
	v_mul_f32_e32 v24, v1, v45
	v_mul_f32_e32 v25, v3, v47
	s_waitcnt vmcnt(4)
	v_mul_f32_e32 v26, v5, v41
	v_mul_f32_e32 v27, v7, v43
	v_fmac_f32_e32 v24, v0, v44
	v_fmac_f32_e32 v25, v2, v46
	v_fmac_f32_e32 v26, v4, v40
	v_fmac_f32_e32 v27, v6, v42
	v_add_f32_e32 v24, v24, v25
	v_add_f32_e32 v26, v26, v27
	v_mov_b32_e32 v25, v201
	v_add_f32_dpp v24, v24, v24 quad_perm:[1,0,3,2] row_mask:0xf bank_mask:0xf bound_ctrl:1
	v_add_f32_dpp v26, v26, v26 quad_perm:[1,0,3,2] row_mask:0xf bank_mask:0xf bound_ctrl:1
	v_mov_b32_e32 v27, v201
	v_add_f32_dpp v24, v24, v24 quad_perm:[2,3,0,1] row_mask:0xf bank_mask:0xf bound_ctrl:1
	v_add_f32_dpp v26, v26, v26 quad_perm:[2,3,0,1] row_mask:0xf bank_mask:0xf bound_ctrl:1
	s_nop 0
	v_add_f32_dpp v24, v24, v24 row_half_mirror row_mask:0xf bank_mask:0xf bound_ctrl:1
	v_add_f32_dpp v26, v26, v26 row_half_mirror row_mask:0xf bank_mask:0xf bound_ctrl:1
	s_nop 0
	v_add_f32_dpp v24, v24, v24 row_mirror row_mask:0xf bank_mask:0xf bound_ctrl:1
	v_add_f32_dpp v26, v26, v26 row_mirror row_mask:0xf bank_mask:0xf bound_ctrl:1
	s_nop 0
	v_mov_b32_dpp v25, v24 row_bcast:15 row_mask:0xa bank_mask:0xf
	v_mov_b32_dpp v27, v26 row_bcast:15 row_mask:0xa bank_mask:0xf
	v_add_f32_e32 v24, v24, v25
	v_mov_b32_e32 v25, v201
	v_add_f32_e32 v26, v26, v27
	v_mov_b32_e32 v27, v201
	v_mov_b32_dpp v25, v24 row_bcast:31 row_mask:0xc bank_mask:0xf
	s_nop 0
	v_mov_b32_dpp v27, v26 row_bcast:31 row_mask:0xc bank_mask:0xf
	s_and_saveexec_b64 s[60:61], s[4:5]
	s_cbranch_execz .LBB0_2030
; __device__ __forceinline__ unsigned cvt_pk_bf16(float lo, float hi) { const f32x2cv v = {lo, hi}; return __builtin_bit_cast(unsigned, __builtin_convertvector(v, bf16x2cv)); }
; #define LAS __attribute__((address_space(3)))
; __device__ __forceinline__ void attn_fused(Frame& F0, int layer) {
;     ...
;     *(LAS f32x4*)(red + w * 512 + 4 * lane) = a0; *(LAS f32x4*)(red + w * 512 + 256 + 4 * lane) = a1;
;     __syncthreads();
;     {
;         float o = 0.f;
; #pragma unroll
;         for (int ww = 0; ww < 8; ++ww) o += red[ww * 512 + tid];
;         ((bf16_t*)(F.ws + WS_SO))[(size_t)sb * D + hp * 512 + tid] = (bf16_t)(cvt_pk_bf16(o, 0.f) & 0xffffu);
;     }
;     __syncthreads();
	v_add_f32_e32 v24, v24, v25
	v_add_f32_e32 v25, v26, v27
	v_mov_b32_e32 v26, s69
	v_add_u32_e32 v26, 0x8c, v26
	ds_write2st64_b32 v26, v24, v25 offset0:3 offset1:7
	s_branch .LBB0_2030
.LBB0_2129:
	s_waitcnt vmcnt(16)
	s_barrier
	s_lshl_b32 s4, s67, 11
	v_readlane_b32 s5, v254, 27
	s_add_i32 s4, s5, s4
	v_lshl_add_u32 v0, v168, 2, s4
	v_lshl_add_u32 v6, v170, 2, s5
	ds_write_b128 v0, v[72:75]
	ds_write_b128 v0, v[76:79] offset:1024
	s_waitcnt lgkmcnt(0)
	s_barrier
	ds_read2st64_b32 v[0:1], v6 offset1:8
	ds_read2st64_b32 v[2:3], v6 offset0:16 offset1:24
	ds_read2st64_b32 v[4:5], v6 offset0:32 offset1:40
	s_lshl_b64 s[2:3], s[2:3], 1
	s_add_u32 s2, s10, s2
	s_waitcnt lgkmcnt(2)
	v_add_f32_e32 v0, 0, v0
	v_add_f32_e32 v7, v0, v1
	ds_read2st64_b32 v[0:1], v6 offset0:48 offset1:56
	s_waitcnt lgkmcnt(2)
	v_add_f32_e32 v2, v7, v2
	v_add_f32_e32 v2, v2, v3
	s_waitcnt lgkmcnt(1)
	v_add_f32_e32 v2, v2, v4
	v_add_f32_e32 v2, v2, v5
	s_addc_u32 s3, s11, s3
	s_lshl_b32 s4, s68, 1
	s_waitcnt lgkmcnt(0)
	v_add_f32_e32 v0, v2, v0
	s_add_u32 s2, s2, s4
	v_add_f32_e32 v0, v0, v1
	v_ashrrev_i32_e32 v171, 31, v170
	s_addc_u32 s3, s3, 0
	v_cvt_pk_bf16_f32 v2, v0, s0
	v_lshl_add_u64 v[0:1], v[170:171], 1, s[2:3]
	v_add_co_u32_e32 v0, vcc, 0x1b700000, v0
	v_readlane_b32 s14, v254, 12
	s_nop 0
	v_addc_co_u32_e32 v1, vcc, 0, v1, vcc
	v_readlane_b32 s15, v254, 13
	global_store_short v[0:1], v2, off
	s_barrier
